# GEMM residual epilogues: batch gate/src loads (2 batches of 16) instead of 32 serialized load-wait-store round trips; ctx split-K atomic epilogue: hoist gate loads, no waits between atomics; xn2 row l
# speedup vs baseline: 1.0400x; 1.0141x over previous
; #define PG8_STAGE(bufoff, gbase, voff) do { _Pragma("unroll") for (int _i = 0; _i < 2; ++_i) \
;         __builtin_amdgcn_global_load_lds((const unsigned*)((const char*)(gbase) + (size_t)_i * r64##voff + (voff)), (LAS unsigned*)(lds + (bufoff) + ldsw + _i * 8192), 16, 0, 0); } while (0)
; #define PG8_LDA(dst, b, h) do { _Pragma("unroll") for (int m = 0; m < 4; ++m) _Pragma("unroll") for (int k = 0; k < 2; ++k) dst[m][k] = *(const LAS bf16x8*)(lds + PG8_SA(b, h) + aoff + m * 2048 + k * 1024); } while (0)
; #define PG8_LDB(dst, b, h) do { _Pragma("unroll") for (int n = 0; n < 2; ++n) _Pragma("unroll") for (int k = 0; k < 2; ++k) dst[n][k] = *(const LAS bf16x8*)(lds + PG8_SB(b, h) + boff + n * 2048 + k * 1024); } while (0)
; #define PG8_MMA(ai, bj, At, Bt) do { __builtin_amdgcn_s_setprio(1); _Pragma("unroll") for (int m = 0; m < 4; ++m) _Pragma("unroll") for (int n = 0; n < 2; ++n) _Pragma("unroll") for (int k = 0; k < 2; ++k) \
;         acc[ai][bj][m][n] = __builtin_amdgcn_mfma_f32_16x16x32_bf16(Bt[n][k], At[m][k], acc[ai][bj][m][n], 0, 0, 0); __builtin_amdgcn_s_setprio(0); } while (0)
; #define PG8_WAIT_V(n) asm volatile("s_waitcnt vmcnt(" #n ")" ::: "memory")
; #define PG8_WAIT_L(n) asm volatile("s_waitcnt lgkmcnt(" #n ")" ::: "memory")
; template <class Epi, class Sched>
; __device__ __forceinline__ void gemm_phase(LAS unsigned char* lds, const Gemm g, const Sched& S, const Epi& E) {
;     ...
;         for (int t = 0; t < nt; t += 2) {
;             const bool last = (t == nt - 2);
;             const char* a1 = cA + (size_t)(t + 1) * kstep;
;             const char* a2 = last ? nA : cA + (size_t)(t + 2) * kstep; const char* b2 = last ? nB : cB + (size_t)(t + 2) * kstep;
;             const char* a3 = a2 + kstep; const char* b3 = b2 + kstep;
;             PG8_LDB(B0, 0, 0); PG8_SCHED; PG8_LDA(At, 0, 0); PG8_STAGE(PG8_SA(1, 1), a1 + hstepA, voffA);
;             PG8_WAIT_L(8); PG8_BAR; PG8_WAIT_L(0); PG8_MMA(0, 0, At, B0); PG8_BAR; PG8_SCHED;
;             PG8_LDB(B1, 0, 1); PG8_STAGE(PG8_SB(0, 0), b2, voffB);
;             PG8_BAR; PG8_WAIT_L(0); PG8_MMA(0, 1, At, B1); PG8_BAR;
;             PG8_LDA(At, 0, 1); PG8_STAGE(PG8_SA(0, 0), a2, voffA);
;             PG8_BAR; PG8_WAIT_L(0); PG8_MMA(1, 0, At, B0); PG8_BAR; PG8_SCHED;
;             PG8_STAGE(PG8_SB(0, 1), b2 + hstepB, voffB);
;             PG8_WAIT_V(6); PG8_BAR; PG8_MMA(1, 1, At, B1); PG8_BAR;
.LBB0_474:
	ds_read_b128 v[136:139], v143
	ds_read_b128 v[146:149], v143 offset:1024
	ds_read_b128 v[150:153], v143 offset:2048
	ds_read_b128 v[154:157], v143 offset:3072
	s_add_u32 s70, s58, 0xfff80080
	s_addc_u32 s71, s59, -1
	s_cmp_eq_u32 s69, 28
	s_cselect_b32 s71, s51, s71
	s_cselect_b32 s70, s57, s70
	s_cselect_b32 s73, s49, s61
	s_cselect_b32 s72, s68, s60
	v_lshl_add_u64 v[140:141], s[58:59], 0, v[130:131]
	s_add_i32 m0, s33, 0xc000
	ds_read_b128 v[158:161], v144
	ds_read_b128 v[162:165], v144 offset:1024
	ds_read_b128 v[166:169], v144 offset:2048
	ds_read_b128 v[170:173], v144 offset:3072
	ds_read_b128 v[174:177], v144 offset:4096
	ds_read_b128 v[178:181], v144 offset:5120
	ds_read_b128 v[182:185], v144 offset:6144
	ds_read_b128 v[186:189], v144 offset:7168
	global_load_lds_dwordx4 v[140:141], off
	v_lshl_add_u64 v[140:141], v[140:141], 0, s[4:5]
	s_add_i32 m0, s33, 0xe000
	s_nop 0
	global_load_lds_dwordx4 v[140:141], off
	s_waitcnt lgkmcnt(8)
	s_barrier
	s_waitcnt lgkmcnt(0)
	s_setprio 1
	s_waitcnt lgkmcnt(0)
	v_mfma_f32_16x16x32_bf16 v[124:127], v[136:139], v[158:161], v[124:127]
	v_mfma_f32_16x16x32_bf16 v[120:123], v[150:153], v[158:161], v[120:123]
	v_mfma_f32_16x16x32_bf16 v[112:115], v[136:139], v[166:169], v[112:115]
	v_mfma_f32_16x16x32_bf16 v[104:107], v[150:153], v[166:169], v[104:107]
	v_mfma_f32_16x16x32_bf16 v[96:99], v[136:139], v[174:177], v[96:99]
	v_mfma_f32_16x16x32_bf16 v[88:91], v[150:153], v[174:177], v[88:91]
	v_mfma_f32_16x16x32_bf16 v[80:83], v[136:139], v[182:185], v[80:83]
	v_mfma_f32_16x16x32_bf16 v[72:75], v[150:153], v[182:185], v[72:75]
	v_mfma_f32_16x16x32_bf16 v[124:127], v[146:149], v[162:165], v[124:127]
	v_mfma_f32_16x16x32_bf16 v[120:123], v[154:157], v[162:165], v[120:123]
	v_mfma_f32_16x16x32_bf16 v[112:115], v[146:149], v[170:173], v[112:115]
	v_mfma_f32_16x16x32_bf16 v[104:107], v[154:157], v[170:173], v[104:107]
	v_mfma_f32_16x16x32_bf16 v[96:99], v[146:149], v[178:181], v[96:99]
	v_mfma_f32_16x16x32_bf16 v[88:91], v[154:157], v[178:181], v[88:91]
	v_mfma_f32_16x16x32_bf16 v[80:83], v[146:149], v[186:189], v[80:83]
	v_mfma_f32_16x16x32_bf16 v[72:75], v[154:157], v[186:189], v[72:75]
	s_setprio 0
	s_barrier
	v_lshl_add_u64 v[140:141], s[72:73], 0, v[128:129]
	s_add_i32 s72, s66, s31
	s_mov_b32 m0, s72
	ds_read_b128 v[190:193], v145
	ds_read_b128 v[194:197], v145 offset:1024
	ds_read_b128 v[198:201], v145 offset:2048
	ds_read_b128 v[202:205], v145 offset:3072
	global_load_lds_dwordx4 v[140:141], off
	v_lshl_add_u64 v[206:207], v[140:141], 0, s[4:5]
	s_add_i32 m0, s72, 0x2000
	s_nop 0
	global_load_lds_dwordx4 v[206:207], off
	s_barrier
	s_waitcnt lgkmcnt(0)
	s_setprio 1
	s_waitcnt lgkmcnt(0)
	v_mfma_f32_16x16x32_bf16 v[116:119], v[190:193], v[158:161], v[116:119]
	v_mfma_f32_16x16x32_bf16 v[108:111], v[198:201], v[158:161], v[108:111]
	v_mfma_f32_16x16x32_bf16 v[100:103], v[190:193], v[166:169], v[100:103]
	v_mfma_f32_16x16x32_bf16 v[92:95], v[198:201], v[166:169], v[92:95]
	v_mfma_f32_16x16x32_bf16 v[84:87], v[190:193], v[174:177], v[84:87]
	v_mfma_f32_16x16x32_bf16 v[76:79], v[198:201], v[174:177], v[76:79]
	v_mfma_f32_16x16x32_bf16 v[68:71], v[190:193], v[182:185], v[68:71]
	v_mfma_f32_16x16x32_bf16 v[64:67], v[198:201], v[182:185], v[64:67]
	v_mfma_f32_16x16x32_bf16 v[116:119], v[194:197], v[162:165], v[116:119]
	v_mfma_f32_16x16x32_bf16 v[108:111], v[202:205], v[162:165], v[108:111]
	v_mfma_f32_16x16x32_bf16 v[100:103], v[194:197], v[170:173], v[100:103]
	v_mfma_f32_16x16x32_bf16 v[92:95], v[202:205], v[170:173], v[92:95]
	v_mfma_f32_16x16x32_bf16 v[84:87], v[194:197], v[178:181], v[84:87]
	v_mfma_f32_16x16x32_bf16 v[76:79], v[202:205], v[178:181], v[76:79]
	v_mfma_f32_16x16x32_bf16 v[68:71], v[194:197], v[186:189], v[68:71]
	v_mfma_f32_16x16x32_bf16 v[64:67], v[202:205], v[186:189], v[64:67]
	s_setprio 0
	s_mov_b32 m0, s33
	v_lshl_add_u64 v[206:207], s[70:71], 0, v[128:129]
	s_barrier
	ds_read_b128 v[158:161], v144 offset:16384
	ds_read_b128 v[162:165], v144 offset:17408
	ds_read_b128 v[166:169], v144 offset:18432
	ds_read_b128 v[170:173], v144 offset:19456
	ds_read_b128 v[174:177], v144 offset:20480
	ds_read_b128 v[178:181], v144 offset:21504
	ds_read_b128 v[182:185], v144 offset:22528
	ds_read_b128 v[186:189], v144 offset:23552
	global_load_lds_dwordx4 v[206:207], off
	v_lshl_add_u64 v[208:209], v[206:207], 0, s[4:5]
	s_mov_b32 m0, s34
	s_nop 0
	global_load_lds_dwordx4 v[208:209], off
	s_barrier
	s_waitcnt lgkmcnt(0)
	s_setprio 1
	s_waitcnt lgkmcnt(0)
	v_mfma_f32_16x16x32_bf16 v[60:63], v[136:139], v[158:161], v[60:63]
	v_mfma_f32_16x16x32_bf16 v[56:59], v[150:153], v[158:161], v[56:59]
	v_mfma_f32_16x16x32_bf16 v[48:51], v[136:139], v[166:169], v[48:51]
	v_mfma_f32_16x16x32_bf16 v[40:43], v[150:153], v[166:169], v[40:43]
	v_mfma_f32_16x16x32_bf16 v[32:35], v[136:139], v[174:177], v[32:35]
	v_mfma_f32_16x16x32_bf16 v[24:27], v[150:153], v[174:177], v[24:27]
	v_mfma_f32_16x16x32_bf16 v[16:19], v[136:139], v[182:185], v[16:19]
	v_mfma_f32_16x16x32_bf16 v[8:11], v[150:153], v[182:185], v[8:11]
	v_mfma_f32_16x16x32_bf16 v[60:63], v[146:149], v[162:165], v[60:63]
	v_mfma_f32_16x16x32_bf16 v[56:59], v[154:157], v[162:165], v[56:59]
	v_mfma_f32_16x16x32_bf16 v[48:51], v[146:149], v[170:173], v[48:51]
	v_mfma_f32_16x16x32_bf16 v[40:43], v[154:157], v[170:173], v[40:43]
	v_mfma_f32_16x16x32_bf16 v[32:35], v[146:149], v[178:181], v[32:35]
	v_mfma_f32_16x16x32_bf16 v[24:27], v[154:157], v[178:181], v[24:27]
	v_mfma_f32_16x16x32_bf16 v[16:19], v[146:149], v[186:189], v[16:19]
	v_mfma_f32_16x16x32_bf16 v[8:11], v[154:157], v[186:189], v[8:11]
	s_setprio 0
	s_barrier
; #define PG8_STAGE(bufoff, gbase, voff) do { _Pragma("unroll") for (int _i = 0; _i < 2; ++_i) \
;         __builtin_amdgcn_global_load_lds((const unsigned*)((const char*)(gbase) + (size_t)_i * r64##voff + (voff)), (LAS unsigned*)(lds + (bufoff) + ldsw + _i * 8192), 16, 0, 0); } while (0)
; #define PG8_LDA(dst, b, h) do { _Pragma("unroll") for (int m = 0; m < 4; ++m) _Pragma("unroll") for (int k = 0; k < 2; ++k) dst[m][k] = *(const LAS bf16x8*)(lds + PG8_SA(b, h) + aoff + m * 2048 + k * 1024); } while (0)
; #define PG8_LDB(dst, b, h) do { _Pragma("unroll") for (int n = 0; n < 2; ++n) _Pragma("unroll") for (int k = 0; k < 2; ++k) dst[n][k] = *(const LAS bf16x8*)(lds + PG8_SB(b, h) + boff + n * 2048 + k * 1024); } while (0)
; #define PG8_MMA(ai, bj, At, Bt) do { __builtin_amdgcn_s_setprio(1); _Pragma("unroll") for (int m = 0; m < 4; ++m) _Pragma("unroll") for (int n = 0; n < 2; ++n) _Pragma("unroll") for (int k = 0; k < 2; ++k) \
;         acc[ai][bj][m][n] = __builtin_amdgcn_mfma_f32_16x16x32_bf16(Bt[n][k], At[m][k], acc[ai][bj][m][n], 0, 0, 0); __builtin_amdgcn_s_setprio(0); } while (0)
; #define PG8_WAIT_V(n) asm volatile("s_waitcnt vmcnt(" #n ")" ::: "memory")
; #define PG8_WAIT_L(n) asm volatile("s_waitcnt lgkmcnt(" #n ")" ::: "memory")
; #define PG8_BAR __builtin_amdgcn_s_barrier()
; #define PG8_SCHED __builtin_amdgcn_sched_barrier(0)
; template <class Epi, class Sched>
; __device__ __forceinline__ void gemm_phase(LAS unsigned char* lds, const Gemm g, const Sched& S, const Epi& E) {
;     ...
;             PG8_STAGE(PG8_SB(0, 1), b2 + hstepB, voffB);
;             PG8_WAIT_V(6); PG8_BAR; PG8_MMA(1, 1, At, B1); PG8_BAR;
;             PG8_LDB(B0, 1, 0); PG8_SCHED; PG8_LDA(At, 1, 0); PG8_STAGE(PG8_SA(0, 1), a2 + hstepA, voffA);
;             PG8_WAIT_L(8); PG8_BAR; PG8_WAIT_L(0); PG8_MMA(0, 0, At, B0); PG8_BAR; PG8_SCHED;
;             PG8_LDB(B1, 1, 1); PG8_STAGE(PG8_SB(1, 0), b3, voffB);
;             PG8_BAR; PG8_WAIT_L(0); PG8_MMA(0, 1, At, B1); PG8_BAR;
;             PG8_LDA(At, 1, 1); PG8_STAGE(PG8_SA(1, 0), a3, voffA);
;             PG8_BAR; PG8_WAIT_L(0); PG8_MMA(1, 0, At, B0); PG8_BAR; PG8_SCHED;
	s_add_i32 s70, s67, s31
	v_lshl_add_u64 v[136:137], v[140:141], 0, s[6:7]
	s_mov_b32 m0, s70
	s_nop 0
	global_load_lds_dwordx4 v[136:137], off
	v_lshl_add_u64 v[136:137], v[140:141], 0, s[8:9]
	s_add_i32 m0, s70, 0x2000
	s_nop 0
	global_load_lds_dwordx4 v[136:137], off
	s_waitcnt vmcnt(6)
	s_barrier
	s_setprio 1
	v_mfma_f32_16x16x32_bf16 v[52:55], v[190:193], v[158:161], v[52:55]
	v_mfma_f32_16x16x32_bf16 v[44:47], v[198:201], v[158:161], v[44:47]
	v_mfma_f32_16x16x32_bf16 v[36:39], v[190:193], v[166:169], v[36:39]
	v_mfma_f32_16x16x32_bf16 v[28:31], v[198:201], v[166:169], v[28:31]
	v_mfma_f32_16x16x32_bf16 v[20:23], v[190:193], v[174:177], v[20:23]
	v_mfma_f32_16x16x32_bf16 v[12:15], v[198:201], v[174:177], v[12:15]
	v_mfma_f32_16x16x32_bf16 v[4:7], v[190:193], v[182:185], v[4:7]
	v_mfma_f32_16x16x32_bf16 v[0:3], v[198:201], v[182:185], v[0:3]
	v_mfma_f32_16x16x32_bf16 v[52:55], v[194:197], v[162:165], v[52:55]
	v_mfma_f32_16x16x32_bf16 v[44:47], v[202:205], v[162:165], v[44:47]
	v_mfma_f32_16x16x32_bf16 v[36:39], v[194:197], v[170:173], v[36:39]
	v_mfma_f32_16x16x32_bf16 v[28:31], v[202:205], v[170:173], v[28:31]
	v_mfma_f32_16x16x32_bf16 v[20:23], v[194:197], v[178:181], v[20:23]
	v_mfma_f32_16x16x32_bf16 v[12:15], v[202:205], v[178:181], v[12:15]
	v_mfma_f32_16x16x32_bf16 v[4:7], v[194:197], v[186:189], v[4:7]
	v_mfma_f32_16x16x32_bf16 v[0:3], v[202:205], v[186:189], v[0:3]
	s_setprio 0
	s_add_i32 s70, 0, 0x18000
	v_add_u32_e32 v154, s70, v142
	s_barrier
	ds_read_b128 v[136:139], v154
	ds_read_b128 v[146:149], v154 offset:1024
	ds_read_b128 v[150:153], v154 offset:2048
	ds_read_b128 v[154:157], v154 offset:3072
	s_mov_b32 m0, s35
	v_lshl_add_u64 v[190:191], v[206:207], 0, s[6:7]
	ds_read_b128 v[158:161], v144 offset:32768
	ds_read_b128 v[162:165], v144 offset:33792
	ds_read_b128 v[166:169], v144 offset:34816
	ds_read_b128 v[170:173], v144 offset:35840
	ds_read_b128 v[174:177], v144 offset:36864
	ds_read_b128 v[178:181], v144 offset:37888
	ds_read_b128 v[182:185], v144 offset:38912
	ds_read_b128 v[186:189], v144 offset:39936
	global_load_lds_dwordx4 v[190:191], off
	v_lshl_add_u64 v[190:191], v[206:207], 0, s[8:9]
	s_mov_b32 m0, s36
	s_nop 0
	global_load_lds_dwordx4 v[190:191], off
	s_waitcnt lgkmcnt(8)
	s_barrier
	s_waitcnt lgkmcnt(0)
	s_setprio 1
	s_waitcnt lgkmcnt(0)
	v_mfma_f32_16x16x32_bf16 v[124:127], v[136:139], v[158:161], v[124:127]
	v_mfma_f32_16x16x32_bf16 v[120:123], v[150:153], v[158:161], v[120:123]
	v_mfma_f32_16x16x32_bf16 v[112:115], v[136:139], v[166:169], v[112:115]
	v_mfma_f32_16x16x32_bf16 v[104:107], v[150:153], v[166:169], v[104:107]
	v_mfma_f32_16x16x32_bf16 v[96:99], v[136:139], v[174:177], v[96:99]
	v_mfma_f32_16x16x32_bf16 v[88:91], v[150:153], v[174:177], v[88:91]
	v_mfma_f32_16x16x32_bf16 v[80:83], v[136:139], v[182:185], v[80:83]
	v_mfma_f32_16x16x32_bf16 v[72:75], v[150:153], v[182:185], v[72:75]
	v_mfma_f32_16x16x32_bf16 v[124:127], v[146:149], v[162:165], v[124:127]
	v_mfma_f32_16x16x32_bf16 v[120:123], v[154:157], v[162:165], v[120:123]
	v_mfma_f32_16x16x32_bf16 v[112:115], v[146:149], v[170:173], v[112:115]
	v_mfma_f32_16x16x32_bf16 v[104:107], v[154:157], v[170:173], v[104:107]
	v_mfma_f32_16x16x32_bf16 v[96:99], v[146:149], v[178:181], v[96:99]
	v_mfma_f32_16x16x32_bf16 v[88:91], v[154:157], v[178:181], v[88:91]
	v_mfma_f32_16x16x32_bf16 v[80:83], v[146:149], v[186:189], v[80:83]
	v_mfma_f32_16x16x32_bf16 v[72:75], v[154:157], v[186:189], v[72:75]
	s_setprio 0
	s_barrier
	s_add_i32 s71, 0, 0x1c000
	s_add_i32 s70, s70, s31
	v_add_u32_e32 v202, s71, v142
	v_lshl_add_u64 v[208:209], v[140:141], 0, s[18:19]
	s_mov_b32 m0, s70
	ds_read_b128 v[190:193], v202
	ds_read_b128 v[194:197], v202 offset:1024
	ds_read_b128 v[198:201], v202 offset:2048
	ds_read_b128 v[202:205], v202 offset:3072
	global_load_lds_dwordx4 v[208:209], off
	v_lshl_add_u64 v[208:209], v[140:141], 0, s[20:21]
	s_add_i32 m0, s70, 0x2000
	s_nop 0
	global_load_lds_dwordx4 v[208:209], off
	s_barrier
	s_waitcnt lgkmcnt(0)
	s_setprio 1
	s_waitcnt lgkmcnt(0)
	v_mfma_f32_16x16x32_bf16 v[116:119], v[190:193], v[158:161], v[116:119]
	v_mfma_f32_16x16x32_bf16 v[108:111], v[198:201], v[158:161], v[108:111]
	v_mfma_f32_16x16x32_bf16 v[100:103], v[190:193], v[166:169], v[100:103]
	v_mfma_f32_16x16x32_bf16 v[92:95], v[198:201], v[166:169], v[92:95]
	v_mfma_f32_16x16x32_bf16 v[84:87], v[190:193], v[174:177], v[84:87]
	v_mfma_f32_16x16x32_bf16 v[76:79], v[198:201], v[174:177], v[76:79]
	v_mfma_f32_16x16x32_bf16 v[68:71], v[190:193], v[182:185], v[68:71]
	v_mfma_f32_16x16x32_bf16 v[64:67], v[198:201], v[182:185], v[64:67]
	v_mfma_f32_16x16x32_bf16 v[116:119], v[194:197], v[162:165], v[116:119]
	v_mfma_f32_16x16x32_bf16 v[108:111], v[202:205], v[162:165], v[108:111]
	v_mfma_f32_16x16x32_bf16 v[100:103], v[194:197], v[170:173], v[100:103]
	v_mfma_f32_16x16x32_bf16 v[92:95], v[202:205], v[170:173], v[92:95]
	v_mfma_f32_16x16x32_bf16 v[84:87], v[194:197], v[178:181], v[84:87]
	v_mfma_f32_16x16x32_bf16 v[76:79], v[202:205], v[178:181], v[76:79]
	v_mfma_f32_16x16x32_bf16 v[68:71], v[194:197], v[186:189], v[68:71]
	v_mfma_f32_16x16x32_bf16 v[64:67], v[202:205], v[186:189], v[64:67]
	s_setprio 0
	s_mov_b32 m0, s40
	v_lshl_add_u64 v[208:209], v[206:207], 0, s[18:19]
	s_barrier
	ds_read_b128 v[158:161], v144 offset:49152
	ds_read_b128 v[162:165], v144 offset:50176
	ds_read_b128 v[166:169], v144 offset:51200
	ds_read_b128 v[170:173], v144 offset:52224
	ds_read_b128 v[174:177], v144 offset:53248
	ds_read_b128 v[178:181], v144 offset:54272
	ds_read_b128 v[182:185], v144 offset:55296
	ds_read_b128 v[186:189], v144 offset:56320
	global_load_lds_dwordx4 v[208:209], off
	v_lshl_add_u64 v[206:207], v[206:207], 0, s[20:21]
	s_mov_b32 m0, s41
	s_nop 0
	global_load_lds_dwordx4 v[206:207], off
	s_barrier
; __device__ __forceinline__ int otid() { int t = (int)__builtin_amdgcn_workitem_id_x(); asm volatile("" : "+v"(t)); return t; }
; #define PG8_STAGE(bufoff, gbase, voff) do { _Pragma("unroll") for (int _i = 0; _i < 2; ++_i) \
;         __builtin_amdgcn_global_load_lds((const unsigned*)((const char*)(gbase) + (size_t)_i * r64##voff + (voff)), (LAS unsigned*)(lds + (bufoff) + ldsw + _i * 8192), 16, 0, 0); } while (0)
; #define PG8_WAIT_V(n) asm volatile("s_waitcnt vmcnt(" #n ")" ::: "memory")
; #define PG8_WAIT_L(n) asm volatile("s_waitcnt lgkmcnt(" #n ")" ::: "memory")
; #define PG8_BAR __builtin_amdgcn_s_barrier()
; #define PG8_SCHED __builtin_amdgcn_sched_barrier(0)
; template <class Epi, class Sched>
; __device__ __forceinline__ void gemm_phase(LAS unsigned char* lds, const Gemm g, const Sched& S, const Epi& E) {
;     ...
;             PG8_BAR; PG8_WAIT_L(0); PG8_MMA(1, 0, At, B0); PG8_BAR; PG8_SCHED;
;             PG8_STAGE(PG8_SB(1, 1), b3 + hstepB, voffB);
;             PG8_WAIT_V(6); PG8_BAR; PG8_MMA(1, 1, At, B1); PG8_BAR;
;     __device__ __forceinline__ void operator()(const f32x4 (&acc)[2][2][4][2], const pg8::Unit& u, int wr_, int wc_, int fr_, int fq_) const {
;         const int t2_ = otid(), wr = t2_ >> 8, wc = (t2_ >> 6) & 3, fr = t2_ & 15, fq = (t2_ >> 4) & 3; (void)wr_; (void)wc_; (void)fr_; (void)fq_;
;         const int rbase = u.pm * 256;
;         const bool isc = rbase >= RL;
;         const int mr = isc ? 4 : (rbase >> 12);
;         const float* gate = modsel + (size_t)mr * 12288;
;         const float* src = isc ? srcC - (size_t)RL * 2048 : srcL;
;         float* dst = isc ? dstC - (size_t)RL * 2048 : dstL;
;         const int row0 = rbase + wr * 64 + fr, col0 = u.pn * 256 + wc * 32 + 4 * fq;
; #pragma unroll
;         for (int ai = 0; ai < 2; ++ai)
; #pragma unroll
;             for (int m = 0; m < 4; ++m) { const size_t ro = (size_t)(row0 + ai * 128 + m * 16) * 2048;
; #pragma unroll
;                 for (int bj = 0; bj < 2; ++bj)
; #pragma unroll
;                     for (int n = 0; n < 2; ++n) { const int col = col0 + bj * 128 + n * 16;
;                         const f32x4 gg = *(const f32x4*)(gate + col), s = *(const f32x4*)(src + ro + col);
;                         *(f32x4*)(dst + ro + col) = s + gg * acc[ai][bj][m][n]; } }
	s_waitcnt lgkmcnt(0)
	s_setprio 1
	s_waitcnt lgkmcnt(0)
	v_mfma_f32_16x16x32_bf16 v[60:63], v[136:139], v[158:161], v[60:63]
	v_mfma_f32_16x16x32_bf16 v[56:59], v[150:153], v[158:161], v[56:59]
	v_mfma_f32_16x16x32_bf16 v[48:51], v[136:139], v[166:169], v[48:51]
	v_mfma_f32_16x16x32_bf16 v[40:43], v[150:153], v[166:169], v[40:43]
	v_mfma_f32_16x16x32_bf16 v[32:35], v[136:139], v[174:177], v[32:35]
	v_mfma_f32_16x16x32_bf16 v[24:27], v[150:153], v[174:177], v[24:27]
	v_mfma_f32_16x16x32_bf16 v[16:19], v[136:139], v[182:185], v[16:19]
	v_mfma_f32_16x16x32_bf16 v[8:11], v[150:153], v[182:185], v[8:11]
	v_mfma_f32_16x16x32_bf16 v[60:63], v[146:149], v[162:165], v[60:63]
	v_mfma_f32_16x16x32_bf16 v[56:59], v[154:157], v[162:165], v[56:59]
	v_mfma_f32_16x16x32_bf16 v[48:51], v[146:149], v[170:173], v[48:51]
	v_mfma_f32_16x16x32_bf16 v[40:43], v[154:157], v[170:173], v[40:43]
	v_mfma_f32_16x16x32_bf16 v[32:35], v[146:149], v[178:181], v[32:35]
	v_mfma_f32_16x16x32_bf16 v[24:27], v[154:157], v[178:181], v[24:27]
	v_mfma_f32_16x16x32_bf16 v[16:19], v[146:149], v[186:189], v[16:19]
	v_mfma_f32_16x16x32_bf16 v[8:11], v[154:157], v[186:189], v[8:11]
	s_setprio 0
	s_barrier
	s_add_i32 s70, s71, s31
	v_lshl_add_u64 v[136:137], v[140:141], 0, s[22:23]
	s_mov_b32 m0, s70
	s_nop 0
	global_load_lds_dwordx4 v[136:137], off
	v_lshl_add_u64 v[136:137], v[140:141], 0, s[24:25]
	s_add_i32 m0, s70, 0x2000
	s_nop 0
	global_load_lds_dwordx4 v[136:137], off
	s_waitcnt vmcnt(6)
	s_barrier
	s_setprio 1
	v_mfma_f32_16x16x32_bf16 v[52:55], v[190:193], v[158:161], v[52:55]
	v_mfma_f32_16x16x32_bf16 v[44:47], v[198:201], v[158:161], v[44:47]
	v_mfma_f32_16x16x32_bf16 v[36:39], v[190:193], v[166:169], v[36:39]
	v_mfma_f32_16x16x32_bf16 v[28:31], v[198:201], v[166:169], v[28:31]
	v_mfma_f32_16x16x32_bf16 v[20:23], v[190:193], v[174:177], v[20:23]
	v_mfma_f32_16x16x32_bf16 v[12:15], v[198:201], v[174:177], v[12:15]
	v_mfma_f32_16x16x32_bf16 v[4:7], v[190:193], v[182:185], v[4:7]
	v_mfma_f32_16x16x32_bf16 v[0:3], v[198:201], v[182:185], v[0:3]
	v_mfma_f32_16x16x32_bf16 v[52:55], v[194:197], v[162:165], v[52:55]
	v_mfma_f32_16x16x32_bf16 v[44:47], v[202:205], v[162:165], v[44:47]
	v_mfma_f32_16x16x32_bf16 v[36:39], v[194:197], v[170:173], v[36:39]
	v_mfma_f32_16x16x32_bf16 v[28:31], v[202:205], v[170:173], v[28:31]
	v_mfma_f32_16x16x32_bf16 v[20:23], v[194:197], v[178:181], v[20:23]
	v_mfma_f32_16x16x32_bf16 v[12:15], v[202:205], v[178:181], v[12:15]
	v_mfma_f32_16x16x32_bf16 v[4:7], v[194:197], v[186:189], v[4:7]
	v_mfma_f32_16x16x32_bf16 v[0:3], v[202:205], v[186:189], v[0:3]
	s_setprio 0
	s_add_i32 s69, s69, 2
	s_add_u32 s58, s58, 0x100
	s_addc_u32 s59, s59, 0
	s_add_u32 s60, s60, 0x100
	s_addc_u32 s61, s61, 0
	s_cmp_gt_u32 s69, 29
	s_barrier
	s_cbranch_scc0 .LBB0_474
	s_min_i32 s51, s56, 64
	s_ashr_i32 s51, s51, 4
	s_lshl_b32 s49, s56, 8
	s_mul_hi_i32 s57, s51, 0xc000
	s_mul_i32 s51, s51, 0xc000
	v_mov_b32_e32 v137, v222
	s_add_u32 s60, s38, s51
	s_addc_u32 s61, s39, s57
	v_ashrrev_i32_e32 v136, 2, v137
	s_cmp_gt_i32 s56, 63
	v_and_b32_e32 v138, 0xffffffc0, v136
	v_lshrrev_b32_e32 v136, 1, v137
	v_lshrrev_b32_e32 v139, 2, v137
	v_and_or_b32 v137, v137, 15, s49
	s_cselect_b32 s59, s63, s11
	s_cselect_b32 s58, s62, s10
	s_cselect_b32 s57, s65, s17
	s_cselect_b32 s56, s64, s16
	s_lshl_b32 s12, s12, 8
	v_and_b32_e32 v136, 0x60, v136
	v_and_b32_e32 v139, 12, v139
	v_add_u32_e32 v154, v137, v138
	v_or3_b32 v136, v136, s12, v139
	v_ashrrev_i32_e32 v155, 31, v154
	v_ashrrev_i32_e32 v137, 31, v136
	v_lshlrev_b64 v[140:141], 13, v[154:155]
	v_lshlrev_b64 v[138:139], 2, v[136:137]
	v_lshl_add_u64 v[150:151], s[58:59], 0, v[140:141]
	v_lshl_add_u64 v[136:137], s[60:61], 0, v[138:139]
	v_lshl_add_u64 v[156:157], v[150:151], 0, v[138:139]
	v_lshl_add_u64 v[158:159], s[56:57], 0, v[140:141]
	v_lshl_add_u64 v[158:159], v[158:159], 0, v[138:139]
	s_mov_b64 s[60:61], s[54:55]
	s_and_b64 vcc, exec, s[2:3]
	s_mov_b32 s12, s48
	s_mov_b64 s[58:59], s[52:53]
	s_mov_b32 s56, s50
	s_mov_b32 s98, 0x20000
	s_mov_b32 s99, 0
	s_mov_b32 s100, 0xa0000
	s_mov_b32 s101, 0
	global_load_dwordx4 v[146:149], v[136:137], off
	global_load_dwordx4 v[160:163], v[136:137], off offset:64
	global_load_dwordx4 v[164:167], v[136:137], off offset:512
	global_load_dwordx4 v[168:171], v[136:137], off offset:576
	global_load_dwordx4 v[172:175], v[156:157], off
	global_load_dwordx4 v[176:179], v[156:157], off offset:64
	global_load_dwordx4 v[180:183], v[156:157], off offset:512
	global_load_dwordx4 v[184:187], v[156:157], off offset:576
	v_lshl_add_u64 v[156:157], v[156:157], 0, s[98:99]
	global_load_dwordx4 v[188:191], v[156:157], off
	global_load_dwordx4 v[192:195], v[156:157], off offset:64
	global_load_dwordx4 v[196:199], v[156:157], off offset:512
	global_load_dwordx4 v[200:203], v[156:157], off offset:576
	v_lshl_add_u64 v[156:157], v[156:157], 0, s[98:99]
	global_load_dwordx4 v[204:207], v[156:157], off
	global_load_dwordx4 v[208:211], v[156:157], off offset:64
	global_load_dwordx4 v[212:215], v[156:157], off offset:512
	global_load_dwordx4 v[216:219], v[156:157], off offset:576
	v_lshl_add_u64 v[156:157], v[156:157], 0, s[98:99]
	global_load_dwordx4 v[224:227], v[156:157], off
	global_load_dwordx4 v[228:231], v[156:157], off offset:64
	global_load_dwordx4 v[232:235], v[156:157], off offset:512
	global_load_dwordx4 v[236:239], v[156:157], off offset:576
	v_lshl_add_u64 v[156:157], v[156:157], 0, s[100:101]
	s_waitcnt vmcnt(0)
; __device__ __forceinline__ int otid() { int t = (int)__builtin_amdgcn_workitem_id_x(); asm volatile("" : "+v"(t)); return t; }
;     __device__ __forceinline__ void operator()(const f32x4 (&acc)[2][2][4][2], const pg8::Unit& u, int wr_, int wc_, int fr_, int fq_) const {
;         const int t2_ = otid(), wr = t2_ >> 8, wc = (t2_ >> 6) & 3, fr = t2_ & 15, fq = (t2_ >> 4) & 3; (void)wr_; (void)wc_; (void)fr_; (void)fq_;
;         const int rbase = u.pm * 256;
;         const bool isc = rbase >= RL;
;         const int mr = isc ? 4 : (rbase >> 12);
;         const float* gate = modsel + (size_t)mr * 12288;
;         const float* src = isc ? srcC - (size_t)RL * 2048 : srcL;
;         float* dst = isc ? dstC - (size_t)RL * 2048 : dstL;
;         const int row0 = rbase + wr * 64 + fr, col0 = u.pn * 256 + wc * 32 + 4 * fq;
; #pragma unroll
;         for (int ai = 0; ai < 2; ++ai)
; #pragma unroll
;             for (int m = 0; m < 4; ++m) { const size_t ro = (size_t)(row0 + ai * 128 + m * 16) * 2048;
; #pragma unroll
;                 for (int bj = 0; bj < 2; ++bj)
; #pragma unroll
;                     for (int n = 0; n < 2; ++n) { const int col = col0 + bj * 128 + n * 16;
;                         const f32x4 gg = *(const f32x4*)(gate + col), s = *(const f32x4*)(src + ro + col);
;                         *(f32x4*)(dst + ro + col) = s + gg * acc[ai][bj][m][n]; } }
;     }
	v_pk_fma_f32 v[124:125], v[124:125], v[146:147], v[172:173]
	v_pk_fma_f32 v[126:127], v[126:127], v[148:149], v[174:175]
	v_pk_fma_f32 v[120:121], v[120:121], v[160:161], v[176:177]
	v_pk_fma_f32 v[122:123], v[122:123], v[162:163], v[178:179]
	v_pk_fma_f32 v[116:117], v[116:117], v[164:165], v[180:181]
	v_pk_fma_f32 v[118:119], v[118:119], v[166:167], v[182:183]
	v_pk_fma_f32 v[108:109], v[108:109], v[168:169], v[184:185]
	v_pk_fma_f32 v[110:111], v[110:111], v[170:171], v[186:187]
	v_pk_fma_f32 v[112:113], v[112:113], v[146:147], v[188:189]
	v_pk_fma_f32 v[114:115], v[114:115], v[148:149], v[190:191]
	v_pk_fma_f32 v[104:105], v[104:105], v[160:161], v[192:193]
	v_pk_fma_f32 v[106:107], v[106:107], v[162:163], v[194:195]
	v_pk_fma_f32 v[100:101], v[100:101], v[164:165], v[196:197]
	v_pk_fma_f32 v[102:103], v[102:103], v[166:167], v[198:199]
	v_pk_fma_f32 v[92:93], v[92:93], v[168:169], v[200:201]
	v_pk_fma_f32 v[94:95], v[94:95], v[170:171], v[202:203]
	v_pk_fma_f32 v[96:97], v[96:97], v[146:147], v[204:205]
	v_pk_fma_f32 v[98:99], v[98:99], v[148:149], v[206:207]
	v_pk_fma_f32 v[88:89], v[88:89], v[160:161], v[208:209]
	v_pk_fma_f32 v[90:91], v[90:91], v[162:163], v[210:211]
	v_pk_fma_f32 v[84:85], v[84:85], v[164:165], v[212:213]
	v_pk_fma_f32 v[86:87], v[86:87], v[166:167], v[214:215]
	v_pk_fma_f32 v[76:77], v[76:77], v[168:169], v[216:217]
	v_pk_fma_f32 v[78:79], v[78:79], v[170:171], v[218:219]
	v_pk_fma_f32 v[80:81], v[80:81], v[146:147], v[224:225]
	v_pk_fma_f32 v[82:83], v[82:83], v[148:149], v[226:227]
	v_pk_fma_f32 v[72:73], v[72:73], v[160:161], v[228:229]
	v_pk_fma_f32 v[74:75], v[74:75], v[162:163], v[230:231]
	v_pk_fma_f32 v[68:69], v[68:69], v[164:165], v[232:233]
	v_pk_fma_f32 v[70:71], v[70:71], v[166:167], v[234:235]
	v_pk_fma_f32 v[64:65], v[64:65], v[168:169], v[236:237]
	v_pk_fma_f32 v[66:67], v[66:67], v[170:171], v[238:239]
	global_load_dwordx4 v[172:175], v[156:157], off
	global_load_dwordx4 v[176:179], v[156:157], off offset:64
	global_load_dwordx4 v[180:183], v[156:157], off offset:512
	global_load_dwordx4 v[184:187], v[156:157], off offset:576
	v_lshl_add_u64 v[156:157], v[156:157], 0, s[98:99]
	global_load_dwordx4 v[188:191], v[156:157], off
	global_load_dwordx4 v[192:195], v[156:157], off offset:64
	global_load_dwordx4 v[196:199], v[156:157], off offset:512
	global_load_dwordx4 v[200:203], v[156:157], off offset:576
	v_lshl_add_u64 v[156:157], v[156:157], 0, s[98:99]
	global_load_dwordx4 v[204:207], v[156:157], off
	global_load_dwordx4 v[208:211], v[156:157], off offset:64
	global_load_dwordx4 v[212:215], v[156:157], off offset:512
	global_load_dwordx4 v[216:219], v[156:157], off offset:576
	v_lshl_add_u64 v[156:157], v[156:157], 0, s[98:99]
	global_load_dwordx4 v[224:227], v[156:157], off
	global_load_dwordx4 v[228:231], v[156:157], off offset:64
	global_load_dwordx4 v[232:235], v[156:157], off offset:512
	global_load_dwordx4 v[236:239], v[156:157], off offset:576
	global_store_dwordx4 v[158:159], v[124:127], off
	global_store_dwordx4 v[158:159], v[120:123], off offset:64
	global_store_dwordx4 v[158:159], v[116:119], off offset:512
	global_store_dwordx4 v[158:159], v[108:111], off offset:576
	v_lshl_add_u64 v[158:159], v[158:159], 0, s[98:99]
	global_store_dwordx4 v[158:159], v[112:115], off
	global_store_dwordx4 v[158:159], v[104:107], off offset:64
	global_store_dwordx4 v[158:159], v[100:103], off offset:512
	global_store_dwordx4 v[158:159], v[92:95], off offset:576
	v_lshl_add_u64 v[158:159], v[158:159], 0, s[98:99]
	global_store_dwordx4 v[158:159], v[96:99], off
	global_store_dwordx4 v[158:159], v[88:91], off offset:64
	global_store_dwordx4 v[158:159], v[84:87], off offset:512
	global_store_dwordx4 v[158:159], v[76:79], off offset:576
	v_lshl_add_u64 v[158:159], v[158:159], 0, s[98:99]
	global_store_dwordx4 v[158:159], v[80:83], off
	global_store_dwordx4 v[158:159], v[72:75], off offset:64
	global_store_dwordx4 v[158:159], v[68:71], off offset:512
	global_store_dwordx4 v[158:159], v[64:67], off offset:576
	v_lshl_add_u64 v[158:159], v[158:159], 0, s[100:101]
	s_waitcnt vmcnt(16)
	v_pk_fma_f32 v[60:61], v[60:61], v[146:147], v[172:173]
	v_pk_fma_f32 v[62:63], v[62:63], v[148:149], v[174:175]
	v_pk_fma_f32 v[56:57], v[56:57], v[160:161], v[176:177]
	v_pk_fma_f32 v[58:59], v[58:59], v[162:163], v[178:179]
	v_pk_fma_f32 v[52:53], v[52:53], v[164:165], v[180:181]
	v_pk_fma_f32 v[54:55], v[54:55], v[166:167], v[182:183]
	v_pk_fma_f32 v[44:45], v[44:45], v[168:169], v[184:185]
	v_pk_fma_f32 v[46:47], v[46:47], v[170:171], v[186:187]
	v_pk_fma_f32 v[48:49], v[48:49], v[146:147], v[188:189]
	v_pk_fma_f32 v[50:51], v[50:51], v[148:149], v[190:191]
	v_pk_fma_f32 v[40:41], v[40:41], v[160:161], v[192:193]
	v_pk_fma_f32 v[42:43], v[42:43], v[162:163], v[194:195]
	v_pk_fma_f32 v[36:37], v[36:37], v[164:165], v[196:197]
	v_pk_fma_f32 v[38:39], v[38:39], v[166:167], v[198:199]
	v_pk_fma_f32 v[28:29], v[28:29], v[168:169], v[200:201]
	v_pk_fma_f32 v[30:31], v[30:31], v[170:171], v[202:203]
	v_pk_fma_f32 v[32:33], v[32:33], v[146:147], v[204:205]
	v_pk_fma_f32 v[34:35], v[34:35], v[148:149], v[206:207]
	v_pk_fma_f32 v[24:25], v[24:25], v[160:161], v[208:209]
	v_pk_fma_f32 v[26:27], v[26:27], v[162:163], v[210:211]
	v_pk_fma_f32 v[20:21], v[20:21], v[164:165], v[212:213]
	v_pk_fma_f32 v[22:23], v[22:23], v[166:167], v[214:215]
	v_pk_fma_f32 v[12:13], v[12:13], v[168:169], v[216:217]
	v_pk_fma_f32 v[14:15], v[14:15], v[170:171], v[218:219]
	v_pk_fma_f32 v[16:17], v[16:17], v[146:147], v[224:225]
	v_pk_fma_f32 v[18:19], v[18:19], v[148:149], v[226:227]
	v_pk_fma_f32 v[8:9], v[8:9], v[160:161], v[228:229]
	v_pk_fma_f32 v[10:11], v[10:11], v[162:163], v[230:231]
	v_pk_fma_f32 v[4:5], v[4:5], v[164:165], v[232:233]
	v_pk_fma_f32 v[6:7], v[6:7], v[166:167], v[234:235]
	v_pk_fma_f32 v[0:1], v[0:1], v[168:169], v[236:237]
	v_pk_fma_f32 v[2:3], v[2:3], v[170:171], v[238:239]
	global_store_dwordx4 v[158:159], v[60:63], off
	global_store_dwordx4 v[158:159], v[56:59], off offset:64
	global_store_dwordx4 v[158:159], v[52:55], off offset:512
	global_store_dwordx4 v[158:159], v[44:47], off offset:576
	v_lshl_add_u64 v[158:159], v[158:159], 0, s[98:99]
	global_store_dwordx4 v[158:159], v[48:51], off
	global_store_dwordx4 v[158:159], v[40:43], off offset:64
	global_store_dwordx4 v[158:159], v[36:39], off offset:512
	global_store_dwordx4 v[158:159], v[28:31], off offset:576
	v_lshl_add_u64 v[158:159], v[158:159], 0, s[98:99]
	global_store_dwordx4 v[158:159], v[32:35], off
	global_store_dwordx4 v[158:159], v[24:27], off offset:64
	global_store_dwordx4 v[158:159], v[20:23], off offset:512
	global_store_dwordx4 v[158:159], v[12:15], off offset:576
	v_lshl_add_u64 v[158:159], v[158:159], 0, s[98:99]
	global_store_dwordx4 v[158:159], v[16:19], off
	global_store_dwordx4 v[158:159], v[8:11], off offset:64
	global_store_dwordx4 v[158:159], v[4:7], off offset:512
	global_store_dwordx4 v[158:159], v[0:3], off offset:576
	s_cbranch_vccz .LBB0_467
	s_waitcnt vmcnt(0)
	s_cmpk_gt_u32 s13, 0xff
	s_cbranch_scc1 .LBB0_478
	s_barrier

; #define PG8_STAGE(bufoff, gbase, voff) do { _Pragma("unroll") for (int _i = 0; _i < 2; ++_i) \
;         __builtin_amdgcn_global_load_lds((const unsigned*)((const char*)(gbase) + (size_t)_i * r64##voff + (voff)), (LAS unsigned*)(lds + (bufoff) + ldsw + _i * 8192), 16, 0, 0); } while (0)
; #define PG8_LDA(dst, b, h) do { _Pragma("unroll") for (int m = 0; m < 4; ++m) _Pragma("unroll") for (int k = 0; k < 2; ++k) dst[m][k] = *(const LAS bf16x8*)(lds + PG8_SA(b, h) + aoff + m * 2048 + k * 1024); } while (0)
; #define PG8_LDB(dst, b, h) do { _Pragma("unroll") for (int n = 0; n < 2; ++n) _Pragma("unroll") for (int k = 0; k < 2; ++k) dst[n][k] = *(const LAS bf16x8*)(lds + PG8_SB(b, h) + boff + n * 2048 + k * 1024); } while (0)
; #define PG8_MMA(ai, bj, At, Bt) do { __builtin_amdgcn_s_setprio(1); _Pragma("unroll") for (int m = 0; m < 4; ++m) _Pragma("unroll") for (int n = 0; n < 2; ++n) _Pragma("unroll") for (int k = 0; k < 2; ++k) \
;         acc[ai][bj][m][n] = __builtin_amdgcn_mfma_f32_16x16x32_bf16(Bt[n][k], At[m][k], acc[ai][bj][m][n], 0, 0, 0); __builtin_amdgcn_s_setprio(0); } while (0)
; #define PG8_WAIT_V(n) asm volatile("s_waitcnt vmcnt(" #n ")" ::: "memory")
; #define PG8_WAIT_L(n) asm volatile("s_waitcnt lgkmcnt(" #n ")" ::: "memory")
; #define PG8_BAR __builtin_amdgcn_s_barrier()
; #define PG8_SCHED __builtin_amdgcn_sched_barrier(0)
; template <class Epi, class Sched>
; __device__ __forceinline__ void gemm_phase(LAS unsigned char* lds, const Gemm g, const Sched& S, const Epi& E) {
;     ...
;             PG8_LDB(B0, 0, 0); PG8_SCHED; PG8_LDA(At, 0, 0); PG8_STAGE(PG8_SA(1, 1), a1 + hstepA, voffA);
;             PG8_WAIT_L(8); PG8_BAR; PG8_WAIT_L(0); PG8_MMA(0, 0, At, B0); PG8_BAR; PG8_SCHED;
;             PG8_LDB(B1, 0, 1); PG8_STAGE(PG8_SB(0, 0), b2, voffB);
;             PG8_BAR; PG8_WAIT_L(0); PG8_MMA(0, 1, At, B1); PG8_BAR;
;             PG8_LDA(At, 0, 1); PG8_STAGE(PG8_SA(0, 0), a2, voffA);
;             PG8_BAR; PG8_WAIT_L(0); PG8_MMA(1, 0, At, B0); PG8_BAR; PG8_SCHED;
;             PG8_STAGE(PG8_SB(0, 1), b2 + hstepB, voffB);
;             PG8_WAIT_V(6); PG8_BAR; PG8_MMA(1, 1, At, B1); PG8_BAR;
.LBB0_485:
	s_add_i32 s58, s2, 0x100
	s_and_b64 s[56:57], s[56:57], exec
	ds_read_b128 v[138:141], v134
	ds_read_b128 v[142:145], v134 offset:1024
	ds_read_b128 v[146:149], v134 offset:2048
	ds_read_b128 v[150:153], v134 offset:3072
	s_cselect_b32 s58, 0, s58
	s_cselect_b32 s59, 0, 0
	s_add_u32 s56, s48, s58
	s_addc_u32 s57, s49, s59
	s_add_u32 s58, s46, s58
	s_addc_u32 s59, s47, s59
	s_add_i32 s65, 0, 0x18000
	s_add_i32 s63, 0, 0x1c000
	s_add_i32 s68, s31, s35
	s_add_i32 s64, s65, s35
	s_add_i32 s69, s63, s35
	s_add_i32 s70, s61, 0x2000
	s_add_i32 s66, s68, 0x2000
	s_add_i32 s71, s64, 0x2000
	s_add_i32 s67, s69, 0x2000
	v_lshl_add_u64 v[186:187], v[130:131], 0, s[2:3]
	s_mov_b32 m0, s45
	v_lshl_add_u64 v[188:189], v[186:187], 0, s[10:11]
	ds_read_b128 v[154:157], v133
	ds_read_b128 v[158:161], v133 offset:1024
	ds_read_b128 v[162:165], v133 offset:2048
	ds_read_b128 v[166:169], v133 offset:3072
	ds_read_b128 v[170:173], v133 offset:4096
	ds_read_b128 v[174:177], v133 offset:5120
	ds_read_b128 v[178:181], v133 offset:6144
	ds_read_b128 v[182:185], v133 offset:7168
	global_load_lds_dwordx4 v[188:189], off
	v_lshl_add_u64 v[186:187], v[186:187], 0, s[16:17]
	s_mov_b32 m0, s60
	s_nop 0
	global_load_lds_dwordx4 v[186:187], off
	s_waitcnt lgkmcnt(8)
	s_barrier
	s_waitcnt lgkmcnt(0)
	s_setprio 1
	s_waitcnt lgkmcnt(0)
	v_mfma_f32_16x16x32_bf16 v[124:127], v[138:141], v[154:157], v[124:127]
	v_mfma_f32_16x16x32_bf16 v[120:123], v[146:149], v[154:157], v[120:123]
	v_mfma_f32_16x16x32_bf16 v[112:115], v[138:141], v[162:165], v[112:115]
	v_mfma_f32_16x16x32_bf16 v[104:107], v[146:149], v[162:165], v[104:107]
	v_mfma_f32_16x16x32_bf16 v[96:99], v[138:141], v[170:173], v[96:99]
	v_mfma_f32_16x16x32_bf16 v[88:91], v[146:149], v[170:173], v[88:91]
	v_mfma_f32_16x16x32_bf16 v[80:83], v[138:141], v[178:181], v[80:83]
	v_mfma_f32_16x16x32_bf16 v[72:75], v[146:149], v[178:181], v[72:75]
	v_mfma_f32_16x16x32_bf16 v[124:127], v[142:145], v[158:161], v[124:127]
	v_mfma_f32_16x16x32_bf16 v[120:123], v[150:153], v[158:161], v[120:123]
	v_mfma_f32_16x16x32_bf16 v[112:115], v[142:145], v[166:169], v[112:115]
	v_mfma_f32_16x16x32_bf16 v[104:107], v[150:153], v[166:169], v[104:107]
	v_mfma_f32_16x16x32_bf16 v[96:99], v[142:145], v[174:177], v[96:99]
	v_mfma_f32_16x16x32_bf16 v[88:91], v[150:153], v[174:177], v[88:91]
	v_mfma_f32_16x16x32_bf16 v[80:83], v[142:145], v[182:185], v[80:83]
	v_mfma_f32_16x16x32_bf16 v[72:75], v[150:153], v[182:185], v[72:75]
	s_setprio 0
	s_barrier
	s_mov_b32 m0, s61
	v_lshl_add_u64 v[202:203], s[58:59], 0, v[128:129]
	ds_read_b128 v[186:189], v135
	ds_read_b128 v[190:193], v135 offset:1024
	ds_read_b128 v[194:197], v135 offset:2048
	ds_read_b128 v[198:201], v135 offset:3072
	global_load_lds_dwordx4 v[202:203], off
	v_lshl_add_u64 v[204:205], v[202:203], 0, s[4:5]
	s_mov_b32 m0, s70
	s_nop 0
	global_load_lds_dwordx4 v[204:205], off
	s_barrier
	s_waitcnt lgkmcnt(0)
	s_setprio 1
	s_waitcnt lgkmcnt(0)
	v_mfma_f32_16x16x32_bf16 v[116:119], v[186:189], v[154:157], v[116:119]
	v_mfma_f32_16x16x32_bf16 v[108:111], v[194:197], v[154:157], v[108:111]
	v_mfma_f32_16x16x32_bf16 v[100:103], v[186:189], v[162:165], v[100:103]
	v_mfma_f32_16x16x32_bf16 v[92:95], v[194:197], v[162:165], v[92:95]
	v_mfma_f32_16x16x32_bf16 v[84:87], v[186:189], v[170:173], v[84:87]
	v_mfma_f32_16x16x32_bf16 v[76:79], v[194:197], v[170:173], v[76:79]
	v_mfma_f32_16x16x32_bf16 v[68:71], v[186:189], v[178:181], v[68:71]
	v_mfma_f32_16x16x32_bf16 v[64:67], v[194:197], v[178:181], v[64:67]
	v_mfma_f32_16x16x32_bf16 v[116:119], v[190:193], v[158:161], v[116:119]
	v_mfma_f32_16x16x32_bf16 v[108:111], v[198:201], v[158:161], v[108:111]
	v_mfma_f32_16x16x32_bf16 v[100:103], v[190:193], v[166:169], v[100:103]
	v_mfma_f32_16x16x32_bf16 v[92:95], v[198:201], v[166:169], v[92:95]
	v_mfma_f32_16x16x32_bf16 v[84:87], v[190:193], v[174:177], v[84:87]
	v_mfma_f32_16x16x32_bf16 v[76:79], v[198:201], v[174:177], v[76:79]
	v_mfma_f32_16x16x32_bf16 v[68:71], v[190:193], v[182:185], v[68:71]
	v_mfma_f32_16x16x32_bf16 v[64:67], v[198:201], v[182:185], v[64:67]
	s_setprio 0
	s_mov_b32 m0, s36
	v_lshl_add_u64 v[204:205], s[56:57], 0, v[128:129]
	s_barrier
	ds_read_b128 v[154:157], v133 offset:16384
	ds_read_b128 v[158:161], v133 offset:17408
	ds_read_b128 v[162:165], v133 offset:18432
	ds_read_b128 v[166:169], v133 offset:19456
	ds_read_b128 v[170:173], v133 offset:20480
	ds_read_b128 v[174:177], v133 offset:21504
	ds_read_b128 v[178:181], v133 offset:22528
	ds_read_b128 v[182:185], v133 offset:23552
	global_load_lds_dwordx4 v[204:205], off
	v_lshl_add_u64 v[206:207], v[204:205], 0, s[4:5]
	s_mov_b32 m0, s37
	s_nop 0
	global_load_lds_dwordx4 v[206:207], off
	s_barrier
	s_waitcnt lgkmcnt(0)
	s_setprio 1
	s_waitcnt lgkmcnt(0)
	v_mfma_f32_16x16x32_bf16 v[60:63], v[138:141], v[154:157], v[60:63]
	v_mfma_f32_16x16x32_bf16 v[56:59], v[146:149], v[154:157], v[56:59]
	v_mfma_f32_16x16x32_bf16 v[48:51], v[138:141], v[162:165], v[48:51]
	v_mfma_f32_16x16x32_bf16 v[40:43], v[146:149], v[162:165], v[40:43]
	v_mfma_f32_16x16x32_bf16 v[32:35], v[138:141], v[170:173], v[32:35]
	v_mfma_f32_16x16x32_bf16 v[24:27], v[146:149], v[170:173], v[24:27]
	v_mfma_f32_16x16x32_bf16 v[16:19], v[138:141], v[178:181], v[16:19]
	v_mfma_f32_16x16x32_bf16 v[8:11], v[146:149], v[178:181], v[8:11]
	v_mfma_f32_16x16x32_bf16 v[60:63], v[142:145], v[158:161], v[60:63]
	v_mfma_f32_16x16x32_bf16 v[56:59], v[150:153], v[158:161], v[56:59]
	v_mfma_f32_16x16x32_bf16 v[48:51], v[142:145], v[166:169], v[48:51]
	v_mfma_f32_16x16x32_bf16 v[40:43], v[150:153], v[166:169], v[40:43]
	v_mfma_f32_16x16x32_bf16 v[32:35], v[142:145], v[174:177], v[32:35]
	v_mfma_f32_16x16x32_bf16 v[24:27], v[150:153], v[174:177], v[24:27]
	v_mfma_f32_16x16x32_bf16 v[16:19], v[142:145], v[182:185], v[16:19]
	v_mfma_f32_16x16x32_bf16 v[8:11], v[150:153], v[182:185], v[8:11]
	s_setprio 0
	s_barrier
; #define PG8_STAGE(bufoff, gbase, voff) do { _Pragma("unroll") for (int _i = 0; _i < 2; ++_i) \
;         __builtin_amdgcn_global_load_lds((const unsigned*)((const char*)(gbase) + (size_t)_i * r64##voff + (voff)), (LAS unsigned*)(lds + (bufoff) + ldsw + _i * 8192), 16, 0, 0); } while (0)
; #define PG8_LDA(dst, b, h) do { _Pragma("unroll") for (int m = 0; m < 4; ++m) _Pragma("unroll") for (int k = 0; k < 2; ++k) dst[m][k] = *(const LAS bf16x8*)(lds + PG8_SA(b, h) + aoff + m * 2048 + k * 1024); } while (0)
; #define PG8_LDB(dst, b, h) do { _Pragma("unroll") for (int n = 0; n < 2; ++n) _Pragma("unroll") for (int k = 0; k < 2; ++k) dst[n][k] = *(const LAS bf16x8*)(lds + PG8_SB(b, h) + boff + n * 2048 + k * 1024); } while (0)
; #define PG8_MMA(ai, bj, At, Bt) do { __builtin_amdgcn_s_setprio(1); _Pragma("unroll") for (int m = 0; m < 4; ++m) _Pragma("unroll") for (int n = 0; n < 2; ++n) _Pragma("unroll") for (int k = 0; k < 2; ++k) \
;         acc[ai][bj][m][n] = __builtin_amdgcn_mfma_f32_16x16x32_bf16(Bt[n][k], At[m][k], acc[ai][bj][m][n], 0, 0, 0); __builtin_amdgcn_s_setprio(0); } while (0)
; #define PG8_WAIT_V(n) asm volatile("s_waitcnt vmcnt(" #n ")" ::: "memory")
; #define PG8_WAIT_L(n) asm volatile("s_waitcnt lgkmcnt(" #n ")" ::: "memory")
; #define PG8_BAR __builtin_amdgcn_s_barrier()
; #define PG8_SCHED __builtin_amdgcn_sched_barrier(0)
; template <class Epi, class Sched>
; __device__ __forceinline__ void gemm_phase(LAS unsigned char* lds, const Gemm g, const Sched& S, const Epi& E) {
;     ...
;             PG8_STAGE(PG8_SB(0, 1), b2 + hstepB, voffB);
;             PG8_WAIT_V(6); PG8_BAR; PG8_MMA(1, 1, At, B1); PG8_BAR;
;             PG8_LDB(B0, 1, 0); PG8_SCHED; PG8_LDA(At, 1, 0); PG8_STAGE(PG8_SA(0, 1), a2 + hstepA, voffA);
;             PG8_WAIT_L(8); PG8_BAR; PG8_WAIT_L(0); PG8_MMA(0, 0, At, B0); PG8_BAR; PG8_SCHED;
;             PG8_LDB(B1, 1, 1); PG8_STAGE(PG8_SB(1, 0), b3, voffB);
;             PG8_BAR; PG8_WAIT_L(0); PG8_MMA(0, 1, At, B1); PG8_BAR;
;             PG8_LDA(At, 1, 1); PG8_STAGE(PG8_SA(1, 0), a3, voffA);
;             PG8_BAR; PG8_WAIT_L(0); PG8_MMA(1, 0, At, B0); PG8_BAR; PG8_SCHED;
	s_mov_b32 m0, s68
	v_lshl_add_u64 v[138:139], v[202:203], 0, s[6:7]
	global_load_lds_dwordx4 v[138:139], off
	v_lshl_add_u64 v[138:139], v[202:203], 0, s[8:9]
	s_mov_b32 m0, s66
	s_nop 0
	global_load_lds_dwordx4 v[138:139], off
	s_waitcnt vmcnt(6)
	s_barrier
	s_setprio 1
	v_mfma_f32_16x16x32_bf16 v[52:55], v[186:189], v[154:157], v[52:55]
	v_mfma_f32_16x16x32_bf16 v[44:47], v[194:197], v[154:157], v[44:47]
	v_mfma_f32_16x16x32_bf16 v[36:39], v[186:189], v[162:165], v[36:39]
	v_mfma_f32_16x16x32_bf16 v[28:31], v[194:197], v[162:165], v[28:31]
	v_mfma_f32_16x16x32_bf16 v[20:23], v[186:189], v[170:173], v[20:23]
	v_mfma_f32_16x16x32_bf16 v[12:15], v[194:197], v[170:173], v[12:15]
	v_mfma_f32_16x16x32_bf16 v[4:7], v[186:189], v[178:181], v[4:7]
	v_mfma_f32_16x16x32_bf16 v[0:3], v[194:197], v[178:181], v[0:3]
	v_mfma_f32_16x16x32_bf16 v[52:55], v[190:193], v[158:161], v[52:55]
	v_mfma_f32_16x16x32_bf16 v[44:47], v[198:201], v[158:161], v[44:47]
	v_mfma_f32_16x16x32_bf16 v[36:39], v[190:193], v[166:169], v[36:39]
	v_mfma_f32_16x16x32_bf16 v[28:31], v[198:201], v[166:169], v[28:31]
	v_mfma_f32_16x16x32_bf16 v[20:23], v[190:193], v[174:177], v[20:23]
	v_mfma_f32_16x16x32_bf16 v[12:15], v[198:201], v[174:177], v[12:15]
	v_mfma_f32_16x16x32_bf16 v[4:7], v[190:193], v[182:185], v[4:7]
	v_mfma_f32_16x16x32_bf16 v[0:3], v[198:201], v[182:185], v[0:3]
	s_setprio 0
	v_add_u32_e32 v137, s65, v132
	s_barrier
	ds_read_b128 v[138:141], v137
	ds_read_b128 v[142:145], v137 offset:1024
	ds_read_b128 v[146:149], v137 offset:2048
	ds_read_b128 v[150:153], v137 offset:3072
	s_mov_b32 m0, s38
	v_lshl_add_u64 v[186:187], v[204:205], 0, s[6:7]
	ds_read_b128 v[154:157], v133 offset:32768
	ds_read_b128 v[158:161], v133 offset:33792
	ds_read_b128 v[162:165], v133 offset:34816
	ds_read_b128 v[166:169], v133 offset:35840
	ds_read_b128 v[170:173], v133 offset:36864
	ds_read_b128 v[174:177], v133 offset:37888
	ds_read_b128 v[178:181], v133 offset:38912
	ds_read_b128 v[182:185], v133 offset:39936
	global_load_lds_dwordx4 v[186:187], off
	v_lshl_add_u64 v[186:187], v[204:205], 0, s[8:9]
	s_mov_b32 m0, s39
	s_nop 0
	global_load_lds_dwordx4 v[186:187], off
	s_waitcnt lgkmcnt(8)
	s_barrier
	s_waitcnt lgkmcnt(0)
	s_setprio 1
	s_waitcnt lgkmcnt(0)
	v_mfma_f32_16x16x32_bf16 v[124:127], v[138:141], v[154:157], v[124:127]
	v_mfma_f32_16x16x32_bf16 v[120:123], v[146:149], v[154:157], v[120:123]
	v_mfma_f32_16x16x32_bf16 v[112:115], v[138:141], v[162:165], v[112:115]
	v_mfma_f32_16x16x32_bf16 v[104:107], v[146:149], v[162:165], v[104:107]
	v_mfma_f32_16x16x32_bf16 v[96:99], v[138:141], v[170:173], v[96:99]
	v_mfma_f32_16x16x32_bf16 v[88:91], v[146:149], v[170:173], v[88:91]
	v_mfma_f32_16x16x32_bf16 v[80:83], v[138:141], v[178:181], v[80:83]
	v_mfma_f32_16x16x32_bf16 v[72:75], v[146:149], v[178:181], v[72:75]
	v_mfma_f32_16x16x32_bf16 v[124:127], v[142:145], v[158:161], v[124:127]
	v_mfma_f32_16x16x32_bf16 v[120:123], v[150:153], v[158:161], v[120:123]
	v_mfma_f32_16x16x32_bf16 v[112:115], v[142:145], v[166:169], v[112:115]
	v_mfma_f32_16x16x32_bf16 v[104:107], v[150:153], v[166:169], v[104:107]
	v_mfma_f32_16x16x32_bf16 v[96:99], v[142:145], v[174:177], v[96:99]
	v_mfma_f32_16x16x32_bf16 v[88:91], v[150:153], v[174:177], v[88:91]
	v_mfma_f32_16x16x32_bf16 v[80:83], v[142:145], v[182:185], v[80:83]
	v_mfma_f32_16x16x32_bf16 v[72:75], v[150:153], v[182:185], v[72:75]
	s_setprio 0
	s_barrier
	s_mov_b32 m0, s64
	v_add_u32_e32 v137, s63, v132
	v_lshl_add_u64 v[206:207], v[202:203], 0, s[10:11]
	ds_read_b128 v[186:189], v137
	ds_read_b128 v[190:193], v137 offset:1024
	ds_read_b128 v[194:197], v137 offset:2048
	ds_read_b128 v[198:201], v137 offset:3072
	global_load_lds_dwordx4 v[206:207], off
	v_lshl_add_u64 v[206:207], v[202:203], 0, s[16:17]
	s_mov_b32 m0, s71
	s_nop 0
	global_load_lds_dwordx4 v[206:207], off
	s_barrier
	s_waitcnt lgkmcnt(0)
	s_setprio 1
	s_waitcnt lgkmcnt(0)
	v_mfma_f32_16x16x32_bf16 v[116:119], v[186:189], v[154:157], v[116:119]
	v_mfma_f32_16x16x32_bf16 v[108:111], v[194:197], v[154:157], v[108:111]
	v_mfma_f32_16x16x32_bf16 v[100:103], v[186:189], v[162:165], v[100:103]
	v_mfma_f32_16x16x32_bf16 v[92:95], v[194:197], v[162:165], v[92:95]
	v_mfma_f32_16x16x32_bf16 v[84:87], v[186:189], v[170:173], v[84:87]
	v_mfma_f32_16x16x32_bf16 v[76:79], v[194:197], v[170:173], v[76:79]
	v_mfma_f32_16x16x32_bf16 v[68:71], v[186:189], v[178:181], v[68:71]
	v_mfma_f32_16x16x32_bf16 v[64:67], v[194:197], v[178:181], v[64:67]
	v_mfma_f32_16x16x32_bf16 v[116:119], v[190:193], v[158:161], v[116:119]
	v_mfma_f32_16x16x32_bf16 v[108:111], v[198:201], v[158:161], v[108:111]
	v_mfma_f32_16x16x32_bf16 v[100:103], v[190:193], v[166:169], v[100:103]
	v_mfma_f32_16x16x32_bf16 v[92:95], v[198:201], v[166:169], v[92:95]
	v_mfma_f32_16x16x32_bf16 v[84:87], v[190:193], v[174:177], v[84:87]
	v_mfma_f32_16x16x32_bf16 v[76:79], v[198:201], v[174:177], v[76:79]
	v_mfma_f32_16x16x32_bf16 v[68:71], v[190:193], v[182:185], v[68:71]
	v_mfma_f32_16x16x32_bf16 v[64:67], v[198:201], v[182:185], v[64:67]
	s_setprio 0
	s_mov_b32 m0, s40
	v_lshl_add_u64 v[206:207], v[204:205], 0, s[10:11]
	s_barrier
	ds_read_b128 v[154:157], v133 offset:49152
	ds_read_b128 v[158:161], v133 offset:50176
	ds_read_b128 v[162:165], v133 offset:51200
	ds_read_b128 v[166:169], v133 offset:52224
	ds_read_b128 v[170:173], v133 offset:53248
	ds_read_b128 v[174:177], v133 offset:54272
	ds_read_b128 v[178:181], v133 offset:55296
	ds_read_b128 v[182:185], v133 offset:56320
	global_load_lds_dwordx4 v[206:207], off
	v_lshl_add_u64 v[204:205], v[204:205], 0, s[16:17]
	s_mov_b32 m0, s41
	s_nop 0
	global_load_lds_dwordx4 v[204:205], off
	s_barrier
; __device__ __forceinline__ int otid() { int t = (int)__builtin_amdgcn_workitem_id_x(); asm volatile("" : "+v"(t)); return t; }
; #define PG8_STAGE(bufoff, gbase, voff) do { _Pragma("unroll") for (int _i = 0; _i < 2; ++_i) \
;         __builtin_amdgcn_global_load_lds((const unsigned*)((const char*)(gbase) + (size_t)_i * r64##voff + (voff)), (LAS unsigned*)(lds + (bufoff) + ldsw + _i * 8192), 16, 0, 0); } while (0)
; #define PG8_WAIT_V(n) asm volatile("s_waitcnt vmcnt(" #n ")" ::: "memory")
; #define PG8_WAIT_L(n) asm volatile("s_waitcnt lgkmcnt(" #n ")" ::: "memory")
; #define PG8_BAR __builtin_amdgcn_s_barrier()
; #define PG8_SCHED __builtin_amdgcn_sched_barrier(0)
; template <class Epi, class Sched>
; __device__ __forceinline__ void gemm_phase(LAS unsigned char* lds, const Gemm g, const Sched& S, const Epi& E) {
;     ...
;             PG8_BAR; PG8_WAIT_L(0); PG8_MMA(1, 0, At, B0); PG8_BAR; PG8_SCHED;
;             PG8_STAGE(PG8_SB(1, 1), b3 + hstepB, voffB);
;             PG8_WAIT_V(6); PG8_BAR; PG8_MMA(1, 1, At, B1); PG8_BAR;
;     __device__ __forceinline__ void operator()(const f32x4 (&acc)[2][2][4][2], const pg8::Unit& u, int wr_, int wc_, int fr_, int fq_) const {
;         const int t2_ = otid(), wr = t2_ >> 8, wc = (t2_ >> 6) & 3, fr = t2_ & 15, fq = (t2_ >> 4) & 3; (void)wr_; (void)wc_; (void)fr_; (void)fq_;
;         float* dst = dstC - (size_t)RL * 2048;
;         const int row0 = u.pm * 256 + wr * 64 + fr, col0 = u.pn * 256 + wc * 32 + 4 * fq;
; #pragma unroll
;         for (int ai = 0; ai < 2; ++ai)
; #pragma unroll
;             for (int m = 0; m < 4; ++m) { const size_t ro = (size_t)(row0 + ai * 128 + m * 16) * 2048;
; #pragma unroll
;                 for (int bj = 0; bj < 2; ++bj)
; #pragma unroll
;                     for (int n = 0; n < 2; ++n) { const int col = col0 + bj * 128 + n * 16;
;                         const f32x4 v = *(const f32x4*)(gate + col) * acc[ai][bj][m][n];
;                         __hip_atomic_fetch_add(dst + ro + col, v[0], __ATOMIC_RELAXED, __HIP_MEMORY_SCOPE_AGENT); __hip_atomic_fetch_add(dst + ro + col + 1, v[1], __ATOMIC_RELAXED, __HIP_MEMORY_SCOPE_AGENT);
;                         __hip_atomic_fetch_add(dst + ro + col + 2, v[2], __ATOMIC_RELAXED, __HIP_MEMORY_SCOPE_AGENT); __hip_atomic_fetch_add(dst + ro + col + 3, v[3], __ATOMIC_RELAXED, __HIP_MEMORY_SCOPE_AGENT); } }
;     }
	s_waitcnt lgkmcnt(0)
	s_setprio 1
	s_waitcnt lgkmcnt(0)
	v_mfma_f32_16x16x32_bf16 v[60:63], v[138:141], v[154:157], v[60:63]
	v_mfma_f32_16x16x32_bf16 v[56:59], v[146:149], v[154:157], v[56:59]
	v_mfma_f32_16x16x32_bf16 v[48:51], v[138:141], v[162:165], v[48:51]
	v_mfma_f32_16x16x32_bf16 v[40:43], v[146:149], v[162:165], v[40:43]
	v_mfma_f32_16x16x32_bf16 v[32:35], v[138:141], v[170:173], v[32:35]
	v_mfma_f32_16x16x32_bf16 v[24:27], v[146:149], v[170:173], v[24:27]
	v_mfma_f32_16x16x32_bf16 v[16:19], v[138:141], v[178:181], v[16:19]
	v_mfma_f32_16x16x32_bf16 v[8:11], v[146:149], v[178:181], v[8:11]
	v_mfma_f32_16x16x32_bf16 v[60:63], v[142:145], v[158:161], v[60:63]
	v_mfma_f32_16x16x32_bf16 v[56:59], v[150:153], v[158:161], v[56:59]
	v_mfma_f32_16x16x32_bf16 v[48:51], v[142:145], v[166:169], v[48:51]
	v_mfma_f32_16x16x32_bf16 v[40:43], v[150:153], v[166:169], v[40:43]
	v_mfma_f32_16x16x32_bf16 v[32:35], v[142:145], v[174:177], v[32:35]
	v_mfma_f32_16x16x32_bf16 v[24:27], v[150:153], v[174:177], v[24:27]
	v_mfma_f32_16x16x32_bf16 v[16:19], v[142:145], v[182:185], v[16:19]
	v_mfma_f32_16x16x32_bf16 v[8:11], v[150:153], v[182:185], v[8:11]
	s_setprio 0
	s_barrier
	s_mov_b32 m0, s69
	v_lshl_add_u64 v[138:139], v[202:203], 0, s[18:19]
	global_load_lds_dwordx4 v[138:139], off
	v_lshl_add_u64 v[138:139], v[202:203], 0, s[20:21]
	s_mov_b32 m0, s67
	s_nop 0
	global_load_lds_dwordx4 v[138:139], off
	s_waitcnt vmcnt(6)
	s_barrier
	s_setprio 1
	v_mfma_f32_16x16x32_bf16 v[52:55], v[186:189], v[154:157], v[52:55]
	v_mfma_f32_16x16x32_bf16 v[44:47], v[194:197], v[154:157], v[44:47]
	v_mfma_f32_16x16x32_bf16 v[36:39], v[186:189], v[162:165], v[36:39]
	v_mfma_f32_16x16x32_bf16 v[28:31], v[194:197], v[162:165], v[28:31]
	v_mfma_f32_16x16x32_bf16 v[20:23], v[186:189], v[170:173], v[20:23]
	v_mfma_f32_16x16x32_bf16 v[12:15], v[194:197], v[170:173], v[12:15]
	v_mfma_f32_16x16x32_bf16 v[4:7], v[186:189], v[178:181], v[4:7]
	v_mfma_f32_16x16x32_bf16 v[0:3], v[194:197], v[178:181], v[0:3]
	v_mfma_f32_16x16x32_bf16 v[52:55], v[190:193], v[158:161], v[52:55]
	v_mfma_f32_16x16x32_bf16 v[44:47], v[198:201], v[158:161], v[44:47]
	v_mfma_f32_16x16x32_bf16 v[36:39], v[190:193], v[166:169], v[36:39]
	v_mfma_f32_16x16x32_bf16 v[28:31], v[198:201], v[166:169], v[28:31]
	v_mfma_f32_16x16x32_bf16 v[20:23], v[190:193], v[174:177], v[20:23]
	v_mfma_f32_16x16x32_bf16 v[12:15], v[198:201], v[174:177], v[12:15]
	v_mfma_f32_16x16x32_bf16 v[4:7], v[190:193], v[182:185], v[4:7]
	v_mfma_f32_16x16x32_bf16 v[0:3], v[198:201], v[182:185], v[0:3]
	s_setprio 0
	s_andn2_b64 vcc, exec, s[54:55]
	s_mov_b64 s[56:57], -1
	s_mov_b64 s[54:55], 0
	s_mov_b32 s2, s62
	s_barrier
	s_cbranch_vccz .LBB0_485
	s_add_u32 s48, s52, 0x66b4000
	s_addc_u32 s49, s53, 0
	v_mov_b32_e32 v128, v222
	s_add_u32 s46, s50, 0xfde80000
	s_addc_u32 s47, s51, -1
	v_lshrrev_b32_e32 v130, 1, v128
	v_lshrrev_b32_e32 v131, 2, v128
	s_lshl_b32 s2, s44, 8
	v_and_b32_e32 v130, 0x60, v130
	v_and_b32_e32 v131, 12, v131
	v_or3_b32 v142, v130, s2, v131
	v_ashrrev_i32_e32 v143, 31, v142
	v_lshlrev_b64 v[144:145], 2, v[142:143]
	v_lshl_add_u64 v[130:131], s[48:49], 0, v[144:145]
	v_ashrrev_i32_e32 v132, 2, v128
	s_lshl_b32 s2, s12, 8
	v_and_b32_e32 v132, 0xffffffc0, v132
	v_and_or_b32 v128, v128, 15, s2
	v_add_u32_e32 v146, v128, v132
	v_ashrrev_i32_e32 v147, 31, v146
	v_lshlrev_b64 v[134:135], 13, v[146:147]
	v_or_b32_e32 v132, 16, v142
	v_lshl_add_u64 v[134:135], s[46:47], 0, v[134:135]
	v_ashrrev_i32_e32 v133, 31, v132
	v_lshl_add_u64 v[134:135], v[134:135], 0, v[144:145]
	v_lshl_add_u64 v[132:133], v[132:133], 2, s[48:49]
	s_cmpk_lt_u32 s34, 0x100
	s_mov_b32 s98, 0x20000
	s_mov_b32 s99, 0
	s_mov_b32 s100, 0xa0000
	s_mov_b32 s101, 0
	global_load_dwordx4 v[138:141], v[130:131], off
	global_load_dwordx4 v[148:151], v[130:131], off offset:64
	global_load_dwordx4 v[152:155], v[130:131], off offset:512
	global_load_dwordx4 v[156:159], v[130:131], off offset:576
	s_waitcnt vmcnt(0)
	v_pk_mul_f32 v[124:125], v[124:125], v[138:139]
	v_pk_mul_f32 v[126:127], v[126:127], v[140:141]
	global_atomic_add_f32 v[134:135], v124, off
	global_atomic_add_f32 v[134:135], v125, off offset:4
	global_atomic_add_f32 v[134:135], v126, off offset:8
	global_atomic_add_f32 v[134:135], v127, off offset:12
	v_pk_mul_f32 v[120:121], v[120:121], v[148:149]
	v_pk_mul_f32 v[122:123], v[122:123], v[150:151]
	global_atomic_add_f32 v[134:135], v120, off offset:64
	global_atomic_add_f32 v[134:135], v121, off offset:68
	global_atomic_add_f32 v[134:135], v122, off offset:72
	global_atomic_add_f32 v[134:135], v123, off offset:76
	v_pk_mul_f32 v[116:117], v[116:117], v[152:153]
	v_pk_mul_f32 v[118:119], v[118:119], v[154:155]
	global_atomic_add_f32 v[134:135], v116, off offset:512
	global_atomic_add_f32 v[134:135], v117, off offset:516
	global_atomic_add_f32 v[134:135], v118, off offset:520
	global_atomic_add_f32 v[134:135], v119, off offset:524
	v_pk_mul_f32 v[108:109], v[108:109], v[156:157]
	v_pk_mul_f32 v[110:111], v[110:111], v[158:159]
	global_atomic_add_f32 v[134:135], v108, off offset:576
	global_atomic_add_f32 v[134:135], v109, off offset:580
	global_atomic_add_f32 v[134:135], v110, off offset:584
	global_atomic_add_f32 v[134:135], v111, off offset:588
	v_lshl_add_u64 v[134:135], v[134:135], 0, s[98:99]
	v_pk_mul_f32 v[112:113], v[112:113], v[138:139]
	v_pk_mul_f32 v[114:115], v[114:115], v[140:141]
	global_atomic_add_f32 v[134:135], v112, off
	global_atomic_add_f32 v[134:135], v113, off offset:4
	global_atomic_add_f32 v[134:135], v114, off offset:8
	global_atomic_add_f32 v[134:135], v115, off offset:12
	v_pk_mul_f32 v[104:105], v[104:105], v[148:149]
;     __device__ __forceinline__ void operator()(const f32x4 (&acc)[2][2][4][2], const pg8::Unit& u, int wr_, int wc_, int fr_, int fq_) const {
;     ...
; #pragma unroll
;         for (int ai = 0; ai < 2; ++ai)
; #pragma unroll
;             for (int m = 0; m < 4; ++m) { const size_t ro = (size_t)(row0 + ai * 128 + m * 16) * 2048;
; #pragma unroll
;                 for (int bj = 0; bj < 2; ++bj)
; #pragma unroll
;                     for (int n = 0; n < 2; ++n) { const int col = col0 + bj * 128 + n * 16;
;                         const f32x4 v = *(const f32x4*)(gate + col) * acc[ai][bj][m][n];
;                         __hip_atomic_fetch_add(dst + ro + col, v[0], __ATOMIC_RELAXED, __HIP_MEMORY_SCOPE_AGENT); __hip_atomic_fetch_add(dst + ro + col + 1, v[1], __ATOMIC_RELAXED, __HIP_MEMORY_SCOPE_AGENT);
;                         __hip_atomic_fetch_add(dst + ro + col + 2, v[2], __ATOMIC_RELAXED, __HIP_MEMORY_SCOPE_AGENT); __hip_atomic_fetch_add(dst + ro + col + 3, v[3], __ATOMIC_RELAXED, __HIP_MEMORY_SCOPE_AGENT); } }
;     }
	v_pk_mul_f32 v[106:107], v[106:107], v[150:151]
	global_atomic_add_f32 v[134:135], v104, off offset:64
	global_atomic_add_f32 v[134:135], v105, off offset:68
	global_atomic_add_f32 v[134:135], v106, off offset:72
	global_atomic_add_f32 v[134:135], v107, off offset:76
	v_pk_mul_f32 v[100:101], v[100:101], v[152:153]
	v_pk_mul_f32 v[102:103], v[102:103], v[154:155]
	global_atomic_add_f32 v[134:135], v100, off offset:512
	global_atomic_add_f32 v[134:135], v101, off offset:516
	global_atomic_add_f32 v[134:135], v102, off offset:520
	global_atomic_add_f32 v[134:135], v103, off offset:524
	v_pk_mul_f32 v[92:93], v[92:93], v[156:157]
	v_pk_mul_f32 v[94:95], v[94:95], v[158:159]
	global_atomic_add_f32 v[134:135], v92, off offset:576
	global_atomic_add_f32 v[134:135], v93, off offset:580
	global_atomic_add_f32 v[134:135], v94, off offset:584
	global_atomic_add_f32 v[134:135], v95, off offset:588
	v_lshl_add_u64 v[134:135], v[134:135], 0, s[98:99]
	v_pk_mul_f32 v[96:97], v[96:97], v[138:139]
	v_pk_mul_f32 v[98:99], v[98:99], v[140:141]
	global_atomic_add_f32 v[134:135], v96, off
	global_atomic_add_f32 v[134:135], v97, off offset:4
	global_atomic_add_f32 v[134:135], v98, off offset:8
	global_atomic_add_f32 v[134:135], v99, off offset:12
	v_pk_mul_f32 v[88:89], v[88:89], v[148:149]
	v_pk_mul_f32 v[90:91], v[90:91], v[150:151]
	global_atomic_add_f32 v[134:135], v88, off offset:64
	global_atomic_add_f32 v[134:135], v89, off offset:68
	global_atomic_add_f32 v[134:135], v90, off offset:72
	global_atomic_add_f32 v[134:135], v91, off offset:76
	v_pk_mul_f32 v[84:85], v[84:85], v[152:153]
	v_pk_mul_f32 v[86:87], v[86:87], v[154:155]
	global_atomic_add_f32 v[134:135], v84, off offset:512
	global_atomic_add_f32 v[134:135], v85, off offset:516
	global_atomic_add_f32 v[134:135], v86, off offset:520
	global_atomic_add_f32 v[134:135], v87, off offset:524
	v_pk_mul_f32 v[76:77], v[76:77], v[156:157]
	v_pk_mul_f32 v[78:79], v[78:79], v[158:159]
	global_atomic_add_f32 v[134:135], v76, off offset:576
	global_atomic_add_f32 v[134:135], v77, off offset:580
	global_atomic_add_f32 v[134:135], v78, off offset:584
	global_atomic_add_f32 v[134:135], v79, off offset:588
	v_lshl_add_u64 v[134:135], v[134:135], 0, s[98:99]
	v_pk_mul_f32 v[80:81], v[80:81], v[138:139]
	v_pk_mul_f32 v[82:83], v[82:83], v[140:141]
	global_atomic_add_f32 v[134:135], v80, off
	global_atomic_add_f32 v[134:135], v81, off offset:4
	global_atomic_add_f32 v[134:135], v82, off offset:8
	global_atomic_add_f32 v[134:135], v83, off offset:12
	v_pk_mul_f32 v[72:73], v[72:73], v[148:149]
	v_pk_mul_f32 v[74:75], v[74:75], v[150:151]
	global_atomic_add_f32 v[134:135], v72, off offset:64
	global_atomic_add_f32 v[134:135], v73, off offset:68
	global_atomic_add_f32 v[134:135], v74, off offset:72
	global_atomic_add_f32 v[134:135], v75, off offset:76
	v_pk_mul_f32 v[68:69], v[68:69], v[152:153]
	v_pk_mul_f32 v[70:71], v[70:71], v[154:155]
	global_atomic_add_f32 v[134:135], v68, off offset:512
	global_atomic_add_f32 v[134:135], v69, off offset:516
	global_atomic_add_f32 v[134:135], v70, off offset:520
	global_atomic_add_f32 v[134:135], v71, off offset:524
	v_pk_mul_f32 v[64:65], v[64:65], v[156:157]
	v_pk_mul_f32 v[66:67], v[66:67], v[158:159]
	global_atomic_add_f32 v[134:135], v64, off offset:576
	global_atomic_add_f32 v[134:135], v65, off offset:580
	global_atomic_add_f32 v[134:135], v66, off offset:584
	global_atomic_add_f32 v[134:135], v67, off offset:588
	v_lshl_add_u64 v[134:135], v[134:135], 0, s[100:101]
	v_pk_mul_f32 v[60:61], v[60:61], v[138:139]
	v_pk_mul_f32 v[62:63], v[62:63], v[140:141]
	global_atomic_add_f32 v[134:135], v60, off
	global_atomic_add_f32 v[134:135], v61, off offset:4
	global_atomic_add_f32 v[134:135], v62, off offset:8
	global_atomic_add_f32 v[134:135], v63, off offset:12
	v_pk_mul_f32 v[56:57], v[56:57], v[148:149]
	v_pk_mul_f32 v[58:59], v[58:59], v[150:151]
	global_atomic_add_f32 v[134:135], v56, off offset:64
	global_atomic_add_f32 v[134:135], v57, off offset:68
	global_atomic_add_f32 v[134:135], v58, off offset:72
	global_atomic_add_f32 v[134:135], v59, off offset:76
	v_pk_mul_f32 v[52:53], v[52:53], v[152:153]
	v_pk_mul_f32 v[54:55], v[54:55], v[154:155]
	global_atomic_add_f32 v[134:135], v52, off offset:512
	global_atomic_add_f32 v[134:135], v53, off offset:516
;     __device__ __forceinline__ void operator()(const f32x4 (&acc)[2][2][4][2], const pg8::Unit& u, int wr_, int wc_, int fr_, int fq_) const {
;     ...
; #pragma unroll
;         for (int ai = 0; ai < 2; ++ai)
; #pragma unroll
;             for (int m = 0; m < 4; ++m) { const size_t ro = (size_t)(row0 + ai * 128 + m * 16) * 2048;
; #pragma unroll
;                 for (int bj = 0; bj < 2; ++bj)
; #pragma unroll
;                     for (int n = 0; n < 2; ++n) { const int col = col0 + bj * 128 + n * 16;
;                         const f32x4 v = *(const f32x4*)(gate + col) * acc[ai][bj][m][n];
;                         __hip_atomic_fetch_add(dst + ro + col, v[0], __ATOMIC_RELAXED, __HIP_MEMORY_SCOPE_AGENT); __hip_atomic_fetch_add(dst + ro + col + 1, v[1], __ATOMIC_RELAXED, __HIP_MEMORY_SCOPE_AGENT);
;                         __hip_atomic_fetch_add(dst + ro + col + 2, v[2], __ATOMIC_RELAXED, __HIP_MEMORY_SCOPE_AGENT); __hip_atomic_fetch_add(dst + ro + col + 3, v[3], __ATOMIC_RELAXED, __HIP_MEMORY_SCOPE_AGENT); } }
;     }
	global_atomic_add_f32 v[134:135], v54, off offset:520
	global_atomic_add_f32 v[134:135], v55, off offset:524
	v_pk_mul_f32 v[44:45], v[44:45], v[156:157]
	v_pk_mul_f32 v[46:47], v[46:47], v[158:159]
	global_atomic_add_f32 v[134:135], v44, off offset:576
	global_atomic_add_f32 v[134:135], v45, off offset:580
	global_atomic_add_f32 v[134:135], v46, off offset:584
	global_atomic_add_f32 v[134:135], v47, off offset:588
	v_lshl_add_u64 v[134:135], v[134:135], 0, s[98:99]
	v_pk_mul_f32 v[48:49], v[48:49], v[138:139]
	v_pk_mul_f32 v[50:51], v[50:51], v[140:141]
	global_atomic_add_f32 v[134:135], v48, off
	global_atomic_add_f32 v[134:135], v49, off offset:4
	global_atomic_add_f32 v[134:135], v50, off offset:8
	global_atomic_add_f32 v[134:135], v51, off offset:12
	v_pk_mul_f32 v[40:41], v[40:41], v[148:149]
	v_pk_mul_f32 v[42:43], v[42:43], v[150:151]
	global_atomic_add_f32 v[134:135], v40, off offset:64
	global_atomic_add_f32 v[134:135], v41, off offset:68
	global_atomic_add_f32 v[134:135], v42, off offset:72
	global_atomic_add_f32 v[134:135], v43, off offset:76
	v_pk_mul_f32 v[36:37], v[36:37], v[152:153]
	v_pk_mul_f32 v[38:39], v[38:39], v[154:155]
	global_atomic_add_f32 v[134:135], v36, off offset:512
	global_atomic_add_f32 v[134:135], v37, off offset:516
	global_atomic_add_f32 v[134:135], v38, off offset:520
	global_atomic_add_f32 v[134:135], v39, off offset:524
	v_pk_mul_f32 v[28:29], v[28:29], v[156:157]
	v_pk_mul_f32 v[30:31], v[30:31], v[158:159]
	global_atomic_add_f32 v[134:135], v28, off offset:576
	global_atomic_add_f32 v[134:135], v29, off offset:580
	global_atomic_add_f32 v[134:135], v30, off offset:584
	global_atomic_add_f32 v[134:135], v31, off offset:588
	v_lshl_add_u64 v[134:135], v[134:135], 0, s[98:99]
	v_pk_mul_f32 v[32:33], v[32:33], v[138:139]
	v_pk_mul_f32 v[34:35], v[34:35], v[140:141]
	global_atomic_add_f32 v[134:135], v32, off
	global_atomic_add_f32 v[134:135], v33, off offset:4
	global_atomic_add_f32 v[134:135], v34, off offset:8
	global_atomic_add_f32 v[134:135], v35, off offset:12
	v_pk_mul_f32 v[24:25], v[24:25], v[148:149]
	v_pk_mul_f32 v[26:27], v[26:27], v[150:151]
	global_atomic_add_f32 v[134:135], v24, off offset:64
	global_atomic_add_f32 v[134:135], v25, off offset:68
	global_atomic_add_f32 v[134:135], v26, off offset:72
	global_atomic_add_f32 v[134:135], v27, off offset:76
	v_pk_mul_f32 v[20:21], v[20:21], v[152:153]
	v_pk_mul_f32 v[22:23], v[22:23], v[154:155]
	global_atomic_add_f32 v[134:135], v20, off offset:512
	global_atomic_add_f32 v[134:135], v21, off offset:516
	global_atomic_add_f32 v[134:135], v22, off offset:520
	global_atomic_add_f32 v[134:135], v23, off offset:524
	v_pk_mul_f32 v[12:13], v[12:13], v[156:157]
	v_pk_mul_f32 v[14:15], v[14:15], v[158:159]
	global_atomic_add_f32 v[134:135], v12, off offset:576
	global_atomic_add_f32 v[134:135], v13, off offset:580
	global_atomic_add_f32 v[134:135], v14, off offset:584
	global_atomic_add_f32 v[134:135], v15, off offset:588
	v_lshl_add_u64 v[134:135], v[134:135], 0, s[98:99]
	v_pk_mul_f32 v[16:17], v[16:17], v[138:139]
	v_pk_mul_f32 v[18:19], v[18:19], v[140:141]
	global_atomic_add_f32 v[134:135], v16, off
	global_atomic_add_f32 v[134:135], v17, off offset:4
	global_atomic_add_f32 v[134:135], v18, off offset:8
	global_atomic_add_f32 v[134:135], v19, off offset:12
	v_pk_mul_f32 v[8:9], v[8:9], v[148:149]
	v_pk_mul_f32 v[10:11], v[10:11], v[150:151]
	global_atomic_add_f32 v[134:135], v8, off offset:64
	global_atomic_add_f32 v[134:135], v9, off offset:68
	global_atomic_add_f32 v[134:135], v10, off offset:72
	global_atomic_add_f32 v[134:135], v11, off offset:76
	v_pk_mul_f32 v[4:5], v[4:5], v[152:153]
	v_pk_mul_f32 v[6:7], v[6:7], v[154:155]
	global_atomic_add_f32 v[134:135], v4, off offset:512
	global_atomic_add_f32 v[134:135], v5, off offset:516
	global_atomic_add_f32 v[134:135], v6, off offset:520
	global_atomic_add_f32 v[134:135], v7, off offset:524
	v_pk_mul_f32 v[0:1], v[0:1], v[156:157]
	v_pk_mul_f32 v[2:3], v[2:3], v[158:159]
	global_atomic_add_f32 v[134:135], v0, off offset:576
	global_atomic_add_f32 v[134:135], v1, off offset:580
	global_atomic_add_f32 v[134:135], v2, off offset:584
	global_atomic_add_f32 v[134:135], v3, off offset:588
	s_cbranch_scc0 .LBB0_481
	s_barrier
	s_branch .LBB0_481

; __device__ __forceinline__ unsigned cvt_pk_bf16(float lo, float hi) { unsigned r; asm("v_cvt_pk_bf16_f32 %0, %1, %2" : "=v"(r) : "v"(lo), "v"(hi)); return r; }
; #define mod ((const float*)(getp().ws + O_MOD))
; #define hL (layer == 0 ? getp().in[0] : (const float*)getp().out)
; #define hC (layer == 0 ? getp().in[2] : (const float*)hctx)
; __device__ __forceinline__ void xn_row(const float* hrow, const float* g, const float* shift, const float* scale, bf16_t* orow, int lane) {
;     const float4* xr = (const float4*)hrow + lane;
;     float4 v[8]; float s = 0.f;
; #pragma unroll
;     for (int j = 0; j < 8; ++j) { v[j] = xr[64 * j]; s += v[j].x * v[j].x + v[j].y * v[j].y + v[j].z * v[j].z + v[j].w * v[j].w; }
;     const float r = rsqrtf(wave_sum(s) * (1.f / D) + 1e-6f);
;     u32x2* o = (u32x2*)orow + lane;
; #pragma unroll
;     for (int j = 0; j < 8; ++j) { const float4 gg = ((const float4*)g)[lane + 64 * j], sh = ((const float4*)shift)[lane + 64 * j], sc = ((const float4*)scale)[lane + 64 * j];
;         u32x2 w; w.x = cvt_pk_bf16(v[j].x * r * gg.x * (1.f + sc.x) + sh.x, v[j].y * r * gg.y * (1.f + sc.y) + sh.y);
;         w.y = cvt_pk_bf16(v[j].z * r * gg.z * (1.f + sc.z) + sh.z, v[j].w * r * gg.w * (1.f + sc.w) + sh.w);
;         o[64 * j] = w; }
; }
; __device__ __forceinline__ void xn_row1(PRef p, int layer, int which  , int row, int lane, const float* hL, const float* hC) {
;     const float* mod = (const float*)(p.ws + O_MOD);
;     const bool isc = row >= RL; const int mr = isc ? 4 : (row >> 12);
;     const float* m = mod + (size_t)(layer * 5 + mr) * 12288 + (which ? 3 * 2048 : 0);
;     const float* hrow = isc ? hC + (size_t)(row - RL) * 2048 : hL + (size_t)row * 2048;
;     xn_row(hrow, p.in[which ? 29 : 6] + layer * 2048, m, m + 2048, (bf16_t*)(p.ws + O_XN) + (size_t)row * 2048, lane);
.LBB0_502:
	s_or_b64 exec, exec, s[22:23]
	v_lshl_add_u64 v[0:1], v[0:1], 0, v[34:35]
	v_add_co_u32_e32 v52, vcc, s13, v0
	global_load_dwordx4 v[28:31], v[0:1], off
	global_load_dwordx4 v[24:27], v[0:1], off offset:1024
	global_load_dwordx4 v[20:23], v[0:1], off offset:2048
	global_load_dwordx4 v[16:19], v[0:1], off offset:3072
	v_addc_co_u32_e32 v53, vcc, 0, v1, vcc
	global_load_dwordx4 v[12:15], v[52:53], off
	global_load_dwordx4 v[8:11], v[52:53], off offset:1024
	global_load_dwordx4 v[4:7], v[52:53], off offset:2048
	global_load_dwordx4 v[0:3], v[52:53], off offset:3072
	s_load_dwordx2 s[20:21], s[18:19], 0x120
	s_nop 0
	s_load_dwordx2 s[18:19], s[18:19], 0xe8
	v_min_i32_e32 v52, 0x4000, v32
	v_cmp_lt_i32_e32 vcc, v60, v59
	v_ashrrev_i32_e32 v52, 12, v52
	v_lshlrev_b64 v[56:57], 12, v[56:57]
	v_cndmask_b32_e32 v53, v58, v60, vcc
	v_lshlrev_b32_e32 v67, 2, v53
	v_mul_hi_i32_i24_e32 v53, 0xc000, v52
	v_mul_i32_i24_e32 v52, 0xc000, v52
	s_waitcnt lgkmcnt(0)
	v_lshl_add_u64 v[54:55], s[20:21], 0, v[52:53]
	v_lshl_add_u64 v[52:53], v[54:55], 0, s[8:9]
	v_lshl_add_u64 v[54:55], v[54:55], 0, s[10:11]
	v_lshl_add_u64 v[72:73], v[52:53], 0, v[34:35]
	v_lshl_add_u64 v[76:77], v[54:55], 0, v[34:35]
	global_load_dwordx4 v[68:71], v34, s[18:19]
	s_nop 0
	global_load_dwordx4 v[72:75], v[72:73], off
	s_nop 0
	global_load_dwordx4 v[76:79], v[76:77], off
	global_load_dwordx4 v[100:103], v34, s[18:19] offset:1024
	v_lshl_add_u64 v[98:99], v[54:55], 0, v[38:39]
	global_load_dwordx4 v[104:107], v[98:99], off
	v_lshl_add_u64 v[98:99], v[52:53], 0, v[38:39]
	global_load_dwordx4 v[108:111], v[98:99], off
	global_load_dwordx4 v[112:115], v34, s[18:19] offset:2048
	v_lshl_add_u64 v[98:99], v[54:55], 0, v[40:41]
	global_load_dwordx4 v[116:119], v[98:99], off
	v_lshl_add_u64 v[98:99], v[52:53], 0, v[40:41]
	global_load_dwordx4 v[120:123], v[98:99], off
	global_load_dwordx4 v[124:127], v34, s[18:19] offset:3072
	v_lshl_add_u64 v[98:99], v[54:55], 0, v[42:43]
	global_load_dwordx4 v[128:131], v[98:99], off
	v_lshl_add_u64 v[98:99], v[52:53], 0, v[42:43]
	global_load_dwordx4 v[132:135], v[98:99], off
	global_load_dwordx4 v[136:139], v44, s[18:19]
	v_lshl_add_u64 v[98:99], v[54:55], 0, v[44:45]
	global_load_dwordx4 v[140:143], v[98:99], off
	v_lshl_add_u64 v[98:99], v[52:53], 0, v[44:45]
	global_load_dwordx4 v[144:147], v[98:99], off
	global_load_dwordx4 v[148:151], v46, s[18:19]
	v_lshl_add_u64 v[98:99], v[54:55], 0, v[46:47]
	global_load_dwordx4 v[152:155], v[98:99], off
	v_lshl_add_u64 v[98:99], v[52:53], 0, v[46:47]
	global_load_dwordx4 v[156:159], v[98:99], off
	global_load_dwordx4 v[160:163], v48, s[18:19]
	v_lshl_add_u64 v[98:99], v[54:55], 0, v[48:49]
	global_load_dwordx4 v[164:167], v[98:99], off
	v_lshl_add_u64 v[98:99], v[52:53], 0, v[48:49]
	global_load_dwordx4 v[168:171], v[98:99], off
	global_load_dwordx4 v[172:175], v50, s[18:19]
	v_lshl_add_u64 v[98:99], v[54:55], 0, v[50:51]
	global_load_dwordx4 v[176:179], v[98:99], off
	v_lshl_add_u64 v[98:99], v[52:53], 0, v[50:51]
	global_load_dwordx4 v[180:183], v[98:99], off
	v_cmp_lt_i32_e32 vcc, v61, v59
	v_lshl_add_u64 v[56:57], s[20:21], 0, v[56:57]
	v_lshl_add_u64 v[56:57], v[56:57], 0, v[36:37]
	v_add_u32_e32 v32, s86, v32
	s_waitcnt vmcnt(31)
	v_mul_f32_e32 v96, v29, v29
	s_waitcnt vmcnt(30)
	v_mul_f32_e32 v97, v25, v25
	s_waitcnt vmcnt(29)
	v_mul_f32_e32 v98, v21, v21
	v_fmac_f32_e32 v96, v28, v28
	v_fmac_f32_e32 v97, v24, v24
	s_waitcnt vmcnt(28)
	v_mul_f32_e32 v99, v17, v17
	v_fmac_f32_e32 v98, v20, v20
	s_waitcnt vmcnt(27)
	v_mov_b32_e32 v82, v13
	s_waitcnt vmcnt(26)
	v_mov_b32_e32 v83, v9
	s_waitcnt vmcnt(25)
	v_mov_b32_e32 v90, v5
	s_waitcnt vmcnt(24)
	v_mov_b32_e32 v91, v1
	v_fmac_f32_e32 v96, v30, v30
	v_fmac_f32_e32 v97, v26, v26
	v_fmac_f32_e32 v99, v16, v16
	v_mov_b32_e32 v80, v12
	v_mov_b32_e32 v81, v8
	v_mov_b32_e32 v88, v4
	v_mov_b32_e32 v89, v0
	v_fmac_f32_e32 v98, v22, v22
	v_pk_mul_f32 v[82:83], v[82:83], v[82:83]
	v_pk_mul_f32 v[90:91], v[90:91], v[90:91]
	v_fmac_f32_e32 v96, v31, v31
	v_fmac_f32_e32 v97, v27, v27
	v_mov_b32_e32 v84, v14
	v_mov_b32_e32 v85, v10
	v_fmac_f32_e32 v99, v18, v18
	v_fmac_f32_e32 v98, v23, v23
	v_pk_fma_f32 v[80:81], v[80:81], v[80:81], v[82:83]
	v_pk_fma_f32 v[82:83], v[88:89], v[88:89], v[90:91]
	v_add_f32_e32 v88, v96, v97
	v_mov_b32_e32 v86, v15
	v_mov_b32_e32 v87, v11
	v_fmac_f32_e32 v99, v19, v19
	v_pk_fma_f32 v[80:81], v[84:85], v[84:85], v[80:81]
	v_add_f32_e32 v84, v88, v98
	v_mov_b32_e32 v92, v6
	v_mov_b32_e32 v93, v2
	v_pk_fma_f32 v[80:81], v[86:87], v[86:87], v[80:81]
	v_add_f32_e32 v84, v84, v99
	v_mov_b32_e32 v94, v7
	v_mov_b32_e32 v95, v3
	v_pk_fma_f32 v[82:83], v[92:93], v[92:93], v[82:83]
	v_add_f32_e32 v80, v84, v80
	v_pk_fma_f32 v[82:83], v[94:95], v[94:95], v[82:83]
	v_add_f32_e32 v80, v80, v81
	v_add_f32_e32 v80, v80, v82
	v_add_f32_e32 v80, v80, v83
	ds_bpermute_b32 v67, v67, v80
	v_cndmask_b32_e32 v81, v58, v61, vcc
	v_lshlrev_b32_e32 v81, 2, v81
	v_cmp_lt_i32_e32 vcc, v62, v59
	s_waitcnt vmcnt(21)
	v_add_f32_e32 v76, 1.0, v76
	s_waitcnt lgkmcnt(0)
	v_add_f32_e32 v67, v80, v67
	ds_bpermute_b32 v80, v81, v67
	v_cndmask_b32_e32 v81, v58, v62, vcc
	v_lshlrev_b32_e32 v81, 2, v81
	v_cmp_lt_i32_e32 vcc, v63, v59
	v_add_f32_e32 v77, 1.0, v77
	s_waitcnt lgkmcnt(0)
	v_add_f32_e32 v67, v67, v80
	ds_bpermute_b32 v80, v81, v67
	v_cndmask_b32_e32 v81, v58, v63, vcc
	v_lshlrev_b32_e32 v81, 2, v81
	v_cmp_lt_i32_e32 vcc, v64, v59
	v_add_f32_e32 v78, 1.0, v78
	s_waitcnt lgkmcnt(0)
	v_add_f32_e32 v67, v67, v80
	ds_bpermute_b32 v80, v81, v67
	v_cndmask_b32_e32 v81, v58, v64, vcc
	v_lshlrev_b32_e32 v81, 2, v81
	v_cmp_lt_i32_e32 vcc, v65, v59
	v_add_f32_e32 v79, 1.0, v79
	s_waitcnt lgkmcnt(0)
; __device__ __forceinline__ unsigned cvt_pk_bf16(float lo, float hi) { unsigned r; asm("v_cvt_pk_bf16_f32 %0, %1, %2" : "=v"(r) : "v"(lo), "v"(hi)); return r; }
; __device__ __forceinline__ void xn_row(const float* hrow, const float* g, const float* shift, const float* scale, bf16_t* orow, int lane) {
;     ...
;     const float r = rsqrtf(wave_sum(s) * (1.f / D) + 1e-6f);
;     u32x2* o = (u32x2*)orow + lane;
; #pragma unroll
;     for (int j = 0; j < 8; ++j) { const float4 gg = ((const float4*)g)[lane + 64 * j], sh = ((const float4*)shift)[lane + 64 * j], sc = ((const float4*)scale)[lane + 64 * j];
;         u32x2 w; w.x = cvt_pk_bf16(v[j].x * r * gg.x * (1.f + sc.x) + sh.x, v[j].y * r * gg.y * (1.f + sc.y) + sh.y);
;         w.y = cvt_pk_bf16(v[j].z * r * gg.z * (1.f + sc.z) + sh.z, v[j].w * r * gg.w * (1.f + sc.w) + sh.w);
;         o[64 * j] = w; }
; }
	v_add_f32_e32 v67, v67, v80
	ds_bpermute_b32 v80, v81, v67
	v_cndmask_b32_e32 v81, v58, v65, vcc
	v_lshlrev_b32_e32 v81, 2, v81
	v_lshl_add_u64 v[82:83], v[54:55], 0, v[38:39]
	s_waitcnt lgkmcnt(0)
	v_add_f32_e32 v67, v67, v80
	ds_bpermute_b32 v84, v81, v67
	v_add_co_u32_e32 v80, vcc, s26, v56
	s_waitcnt lgkmcnt(0)
	v_add_f32_e32 v67, v67, v84
	v_addc_co_u32_e32 v81, vcc, 0, v57, vcc
	v_fmamk_f32 v67, v67, 0x3a000000, v66
	v_mul_f32_e32 v84, 0x4b800000, v67
	v_cmp_gt_f32_e32 vcc, s14, v67
	s_nop 1
	v_cndmask_b32_e32 v67, v67, v84, vcc
	v_rsq_f32_e32 v67, v67
	s_nop 0
	v_mul_f32_e32 v84, 0x45800000, v67
	v_cndmask_b32_e32 v67, v67, v84, vcc
	v_mul_f32_e32 v28, v28, v67
	v_mul_f32_e32 v29, v29, v67
	v_mul_f32_e32 v30, v30, v67
	v_mul_f32_e32 v31, v31, v67
	v_mul_f32_e32 v28, v68, v28
	v_mul_f32_e32 v29, v69, v29
	v_mul_f32_e32 v30, v70, v30
	v_mul_f32_e32 v31, v71, v31
	v_fma_f32 v28, v76, v28, v72
	v_fma_f32 v29, v77, v29, v73
	v_fma_f32 v30, v30, v78, v74
	v_fmac_f32_e32 v75, v31, v79
	v_cvt_pk_bf16_f32 v28, v28, v29
	v_cvt_pk_bf16_f32 v29, v30, v75
	global_store_dwordx2 v[80:81], v[28:29], off
	v_mul_f32_e32 v24, v24, v67
	v_mul_f32_e32 v25, v25, v67
	v_lshl_add_u64 v[28:29], v[56:57], 0, s[16:17]
	v_mul_f32_e32 v26, v26, v67
	v_mul_f32_e32 v27, v27, v67
	v_mul_f32_e32 v20, v20, v67
	v_mul_f32_e32 v21, v21, v67
	v_mul_f32_e32 v22, v22, v67
	v_mul_f32_e32 v23, v23, v67
	v_mul_f32_e32 v16, v16, v67
	v_mul_f32_e32 v17, v17, v67
	v_mul_f32_e32 v18, v18, v67
	v_mul_f32_e32 v19, v19, v67
	v_mul_f32_e32 v12, v12, v67
	v_mul_f32_e32 v13, v13, v67
	v_mul_f32_e32 v14, v14, v67
	v_mul_f32_e32 v15, v15, v67
	v_mul_f32_e32 v8, v8, v67
	v_mul_f32_e32 v9, v9, v67
	v_mul_f32_e32 v10, v10, v67
	v_mul_f32_e32 v11, v11, v67
	v_mul_f32_e32 v4, v4, v67
	v_mul_f32_e32 v5, v5, v67
	v_mul_f32_e32 v6, v6, v67
	v_mul_f32_e32 v7, v7, v67
	v_mul_f32_e32 v0, v0, v67
	v_mul_f32_e32 v1, v1, v67
	v_cmp_lt_i32_e32 vcc, s27, v32
	v_mul_f32_e32 v2, v2, v67
	v_mul_f32_e32 v3, v3, v67
	s_or_b64 s[4:5], vcc, s[4:5]
	s_waitcnt vmcnt(18)
	v_mul_f32_e32 v24, v24, v100
	v_mul_f32_e32 v25, v25, v101
	v_mul_f32_e32 v26, v26, v102
	v_mul_f32_e32 v27, v27, v103
	v_add_f32_e32 v104, 1.0, v104
	v_add_f32_e32 v105, 1.0, v105
	v_add_f32_e32 v106, 1.0, v106
	v_add_f32_e32 v107, 1.0, v107
	v_fma_f32 v24, v24, v104, v108
	v_fma_f32 v25, v25, v105, v109
	v_fma_f32 v26, v26, v106, v110
	v_fma_f32 v27, v27, v107, v111
	v_cvt_pk_bf16_f32 v24, v24, v25
	v_cvt_pk_bf16_f32 v25, v26, v27
	global_store_dwordx2 v[28:29], v[24:25], off offset:512
	s_waitcnt vmcnt(15)
	v_mul_f32_e32 v20, v20, v112
	v_mul_f32_e32 v21, v21, v113
	v_mul_f32_e32 v22, v22, v114
	v_mul_f32_e32 v23, v23, v115
	v_add_f32_e32 v116, 1.0, v116
	v_add_f32_e32 v117, 1.0, v117
	v_add_f32_e32 v118, 1.0, v118
	v_add_f32_e32 v119, 1.0, v119
	v_fma_f32 v20, v20, v116, v120
	v_fma_f32 v21, v21, v117, v121
	v_fma_f32 v22, v22, v118, v122
	v_fma_f32 v23, v23, v119, v123
	v_cvt_pk_bf16_f32 v20, v20, v21
	v_cvt_pk_bf16_f32 v21, v22, v23
	global_store_dwordx2 v[28:29], v[20:21], off offset:1024
	s_waitcnt vmcnt(12)
	v_mul_f32_e32 v16, v16, v124
	v_mul_f32_e32 v17, v17, v125
	v_mul_f32_e32 v18, v18, v126
	v_mul_f32_e32 v19, v19, v127
	v_add_f32_e32 v128, 1.0, v128
	v_add_f32_e32 v129, 1.0, v129
	v_add_f32_e32 v130, 1.0, v130
	v_add_f32_e32 v131, 1.0, v131
	v_fma_f32 v16, v16, v128, v132
	v_fma_f32 v17, v17, v129, v133
	v_fma_f32 v18, v18, v130, v134
	v_fma_f32 v19, v19, v131, v135
	v_cvt_pk_bf16_f32 v16, v16, v17
	v_cvt_pk_bf16_f32 v17, v18, v19
	global_store_dwordx2 v[28:29], v[16:17], off offset:1536
	s_waitcnt vmcnt(9)
	v_mul_f32_e32 v12, v12, v136
	v_mul_f32_e32 v13, v13, v137
	v_mul_f32_e32 v14, v14, v138
	v_mul_f32_e32 v15, v15, v139
	v_add_f32_e32 v140, 1.0, v140
	v_add_f32_e32 v141, 1.0, v141
	v_add_f32_e32 v142, 1.0, v142
	v_add_f32_e32 v143, 1.0, v143
	v_fma_f32 v12, v12, v140, v144
	v_fma_f32 v13, v13, v141, v145
	v_fma_f32 v14, v14, v142, v146
	v_fma_f32 v15, v15, v143, v147
	v_cvt_pk_bf16_f32 v12, v12, v13
	v_cvt_pk_bf16_f32 v13, v14, v15
	global_store_dwordx2 v[28:29], v[12:13], off offset:2048
	s_waitcnt vmcnt(6)
	v_mul_f32_e32 v8, v8, v148
	v_mul_f32_e32 v9, v9, v149
	v_mul_f32_e32 v10, v10, v150
	v_mul_f32_e32 v11, v11, v151
	v_add_f32_e32 v152, 1.0, v152
	v_add_f32_e32 v153, 1.0, v153
	v_add_f32_e32 v154, 1.0, v154
	v_add_f32_e32 v155, 1.0, v155
	v_fma_f32 v8, v8, v152, v156
	v_fma_f32 v9, v9, v153, v157
	v_fma_f32 v10, v10, v154, v158
	v_fma_f32 v11, v11, v155, v159
	v_cvt_pk_bf16_f32 v8, v8, v9
	v_cvt_pk_bf16_f32 v9, v10, v11
	global_store_dwordx2 v[28:29], v[8:9], off offset:2560
	s_waitcnt vmcnt(3)
	v_mul_f32_e32 v4, v4, v160
	v_mul_f32_e32 v5, v5, v161
	v_mul_f32_e32 v6, v6, v162
	v_mul_f32_e32 v7, v7, v163
	v_add_f32_e32 v164, 1.0, v164
	v_add_f32_e32 v165, 1.0, v165
	v_add_f32_e32 v166, 1.0, v166
	v_add_f32_e32 v167, 1.0, v167
	v_fma_f32 v4, v4, v164, v168
	v_fma_f32 v5, v5, v165, v169
	v_fma_f32 v6, v6, v166, v170
	v_fma_f32 v7, v7, v167, v171
	v_cvt_pk_bf16_f32 v4, v4, v5
	v_cvt_pk_bf16_f32 v5, v6, v7
	global_store_dwordx2 v[28:29], v[4:5], off offset:3072
	s_waitcnt vmcnt(0)
	v_mul_f32_e32 v0, v0, v172
	v_mul_f32_e32 v1, v1, v173
	v_mul_f32_e32 v2, v2, v174
	v_mul_f32_e32 v3, v3, v175
	v_add_f32_e32 v176, 1.0, v176
	v_add_f32_e32 v177, 1.0, v177
	v_add_f32_e32 v178, 1.0, v178
	v_add_f32_e32 v179, 1.0, v179
	v_fma_f32 v0, v0, v176, v180
	v_fma_f32 v1, v1, v177, v181
	v_fma_f32 v2, v2, v178, v182
	v_fma_f32 v3, v3, v179, v183
	v_cvt_pk_bf16_f32 v0, v0, v1
	v_cvt_pk_bf16_f32 v1, v2, v3
	global_store_dwordx2 v[28:29], v[0:1], off offset:3584
	s_andn2_b64 exec, exec, s[4:5]
	s_cbranch_execz .LBB0_507

; #define PG8_STAGE(bufoff, gbase, voff) do { _Pragma("unroll") for (int _i = 0; _i < 2; ++_i) \
;         __builtin_amdgcn_global_load_lds((const unsigned*)((const char*)(gbase) + (size_t)_i * r64##voff + (voff)), (LAS unsigned*)(lds + (bufoff) + ldsw + _i * 8192), 16, 0, 0); } while (0)
; #define PG8_LDA(dst, b, h) do { _Pragma("unroll") for (int m = 0; m < 4; ++m) _Pragma("unroll") for (int k = 0; k < 2; ++k) dst[m][k] = *(const LAS bf16x8*)(lds + PG8_SA(b, h) + aoff + m * 2048 + k * 1024); } while (0)
; #define PG8_LDB(dst, b, h) do { _Pragma("unroll") for (int n = 0; n < 2; ++n) _Pragma("unroll") for (int k = 0; k < 2; ++k) dst[n][k] = *(const LAS bf16x8*)(lds + PG8_SB(b, h) + boff + n * 2048 + k * 1024); } while (0)
; #define PG8_MMA(ai, bj, At, Bt) do { __builtin_amdgcn_s_setprio(1); _Pragma("unroll") for (int m = 0; m < 4; ++m) _Pragma("unroll") for (int n = 0; n < 2; ++n) _Pragma("unroll") for (int k = 0; k < 2; ++k) \
;         acc[ai][bj][m][n] = __builtin_amdgcn_mfma_f32_16x16x32_bf16(Bt[n][k], At[m][k], acc[ai][bj][m][n], 0, 0, 0); __builtin_amdgcn_s_setprio(0); } while (0)
; #define PG8_WAIT_V(n) asm volatile("s_waitcnt vmcnt(" #n ")" ::: "memory")
; #define PG8_WAIT_L(n) asm volatile("s_waitcnt lgkmcnt(" #n ")" ::: "memory")
; #define PG8_BAR __builtin_amdgcn_s_barrier()
; #define PG8_SCHED __builtin_amdgcn_sched_barrier(0)
; template <class Epi, class Sched>
; __device__ __forceinline__ void gemm_phase(LAS unsigned char* lds, const Gemm g, const Sched& S, const Epi& E) {
;     ...
;             PG8_LDB(B0, 0, 0); PG8_SCHED; PG8_LDA(At, 0, 0); PG8_STAGE(PG8_SA(1, 1), a1 + hstepA, voffA);
;             PG8_WAIT_L(8); PG8_BAR; PG8_WAIT_L(0); PG8_MMA(0, 0, At, B0); PG8_BAR; PG8_SCHED;
;             PG8_LDB(B1, 0, 1); PG8_STAGE(PG8_SB(0, 0), b2, voffB);
;             PG8_BAR; PG8_WAIT_L(0); PG8_MMA(0, 1, At, B1); PG8_BAR;
;             PG8_LDA(At, 0, 1); PG8_STAGE(PG8_SA(0, 0), a2, voffA);
;             PG8_BAR; PG8_WAIT_L(0); PG8_MMA(1, 0, At, B0); PG8_BAR; PG8_SCHED;
;             PG8_STAGE(PG8_SB(0, 1), b2 + hstepB, voffB);
;             PG8_WAIT_V(6); PG8_BAR; PG8_MMA(1, 1, At, B1); PG8_BAR;
.LBB0_615:
	ds_read_b128 v[138:141], v145
	ds_read_b128 v[148:151], v145 offset:1024
	ds_read_b128 v[152:155], v145 offset:2048
	ds_read_b128 v[156:159], v145 offset:3072
	s_add_u32 s68, s54, 0xffd40080
	s_addc_u32 s69, s55, -1
	s_cmpk_eq_i32 s57, 0x54
	s_cselect_b32 s69, s7, s69
	s_cselect_b32 s68, s6, s68
	s_cselect_b32 s71, s9, s56
	s_cselect_b32 s70, s8, s12
	v_lshl_add_u64 v[142:143], s[54:55], 0, v[132:133]
	s_add_i32 m0, s30, 0xc000
	ds_read_b128 v[160:163], v146
	ds_read_b128 v[164:167], v146 offset:1024
	ds_read_b128 v[168:171], v146 offset:2048
	ds_read_b128 v[172:175], v146 offset:3072
	ds_read_b128 v[176:179], v146 offset:4096
	ds_read_b128 v[180:183], v146 offset:5120
	ds_read_b128 v[184:187], v146 offset:6144
	ds_read_b128 v[188:191], v146 offset:7168
	global_load_lds_dwordx4 v[142:143], off
	v_lshl_add_u64 v[142:143], v[142:143], 0, s[16:17]
	s_add_i32 m0, s30, 0xe000
	s_nop 0
	global_load_lds_dwordx4 v[142:143], off
	s_waitcnt lgkmcnt(8)
	s_barrier
	s_waitcnt lgkmcnt(0)
	s_setprio 1
	s_waitcnt lgkmcnt(0)
	v_mfma_f32_16x16x32_bf16 v[124:127], v[138:141], v[160:163], v[124:127]
	v_mfma_f32_16x16x32_bf16 v[120:123], v[152:155], v[160:163], v[120:123]
	v_mfma_f32_16x16x32_bf16 v[112:115], v[138:141], v[168:171], v[112:115]
	v_mfma_f32_16x16x32_bf16 v[104:107], v[152:155], v[168:171], v[104:107]
	v_mfma_f32_16x16x32_bf16 v[96:99], v[138:141], v[176:179], v[96:99]
	v_mfma_f32_16x16x32_bf16 v[88:91], v[152:155], v[176:179], v[88:91]
	v_mfma_f32_16x16x32_bf16 v[80:83], v[138:141], v[184:187], v[80:83]
	v_mfma_f32_16x16x32_bf16 v[72:75], v[152:155], v[184:187], v[72:75]
	v_mfma_f32_16x16x32_bf16 v[124:127], v[148:151], v[164:167], v[124:127]
	v_mfma_f32_16x16x32_bf16 v[120:123], v[156:159], v[164:167], v[120:123]
	v_mfma_f32_16x16x32_bf16 v[112:115], v[148:151], v[172:175], v[112:115]
	v_mfma_f32_16x16x32_bf16 v[104:107], v[156:159], v[172:175], v[104:107]
	v_mfma_f32_16x16x32_bf16 v[96:99], v[148:151], v[180:183], v[96:99]
	v_mfma_f32_16x16x32_bf16 v[88:91], v[156:159], v[180:183], v[88:91]
	v_mfma_f32_16x16x32_bf16 v[80:83], v[148:151], v[188:191], v[80:83]
	v_mfma_f32_16x16x32_bf16 v[72:75], v[156:159], v[188:191], v[72:75]
	s_setprio 0
	s_barrier
	v_lshl_add_u64 v[142:143], s[70:71], 0, v[128:129]
	s_add_i32 s70, s62, s29
	s_mov_b32 m0, s70
	ds_read_b128 v[192:195], v147
	ds_read_b128 v[196:199], v147 offset:1024
	ds_read_b128 v[200:203], v147 offset:2048
	ds_read_b128 v[204:207], v147 offset:3072
	global_load_lds_dwordx4 v[142:143], off
	v_lshl_add_u64 v[208:209], v[142:143], 0, s[10:11]
	s_add_i32 m0, s70, 0x2000
	s_nop 0
	global_load_lds_dwordx4 v[208:209], off
	s_barrier
	s_waitcnt lgkmcnt(0)
	s_setprio 1
	s_waitcnt lgkmcnt(0)
	v_mfma_f32_16x16x32_bf16 v[116:119], v[192:195], v[160:163], v[116:119]
	v_mfma_f32_16x16x32_bf16 v[108:111], v[200:203], v[160:163], v[108:111]
	v_mfma_f32_16x16x32_bf16 v[100:103], v[192:195], v[168:171], v[100:103]
	v_mfma_f32_16x16x32_bf16 v[92:95], v[200:203], v[168:171], v[92:95]
	v_mfma_f32_16x16x32_bf16 v[84:87], v[192:195], v[176:179], v[84:87]
	v_mfma_f32_16x16x32_bf16 v[76:79], v[200:203], v[176:179], v[76:79]
	v_mfma_f32_16x16x32_bf16 v[68:71], v[192:195], v[184:187], v[68:71]
	v_mfma_f32_16x16x32_bf16 v[64:67], v[200:203], v[184:187], v[64:67]
	v_mfma_f32_16x16x32_bf16 v[116:119], v[196:199], v[164:167], v[116:119]
	v_mfma_f32_16x16x32_bf16 v[108:111], v[204:207], v[164:167], v[108:111]
	v_mfma_f32_16x16x32_bf16 v[100:103], v[196:199], v[172:175], v[100:103]
	v_mfma_f32_16x16x32_bf16 v[92:95], v[204:207], v[172:175], v[92:95]
	v_mfma_f32_16x16x32_bf16 v[84:87], v[196:199], v[180:183], v[84:87]
	v_mfma_f32_16x16x32_bf16 v[76:79], v[204:207], v[180:183], v[76:79]
	v_mfma_f32_16x16x32_bf16 v[68:71], v[196:199], v[188:191], v[68:71]
	v_mfma_f32_16x16x32_bf16 v[64:67], v[204:207], v[188:191], v[64:67]
	s_setprio 0
	s_mov_b32 m0, s30
	v_lshl_add_u64 v[208:209], s[68:69], 0, v[130:131]
	s_barrier
	ds_read_b128 v[160:163], v146 offset:16384
	ds_read_b128 v[164:167], v146 offset:17408
	ds_read_b128 v[168:171], v146 offset:18432
	ds_read_b128 v[172:175], v146 offset:19456
	ds_read_b128 v[176:179], v146 offset:20480
	ds_read_b128 v[180:183], v146 offset:21504
	ds_read_b128 v[184:187], v146 offset:22528
	ds_read_b128 v[188:191], v146 offset:23552
	global_load_lds_dwordx4 v[208:209], off
	v_lshl_add_u64 v[210:211], v[208:209], 0, s[16:17]
	s_mov_b32 m0, s31
	s_nop 0
	global_load_lds_dwordx4 v[210:211], off
	s_barrier
	s_waitcnt lgkmcnt(0)
	s_setprio 1
	s_waitcnt lgkmcnt(0)
	v_mfma_f32_16x16x32_bf16 v[60:63], v[138:141], v[160:163], v[60:63]
	v_mfma_f32_16x16x32_bf16 v[56:59], v[152:155], v[160:163], v[56:59]
	v_mfma_f32_16x16x32_bf16 v[48:51], v[138:141], v[168:171], v[48:51]
	v_mfma_f32_16x16x32_bf16 v[40:43], v[152:155], v[168:171], v[40:43]
	v_mfma_f32_16x16x32_bf16 v[32:35], v[138:141], v[176:179], v[32:35]
	v_mfma_f32_16x16x32_bf16 v[24:27], v[152:155], v[176:179], v[24:27]
	v_mfma_f32_16x16x32_bf16 v[16:19], v[138:141], v[184:187], v[16:19]
	v_mfma_f32_16x16x32_bf16 v[8:11], v[152:155], v[184:187], v[8:11]
	v_mfma_f32_16x16x32_bf16 v[60:63], v[148:151], v[164:167], v[60:63]
	v_mfma_f32_16x16x32_bf16 v[56:59], v[156:159], v[164:167], v[56:59]
	v_mfma_f32_16x16x32_bf16 v[48:51], v[148:151], v[172:175], v[48:51]
	v_mfma_f32_16x16x32_bf16 v[40:43], v[156:159], v[172:175], v[40:43]
	v_mfma_f32_16x16x32_bf16 v[32:35], v[148:151], v[180:183], v[32:35]
	v_mfma_f32_16x16x32_bf16 v[24:27], v[156:159], v[180:183], v[24:27]
	v_mfma_f32_16x16x32_bf16 v[16:19], v[148:151], v[188:191], v[16:19]
	v_mfma_f32_16x16x32_bf16 v[8:11], v[156:159], v[188:191], v[8:11]
	s_setprio 0
	s_barrier
; #define PG8_STAGE(bufoff, gbase, voff) do { _Pragma("unroll") for (int _i = 0; _i < 2; ++_i) \
;         __builtin_amdgcn_global_load_lds((const unsigned*)((const char*)(gbase) + (size_t)_i * r64##voff + (voff)), (LAS unsigned*)(lds + (bufoff) + ldsw + _i * 8192), 16, 0, 0); } while (0)
; #define PG8_LDA(dst, b, h) do { _Pragma("unroll") for (int m = 0; m < 4; ++m) _Pragma("unroll") for (int k = 0; k < 2; ++k) dst[m][k] = *(const LAS bf16x8*)(lds + PG8_SA(b, h) + aoff + m * 2048 + k * 1024); } while (0)
; #define PG8_LDB(dst, b, h) do { _Pragma("unroll") for (int n = 0; n < 2; ++n) _Pragma("unroll") for (int k = 0; k < 2; ++k) dst[n][k] = *(const LAS bf16x8*)(lds + PG8_SB(b, h) + boff + n * 2048 + k * 1024); } while (0)
; #define PG8_MMA(ai, bj, At, Bt) do { __builtin_amdgcn_s_setprio(1); _Pragma("unroll") for (int m = 0; m < 4; ++m) _Pragma("unroll") for (int n = 0; n < 2; ++n) _Pragma("unroll") for (int k = 0; k < 2; ++k) \
;         acc[ai][bj][m][n] = __builtin_amdgcn_mfma_f32_16x16x32_bf16(Bt[n][k], At[m][k], acc[ai][bj][m][n], 0, 0, 0); __builtin_amdgcn_s_setprio(0); } while (0)
; #define PG8_WAIT_V(n) asm volatile("s_waitcnt vmcnt(" #n ")" ::: "memory")
; #define PG8_WAIT_L(n) asm volatile("s_waitcnt lgkmcnt(" #n ")" ::: "memory")
; #define PG8_BAR __builtin_amdgcn_s_barrier()
; #define PG8_SCHED __builtin_amdgcn_sched_barrier(0)
; template <class Epi, class Sched>
; __device__ __forceinline__ void gemm_phase(LAS unsigned char* lds, const Gemm g, const Sched& S, const Epi& E) {
;     ...
;             PG8_STAGE(PG8_SB(0, 1), b2 + hstepB, voffB);
;             PG8_WAIT_V(6); PG8_BAR; PG8_MMA(1, 1, At, B1); PG8_BAR;
;             PG8_LDB(B0, 1, 0); PG8_SCHED; PG8_LDA(At, 1, 0); PG8_STAGE(PG8_SA(0, 1), a2 + hstepA, voffA);
;             PG8_WAIT_L(8); PG8_BAR; PG8_WAIT_L(0); PG8_MMA(0, 0, At, B0); PG8_BAR; PG8_SCHED;
;             PG8_LDB(B1, 1, 1); PG8_STAGE(PG8_SB(1, 0), b3, voffB);
;             PG8_BAR; PG8_WAIT_L(0); PG8_MMA(0, 1, At, B1); PG8_BAR;
;             PG8_LDA(At, 1, 1); PG8_STAGE(PG8_SA(1, 0), a3, voffA);
;             PG8_BAR; PG8_WAIT_L(0); PG8_MMA(1, 0, At, B0); PG8_BAR; PG8_SCHED;
	s_add_i32 s68, s63, s29
	v_lshl_add_u64 v[138:139], v[142:143], 0, s[16:17]
	s_mov_b32 m0, s68
	s_nop 0
	global_load_lds_dwordx4 v[138:139], off
	v_lshl_add_u64 v[138:139], v[142:143], 0, s[18:19]
	s_add_i32 m0, s68, 0x2000
	s_nop 0
	global_load_lds_dwordx4 v[138:139], off
	s_waitcnt vmcnt(6)
	s_barrier
	s_setprio 1
	v_mfma_f32_16x16x32_bf16 v[52:55], v[192:195], v[160:163], v[52:55]
	v_mfma_f32_16x16x32_bf16 v[44:47], v[200:203], v[160:163], v[44:47]
	v_mfma_f32_16x16x32_bf16 v[36:39], v[192:195], v[168:171], v[36:39]
	v_mfma_f32_16x16x32_bf16 v[28:31], v[200:203], v[168:171], v[28:31]
	v_mfma_f32_16x16x32_bf16 v[20:23], v[192:195], v[176:179], v[20:23]
	v_mfma_f32_16x16x32_bf16 v[12:15], v[200:203], v[176:179], v[12:15]
	v_mfma_f32_16x16x32_bf16 v[4:7], v[192:195], v[184:187], v[4:7]
	v_mfma_f32_16x16x32_bf16 v[0:3], v[200:203], v[184:187], v[0:3]
	v_mfma_f32_16x16x32_bf16 v[52:55], v[196:199], v[164:167], v[52:55]
	v_mfma_f32_16x16x32_bf16 v[44:47], v[204:207], v[164:167], v[44:47]
	v_mfma_f32_16x16x32_bf16 v[36:39], v[196:199], v[172:175], v[36:39]
	v_mfma_f32_16x16x32_bf16 v[28:31], v[204:207], v[172:175], v[28:31]
	v_mfma_f32_16x16x32_bf16 v[20:23], v[196:199], v[180:183], v[20:23]
	v_mfma_f32_16x16x32_bf16 v[12:15], v[204:207], v[180:183], v[12:15]
	v_mfma_f32_16x16x32_bf16 v[4:7], v[196:199], v[188:191], v[4:7]
	v_mfma_f32_16x16x32_bf16 v[0:3], v[204:207], v[188:191], v[0:3]
	s_setprio 0
	s_add_i32 s68, 0, 0x18000
	v_add_u32_e32 v156, s68, v144
	s_barrier
	ds_read_b128 v[138:141], v156
	ds_read_b128 v[148:151], v156 offset:1024
	ds_read_b128 v[152:155], v156 offset:2048
	ds_read_b128 v[156:159], v156 offset:3072
	s_mov_b32 m0, s33
	v_lshl_add_u64 v[192:193], v[208:209], 0, s[20:21]
	ds_read_b128 v[160:163], v146 offset:32768
	ds_read_b128 v[164:167], v146 offset:33792
	ds_read_b128 v[168:171], v146 offset:34816
	ds_read_b128 v[172:175], v146 offset:35840
	ds_read_b128 v[176:179], v146 offset:36864
	ds_read_b128 v[180:183], v146 offset:37888
	ds_read_b128 v[184:187], v146 offset:38912
	ds_read_b128 v[188:191], v146 offset:39936
	global_load_lds_dwordx4 v[192:193], off
	v_lshl_add_u64 v[192:193], v[208:209], 0, s[22:23]
	s_mov_b32 m0, s34
	s_nop 0
	global_load_lds_dwordx4 v[192:193], off
	s_waitcnt lgkmcnt(8)
	s_barrier
	s_waitcnt lgkmcnt(0)
	s_setprio 1
	s_waitcnt lgkmcnt(0)
	v_mfma_f32_16x16x32_bf16 v[124:127], v[138:141], v[160:163], v[124:127]
	v_mfma_f32_16x16x32_bf16 v[120:123], v[152:155], v[160:163], v[120:123]
	v_mfma_f32_16x16x32_bf16 v[112:115], v[138:141], v[168:171], v[112:115]
	v_mfma_f32_16x16x32_bf16 v[104:107], v[152:155], v[168:171], v[104:107]
	v_mfma_f32_16x16x32_bf16 v[96:99], v[138:141], v[176:179], v[96:99]
	v_mfma_f32_16x16x32_bf16 v[88:91], v[152:155], v[176:179], v[88:91]
	v_mfma_f32_16x16x32_bf16 v[80:83], v[138:141], v[184:187], v[80:83]
	v_mfma_f32_16x16x32_bf16 v[72:75], v[152:155], v[184:187], v[72:75]
	v_mfma_f32_16x16x32_bf16 v[124:127], v[148:151], v[164:167], v[124:127]
	v_mfma_f32_16x16x32_bf16 v[120:123], v[156:159], v[164:167], v[120:123]
	v_mfma_f32_16x16x32_bf16 v[112:115], v[148:151], v[172:175], v[112:115]
	v_mfma_f32_16x16x32_bf16 v[104:107], v[156:159], v[172:175], v[104:107]
	v_mfma_f32_16x16x32_bf16 v[96:99], v[148:151], v[180:183], v[96:99]
	v_mfma_f32_16x16x32_bf16 v[88:91], v[156:159], v[180:183], v[88:91]
	v_mfma_f32_16x16x32_bf16 v[80:83], v[148:151], v[188:191], v[80:83]
	v_mfma_f32_16x16x32_bf16 v[72:75], v[156:159], v[188:191], v[72:75]
	s_setprio 0
	s_barrier
	s_add_i32 s69, 0, 0x1c000
	s_add_i32 s68, s68, s29
	v_add_u32_e32 v204, s69, v144
	v_lshl_add_u64 v[210:211], v[142:143], 0, s[38:39]
	s_mov_b32 m0, s68
	ds_read_b128 v[192:195], v204
	ds_read_b128 v[196:199], v204 offset:1024
	ds_read_b128 v[200:203], v204 offset:2048
	ds_read_b128 v[204:207], v204 offset:3072
	global_load_lds_dwordx4 v[210:211], off
	v_lshl_add_u64 v[210:211], v[142:143], 0, s[42:43]
	s_add_i32 m0, s68, 0x2000
	s_nop 0
	global_load_lds_dwordx4 v[210:211], off
	s_barrier
	s_waitcnt lgkmcnt(0)
	s_setprio 1
	s_waitcnt lgkmcnt(0)
	v_mfma_f32_16x16x32_bf16 v[116:119], v[192:195], v[160:163], v[116:119]
	v_mfma_f32_16x16x32_bf16 v[108:111], v[200:203], v[160:163], v[108:111]
	v_mfma_f32_16x16x32_bf16 v[100:103], v[192:195], v[168:171], v[100:103]
	v_mfma_f32_16x16x32_bf16 v[92:95], v[200:203], v[168:171], v[92:95]
	v_mfma_f32_16x16x32_bf16 v[84:87], v[192:195], v[176:179], v[84:87]
	v_mfma_f32_16x16x32_bf16 v[76:79], v[200:203], v[176:179], v[76:79]
	v_mfma_f32_16x16x32_bf16 v[68:71], v[192:195], v[184:187], v[68:71]
	v_mfma_f32_16x16x32_bf16 v[64:67], v[200:203], v[184:187], v[64:67]
	v_mfma_f32_16x16x32_bf16 v[116:119], v[196:199], v[164:167], v[116:119]
	v_mfma_f32_16x16x32_bf16 v[108:111], v[204:207], v[164:167], v[108:111]
	v_mfma_f32_16x16x32_bf16 v[100:103], v[196:199], v[172:175], v[100:103]
	v_mfma_f32_16x16x32_bf16 v[92:95], v[204:207], v[172:175], v[92:95]
	v_mfma_f32_16x16x32_bf16 v[84:87], v[196:199], v[180:183], v[84:87]
	v_mfma_f32_16x16x32_bf16 v[76:79], v[204:207], v[180:183], v[76:79]
	v_mfma_f32_16x16x32_bf16 v[68:71], v[196:199], v[188:191], v[68:71]
	v_mfma_f32_16x16x32_bf16 v[64:67], v[204:207], v[188:191], v[64:67]
	s_setprio 0
	s_mov_b32 m0, s40
	v_lshl_add_u64 v[210:211], v[208:209], 0, s[38:39]
	s_barrier
	ds_read_b128 v[160:163], v146 offset:49152
	ds_read_b128 v[164:167], v146 offset:50176
	ds_read_b128 v[168:171], v146 offset:51200
	ds_read_b128 v[172:175], v146 offset:52224
	ds_read_b128 v[176:179], v146 offset:53248
	ds_read_b128 v[180:183], v146 offset:54272
	ds_read_b128 v[184:187], v146 offset:55296
	ds_read_b128 v[188:191], v146 offset:56320
	global_load_lds_dwordx4 v[210:211], off
	v_lshl_add_u64 v[208:209], v[208:209], 0, s[44:45]
	s_mov_b32 m0, s41
	s_nop 0
	global_load_lds_dwordx4 v[208:209], off
	s_barrier
; __device__ __forceinline__ int otid() { int t = (int)__builtin_amdgcn_workitem_id_x(); asm volatile("" : "+v"(t)); return t; }
; #define PG8_STAGE(bufoff, gbase, voff) do { _Pragma("unroll") for (int _i = 0; _i < 2; ++_i) \
;         __builtin_amdgcn_global_load_lds((const unsigned*)((const char*)(gbase) + (size_t)_i * r64##voff + (voff)), (LAS unsigned*)(lds + (bufoff) + ldsw + _i * 8192), 16, 0, 0); } while (0)
; #define PG8_WAIT_V(n) asm volatile("s_waitcnt vmcnt(" #n ")" ::: "memory")
; #define PG8_WAIT_L(n) asm volatile("s_waitcnt lgkmcnt(" #n ")" ::: "memory")
; #define PG8_BAR __builtin_amdgcn_s_barrier()
; #define PG8_SCHED __builtin_amdgcn_sched_barrier(0)
; template <class Epi, class Sched>
; __device__ __forceinline__ void gemm_phase(LAS unsigned char* lds, const Gemm g, const Sched& S, const Epi& E) {
;     ...
;             PG8_BAR; PG8_WAIT_L(0); PG8_MMA(1, 0, At, B0); PG8_BAR; PG8_SCHED;
;             PG8_STAGE(PG8_SB(1, 1), b3 + hstepB, voffB);
;             PG8_WAIT_V(6); PG8_BAR; PG8_MMA(1, 1, At, B1); PG8_BAR;
;     __device__ __forceinline__ void operator()(const f32x4 (&acc)[2][2][4][2], const pg8::Unit& u, int wr_, int wc_, int fr_, int fq_) const {
;         const int t2_ = otid(), wr = t2_ >> 8, wc = (t2_ >> 6) & 3, fr = t2_ & 15, fq = (t2_ >> 4) & 3; (void)wr_; (void)wc_; (void)fr_; (void)fq_;
;         const int rbase = u.pm * 256;
;         const bool isc = rbase >= RL;
;         const int mr = isc ? 4 : (rbase >> 12);
;         const float* gate = modsel + (size_t)mr * 12288;
;         const float* src = isc ? srcC - (size_t)RL * 2048 : srcL;
;         float* dst = isc ? dstC - (size_t)RL * 2048 : dstL;
;         const int row0 = rbase + wr * 64 + fr, col0 = u.pn * 256 + wc * 32 + 4 * fq;
; #pragma unroll
;         for (int ai = 0; ai < 2; ++ai)
; #pragma unroll
;             for (int m = 0; m < 4; ++m) { const size_t ro = (size_t)(row0 + ai * 128 + m * 16) * 2048;
; #pragma unroll
;                 for (int bj = 0; bj < 2; ++bj)
; #pragma unroll
;                     for (int n = 0; n < 2; ++n) { const int col = col0 + bj * 128 + n * 16;
;                         const f32x4 gg = *(const f32x4*)(gate + col), s = *(const f32x4*)(src + ro + col);
;                         *(f32x4*)(dst + ro + col) = s + gg * acc[ai][bj][m][n]; } }
	s_waitcnt lgkmcnt(0)
	s_setprio 1
	s_waitcnt lgkmcnt(0)
	v_mfma_f32_16x16x32_bf16 v[60:63], v[138:141], v[160:163], v[60:63]
	v_mfma_f32_16x16x32_bf16 v[56:59], v[152:155], v[160:163], v[56:59]
	v_mfma_f32_16x16x32_bf16 v[48:51], v[138:141], v[168:171], v[48:51]
	v_mfma_f32_16x16x32_bf16 v[40:43], v[152:155], v[168:171], v[40:43]
	v_mfma_f32_16x16x32_bf16 v[32:35], v[138:141], v[176:179], v[32:35]
	v_mfma_f32_16x16x32_bf16 v[24:27], v[152:155], v[176:179], v[24:27]
	v_mfma_f32_16x16x32_bf16 v[16:19], v[138:141], v[184:187], v[16:19]
	v_mfma_f32_16x16x32_bf16 v[8:11], v[152:155], v[184:187], v[8:11]
	v_mfma_f32_16x16x32_bf16 v[60:63], v[148:151], v[164:167], v[60:63]
	v_mfma_f32_16x16x32_bf16 v[56:59], v[156:159], v[164:167], v[56:59]
	v_mfma_f32_16x16x32_bf16 v[48:51], v[148:151], v[172:175], v[48:51]
	v_mfma_f32_16x16x32_bf16 v[40:43], v[156:159], v[172:175], v[40:43]
	v_mfma_f32_16x16x32_bf16 v[32:35], v[148:151], v[180:183], v[32:35]
	v_mfma_f32_16x16x32_bf16 v[24:27], v[156:159], v[180:183], v[24:27]
	v_mfma_f32_16x16x32_bf16 v[16:19], v[148:151], v[188:191], v[16:19]
	v_mfma_f32_16x16x32_bf16 v[8:11], v[156:159], v[188:191], v[8:11]
	s_setprio 0
	s_barrier
	s_add_i32 s68, s69, s29
	v_lshl_add_u64 v[138:139], v[142:143], 0, s[44:45]
	s_mov_b32 m0, s68
	s_nop 0
	global_load_lds_dwordx4 v[138:139], off
	v_lshl_add_u64 v[138:139], v[142:143], 0, s[46:47]
	s_add_i32 m0, s68, 0x2000
	s_nop 0
	global_load_lds_dwordx4 v[138:139], off
	s_waitcnt vmcnt(6)
	s_barrier
	s_setprio 1
	v_mfma_f32_16x16x32_bf16 v[52:55], v[192:195], v[160:163], v[52:55]
	v_mfma_f32_16x16x32_bf16 v[44:47], v[200:203], v[160:163], v[44:47]
	v_mfma_f32_16x16x32_bf16 v[36:39], v[192:195], v[168:171], v[36:39]
	v_mfma_f32_16x16x32_bf16 v[28:31], v[200:203], v[168:171], v[28:31]
	v_mfma_f32_16x16x32_bf16 v[20:23], v[192:195], v[176:179], v[20:23]
	v_mfma_f32_16x16x32_bf16 v[12:15], v[200:203], v[176:179], v[12:15]
	v_mfma_f32_16x16x32_bf16 v[4:7], v[192:195], v[184:187], v[4:7]
	v_mfma_f32_16x16x32_bf16 v[0:3], v[200:203], v[184:187], v[0:3]
	v_mfma_f32_16x16x32_bf16 v[52:55], v[196:199], v[164:167], v[52:55]
	v_mfma_f32_16x16x32_bf16 v[44:47], v[204:207], v[164:167], v[44:47]
	v_mfma_f32_16x16x32_bf16 v[36:39], v[196:199], v[172:175], v[36:39]
	v_mfma_f32_16x16x32_bf16 v[28:31], v[204:207], v[172:175], v[28:31]
	v_mfma_f32_16x16x32_bf16 v[20:23], v[196:199], v[180:183], v[20:23]
	v_mfma_f32_16x16x32_bf16 v[12:15], v[204:207], v[180:183], v[12:15]
	v_mfma_f32_16x16x32_bf16 v[4:7], v[196:199], v[188:191], v[4:7]
	v_mfma_f32_16x16x32_bf16 v[0:3], v[204:207], v[188:191], v[0:3]
	s_setprio 0
	s_add_i32 s57, s57, 2
	s_add_u32 s54, s54, 0x100
	s_addc_u32 s55, s55, 0
	s_add_u32 s12, s12, 0x100
	s_addc_u32 s56, s56, 0
	s_cmpk_gt_u32 s57, 0x55
	s_barrier
	s_cbranch_scc0 .LBB0_615
	s_min_i32 s54, s66, 64
	s_ashr_i32 s54, s54, 4
	s_lshl_b32 s12, s66, 8
	s_mul_hi_i32 s55, s54, 0xc000
	s_mul_i32 s54, s54, 0xc000
	v_mov_b32_e32 v139, v222
	s_add_u32 s68, s36, s54
	s_addc_u32 s69, s37, s55
	v_ashrrev_i32_e32 v138, 2, v139
	s_cmp_gt_i32 s66, 63
	v_and_b32_e32 v140, 0xffffffc0, v138
	v_lshrrev_b32_e32 v138, 1, v139
	v_lshrrev_b32_e32 v141, 2, v139
	v_and_or_b32 v139, v139, 15, s12
	s_cselect_b32 s57, s59, s25
	s_cselect_b32 s56, s58, s24
	s_cselect_b32 s55, s61, s27
	s_cselect_b32 s54, s60, s26
	s_lshl_b32 s66, s67, 8
	v_and_b32_e32 v138, 0x60, v138
	v_and_b32_e32 v141, 12, v141
	v_add_u32_e32 v156, v139, v140
	v_or3_b32 v138, v138, s66, v141
	v_ashrrev_i32_e32 v157, 31, v156
	v_ashrrev_i32_e32 v139, 31, v138
	v_lshlrev_b64 v[142:143], 13, v[156:157]
	v_lshlrev_b64 v[140:141], 2, v[138:139]
	v_lshl_add_u64 v[152:153], s[56:57], 0, v[142:143]
	v_lshl_add_u64 v[138:139], s[68:69], 0, v[140:141]
	v_lshl_add_u64 v[158:159], v[152:153], 0, v[140:141]
	v_lshl_add_u64 v[160:161], s[54:55], 0, v[142:143]
	v_lshl_add_u64 v[160:161], v[160:161], 0, v[140:141]
	s_mov_b32 s66, s65
	s_and_b64 vcc, exec, s[4:5]
	s_mov_b32 s67, s64
	s_mov_b64 s[56:57], s[8:9]
	s_mov_b64 s[54:55], s[6:7]
	s_mov_b32 s98, 0x20000
	s_mov_b32 s99, 0
	s_mov_b32 s100, 0xa0000
	s_mov_b32 s101, 0
	global_load_dwordx4 v[148:151], v[138:139], off
	global_load_dwordx4 v[162:165], v[138:139], off offset:64
	global_load_dwordx4 v[166:169], v[138:139], off offset:512
	global_load_dwordx4 v[170:173], v[138:139], off offset:576
	global_load_dwordx4 v[174:177], v[158:159], off
	global_load_dwordx4 v[178:181], v[158:159], off offset:64
	global_load_dwordx4 v[182:185], v[158:159], off offset:512
	global_load_dwordx4 v[186:189], v[158:159], off offset:576
	v_lshl_add_u64 v[158:159], v[158:159], 0, s[98:99]
	global_load_dwordx4 v[190:193], v[158:159], off
	global_load_dwordx4 v[194:197], v[158:159], off offset:64
	global_load_dwordx4 v[198:201], v[158:159], off offset:512
	global_load_dwordx4 v[202:205], v[158:159], off offset:576
	v_lshl_add_u64 v[158:159], v[158:159], 0, s[98:99]
	global_load_dwordx4 v[206:209], v[158:159], off
	global_load_dwordx4 v[210:213], v[158:159], off offset:64
	global_load_dwordx4 v[214:217], v[158:159], off offset:512
	global_load_dwordx4 v[218:221], v[158:159], off offset:576
	v_lshl_add_u64 v[158:159], v[158:159], 0, s[98:99]
	global_load_dwordx4 v[224:227], v[158:159], off
	global_load_dwordx4 v[228:231], v[158:159], off offset:64
	global_load_dwordx4 v[232:235], v[158:159], off offset:512
	global_load_dwordx4 v[236:239], v[158:159], off offset:576
	v_lshl_add_u64 v[158:159], v[158:159], 0, s[100:101]
	s_waitcnt vmcnt(0)
;     __device__ __forceinline__ void operator()(const f32x4 (&acc)[2][2][4][2], const pg8::Unit& u, int wr_, int wc_, int fr_, int fq_) const {
;     ...
;         const int rbase = u.pm * 256;
;         const bool isc = rbase >= RL;
;         const int mr = isc ? 4 : (rbase >> 12);
;         const float* gate = modsel + (size_t)mr * 12288;
;         const float* src = isc ? srcC - (size_t)RL * 2048 : srcL;
;         float* dst = isc ? dstC - (size_t)RL * 2048 : dstL;
;         const int row0 = rbase + wr * 64 + fr, col0 = u.pn * 256 + wc * 32 + 4 * fq;
; #pragma unroll
;         for (int ai = 0; ai < 2; ++ai)
; #pragma unroll
;             for (int m = 0; m < 4; ++m) { const size_t ro = (size_t)(row0 + ai * 128 + m * 16) * 2048;
; #pragma unroll
;                 for (int bj = 0; bj < 2; ++bj)
; #pragma unroll
;                     for (int n = 0; n < 2; ++n) { const int col = col0 + bj * 128 + n * 16;
;                         const f32x4 gg = *(const f32x4*)(gate + col), s = *(const f32x4*)(src + ro + col);
;                         *(f32x4*)(dst + ro + col) = s + gg * acc[ai][bj][m][n]; } }
	v_pk_fma_f32 v[124:125], v[124:125], v[148:149], v[174:175]
	v_pk_fma_f32 v[126:127], v[126:127], v[150:151], v[176:177]
	v_pk_fma_f32 v[120:121], v[120:121], v[162:163], v[178:179]
	v_pk_fma_f32 v[122:123], v[122:123], v[164:165], v[180:181]
	v_pk_fma_f32 v[116:117], v[116:117], v[166:167], v[182:183]
	v_pk_fma_f32 v[118:119], v[118:119], v[168:169], v[184:185]
	v_pk_fma_f32 v[108:109], v[108:109], v[170:171], v[186:187]
	v_pk_fma_f32 v[110:111], v[110:111], v[172:173], v[188:189]
	v_pk_fma_f32 v[112:113], v[112:113], v[148:149], v[190:191]
	v_pk_fma_f32 v[114:115], v[114:115], v[150:151], v[192:193]
	v_pk_fma_f32 v[104:105], v[104:105], v[162:163], v[194:195]
	v_pk_fma_f32 v[106:107], v[106:107], v[164:165], v[196:197]
	v_pk_fma_f32 v[100:101], v[100:101], v[166:167], v[198:199]
	v_pk_fma_f32 v[102:103], v[102:103], v[168:169], v[200:201]
	v_pk_fma_f32 v[92:93], v[92:93], v[170:171], v[202:203]
	v_pk_fma_f32 v[94:95], v[94:95], v[172:173], v[204:205]
	v_pk_fma_f32 v[96:97], v[96:97], v[148:149], v[206:207]
	v_pk_fma_f32 v[98:99], v[98:99], v[150:151], v[208:209]
	v_pk_fma_f32 v[88:89], v[88:89], v[162:163], v[210:211]
	v_pk_fma_f32 v[90:91], v[90:91], v[164:165], v[212:213]
	v_pk_fma_f32 v[84:85], v[84:85], v[166:167], v[214:215]
	v_pk_fma_f32 v[86:87], v[86:87], v[168:169], v[216:217]
	v_pk_fma_f32 v[76:77], v[76:77], v[170:171], v[218:219]
	v_pk_fma_f32 v[78:79], v[78:79], v[172:173], v[220:221]
	v_pk_fma_f32 v[80:81], v[80:81], v[148:149], v[224:225]
	v_pk_fma_f32 v[82:83], v[82:83], v[150:151], v[226:227]
	v_pk_fma_f32 v[72:73], v[72:73], v[162:163], v[228:229]
	v_pk_fma_f32 v[74:75], v[74:75], v[164:165], v[230:231]
	v_pk_fma_f32 v[68:69], v[68:69], v[166:167], v[232:233]
	v_pk_fma_f32 v[70:71], v[70:71], v[168:169], v[234:235]
	v_pk_fma_f32 v[64:65], v[64:65], v[170:171], v[236:237]
	v_pk_fma_f32 v[66:67], v[66:67], v[172:173], v[238:239]
	global_load_dwordx4 v[174:177], v[158:159], off
	global_load_dwordx4 v[178:181], v[158:159], off offset:64
	global_load_dwordx4 v[182:185], v[158:159], off offset:512
	global_load_dwordx4 v[186:189], v[158:159], off offset:576
	v_lshl_add_u64 v[158:159], v[158:159], 0, s[98:99]
	global_load_dwordx4 v[190:193], v[158:159], off
	global_load_dwordx4 v[194:197], v[158:159], off offset:64
	global_load_dwordx4 v[198:201], v[158:159], off offset:512
	global_load_dwordx4 v[202:205], v[158:159], off offset:576
	v_lshl_add_u64 v[158:159], v[158:159], 0, s[98:99]
	global_load_dwordx4 v[206:209], v[158:159], off
	global_load_dwordx4 v[210:213], v[158:159], off offset:64
	global_load_dwordx4 v[214:217], v[158:159], off offset:512
	global_load_dwordx4 v[218:221], v[158:159], off offset:576
	v_lshl_add_u64 v[158:159], v[158:159], 0, s[98:99]
	global_load_dwordx4 v[224:227], v[158:159], off
	global_load_dwordx4 v[228:231], v[158:159], off offset:64
	global_load_dwordx4 v[232:235], v[158:159], off offset:512
	global_load_dwordx4 v[236:239], v[158:159], off offset:576
	global_store_dwordx4 v[160:161], v[124:127], off
	global_store_dwordx4 v[160:161], v[120:123], off offset:64
	global_store_dwordx4 v[160:161], v[116:119], off offset:512
	global_store_dwordx4 v[160:161], v[108:111], off offset:576
	v_lshl_add_u64 v[160:161], v[160:161], 0, s[98:99]
	global_store_dwordx4 v[160:161], v[112:115], off
	global_store_dwordx4 v[160:161], v[104:107], off offset:64
	global_store_dwordx4 v[160:161], v[100:103], off offset:512
	global_store_dwordx4 v[160:161], v[92:95], off offset:576
	v_lshl_add_u64 v[160:161], v[160:161], 0, s[98:99]
	global_store_dwordx4 v[160:161], v[96:99], off
	global_store_dwordx4 v[160:161], v[88:91], off offset:64
	global_store_dwordx4 v[160:161], v[84:87], off offset:512
	global_store_dwordx4 v[160:161], v[76:79], off offset:576
	v_lshl_add_u64 v[160:161], v[160:161], 0, s[98:99]
	global_store_dwordx4 v[160:161], v[80:83], off
	global_store_dwordx4 v[160:161], v[72:75], off offset:64
	global_store_dwordx4 v[160:161], v[68:71], off offset:512
	global_store_dwordx4 v[160:161], v[64:67], off offset:576
	v_lshl_add_u64 v[160:161], v[160:161], 0, s[100:101]
	s_waitcnt vmcnt(16)
	v_pk_fma_f32 v[60:61], v[60:61], v[148:149], v[174:175]
	v_pk_fma_f32 v[62:63], v[62:63], v[150:151], v[176:177]
	v_pk_fma_f32 v[56:57], v[56:57], v[162:163], v[178:179]
	v_pk_fma_f32 v[58:59], v[58:59], v[164:165], v[180:181]
	v_pk_fma_f32 v[52:53], v[52:53], v[166:167], v[182:183]
	v_pk_fma_f32 v[54:55], v[54:55], v[168:169], v[184:185]
	v_pk_fma_f32 v[44:45], v[44:45], v[170:171], v[186:187]
	v_pk_fma_f32 v[46:47], v[46:47], v[172:173], v[188:189]
	v_pk_fma_f32 v[48:49], v[48:49], v[148:149], v[190:191]
	v_pk_fma_f32 v[50:51], v[50:51], v[150:151], v[192:193]
	v_pk_fma_f32 v[40:41], v[40:41], v[162:163], v[194:195]
	v_pk_fma_f32 v[42:43], v[42:43], v[164:165], v[196:197]
	v_pk_fma_f32 v[36:37], v[36:37], v[166:167], v[198:199]
	v_pk_fma_f32 v[38:39], v[38:39], v[168:169], v[200:201]
	v_pk_fma_f32 v[28:29], v[28:29], v[170:171], v[202:203]
	v_pk_fma_f32 v[30:31], v[30:31], v[172:173], v[204:205]
	v_pk_fma_f32 v[32:33], v[32:33], v[148:149], v[206:207]
	v_pk_fma_f32 v[34:35], v[34:35], v[150:151], v[208:209]
	v_pk_fma_f32 v[24:25], v[24:25], v[162:163], v[210:211]
	v_pk_fma_f32 v[26:27], v[26:27], v[164:165], v[212:213]
	v_pk_fma_f32 v[20:21], v[20:21], v[166:167], v[214:215]
	v_pk_fma_f32 v[22:23], v[22:23], v[168:169], v[216:217]
	v_pk_fma_f32 v[12:13], v[12:13], v[170:171], v[218:219]
	v_pk_fma_f32 v[14:15], v[14:15], v[172:173], v[220:221]
	v_pk_fma_f32 v[16:17], v[16:17], v[148:149], v[224:225]
	v_pk_fma_f32 v[18:19], v[18:19], v[150:151], v[226:227]
	v_pk_fma_f32 v[8:9], v[8:9], v[162:163], v[228:229]
	v_pk_fma_f32 v[10:11], v[10:11], v[164:165], v[230:231]
	v_pk_fma_f32 v[4:5], v[4:5], v[166:167], v[232:233]
	v_pk_fma_f32 v[6:7], v[6:7], v[168:169], v[234:235]
	v_pk_fma_f32 v[0:1], v[0:1], v[170:171], v[236:237]
	v_pk_fma_f32 v[2:3], v[2:3], v[172:173], v[238:239]
	global_store_dwordx4 v[160:161], v[60:63], off
	global_store_dwordx4 v[160:161], v[56:59], off offset:64
	global_store_dwordx4 v[160:161], v[52:55], off offset:512
	global_store_dwordx4 v[160:161], v[44:47], off offset:576
	v_lshl_add_u64 v[160:161], v[160:161], 0, s[98:99]
	global_store_dwordx4 v[160:161], v[48:51], off
	global_store_dwordx4 v[160:161], v[40:43], off offset:64
	global_store_dwordx4 v[160:161], v[36:39], off offset:512
	global_store_dwordx4 v[160:161], v[28:31], off offset:576
	v_lshl_add_u64 v[160:161], v[160:161], 0, s[98:99]
	global_store_dwordx4 v[160:161], v[32:35], off
	global_store_dwordx4 v[160:161], v[24:27], off offset:64
	global_store_dwordx4 v[160:161], v[20:23], off offset:512
	global_store_dwordx4 v[160:161], v[12:15], off offset:576
	v_lshl_add_u64 v[160:161], v[160:161], 0, s[98:99]
	global_store_dwordx4 v[160:161], v[16:19], off
	global_store_dwordx4 v[160:161], v[8:11], off offset:64
	global_store_dwordx4 v[160:161], v[4:7], off offset:512
	global_store_dwordx4 v[160:161], v[0:3], off offset:576
	s_cbranch_vccz .LBB0_604
	s_waitcnt vmcnt(0)
	s_cmpk_gt_u32 s2, 0xff
	s_cbranch_scc1 .LBB0_619
	s_barrier

; #define PG8_STAGE(bufoff, gbase, voff) do { _Pragma("unroll") for (int _i = 0; _i < 2; ++_i) \
;         __builtin_amdgcn_global_load_lds((const unsigned*)((const char*)(gbase) + (size_t)_i * r64##voff + (voff)), (LAS unsigned*)(lds + (bufoff) + ldsw + _i * 8192), 16, 0, 0); } while (0)
; #define PG8_LDA(dst, b, h) do { _Pragma("unroll") for (int m = 0; m < 4; ++m) _Pragma("unroll") for (int k = 0; k < 2; ++k) dst[m][k] = *(const LAS bf16x8*)(lds + PG8_SA(b, h) + aoff + m * 2048 + k * 1024); } while (0)
; #define PG8_LDB(dst, b, h) do { _Pragma("unroll") for (int n = 0; n < 2; ++n) _Pragma("unroll") for (int k = 0; k < 2; ++k) dst[n][k] = *(const LAS bf16x8*)(lds + PG8_SB(b, h) + boff + n * 2048 + k * 1024); } while (0)
; #define PG8_MMA(ai, bj, At, Bt) do { __builtin_amdgcn_s_setprio(1); _Pragma("unroll") for (int m = 0; m < 4; ++m) _Pragma("unroll") for (int n = 0; n < 2; ++n) _Pragma("unroll") for (int k = 0; k < 2; ++k) \
;         acc[ai][bj][m][n] = __builtin_amdgcn_mfma_f32_16x16x32_bf16(Bt[n][k], At[m][k], acc[ai][bj][m][n], 0, 0, 0); __builtin_amdgcn_s_setprio(0); } while (0)
; #define PG8_WAIT_L(n) asm volatile("s_waitcnt lgkmcnt(" #n ")" ::: "memory")
; #define PG8_BAR __builtin_amdgcn_s_barrier()
; #define PG8_SCHED __builtin_amdgcn_sched_barrier(0)
; template <class Epi, class Sched>
; __device__ __forceinline__ void gemm_phase(LAS unsigned char* lds, const Gemm g, const Sched& S, const Epi& E) {
;     ...
;         for (int t = 0; t < nt; t += 2) {
;             const bool last = (t == nt - 2);
;             const char* a1 = cA + (size_t)(t + 1) * kstep;
;             const char* a2 = last ? nA : cA + (size_t)(t + 2) * kstep; const char* b2 = last ? nB : cB + (size_t)(t + 2) * kstep;
;             const char* a3 = a2 + kstep; const char* b3 = b2 + kstep;
;             PG8_LDB(B0, 0, 0); PG8_SCHED; PG8_LDA(At, 0, 0); PG8_STAGE(PG8_SA(1, 1), a1 + hstepA, voffA);
;             PG8_WAIT_L(8); PG8_BAR; PG8_WAIT_L(0); PG8_MMA(0, 0, At, B0); PG8_BAR; PG8_SCHED;
;             PG8_LDB(B1, 0, 1); PG8_STAGE(PG8_SB(0, 0), b2, voffB);
;             PG8_BAR; PG8_WAIT_L(0); PG8_MMA(0, 1, At, B1); PG8_BAR;
;             PG8_LDA(At, 0, 1); PG8_STAGE(PG8_SA(0, 0), a2, voffA);
;             PG8_BAR; PG8_WAIT_L(0); PG8_MMA(1, 0, At, B0); PG8_BAR; PG8_SCHED;
.LBB0_626:
	s_cmp_lg_u32 s63, 18
	s_cselect_b32 s64, s56, 0
	s_cselect_b32 s65, s57, 0
	s_add_u32 s58, s50, s64
	s_addc_u32 s59, s51, s65
	s_add_i32 s66, 0, 0x10000
	v_add_u32_e32 v137, s66, v135
	ds_read_b128 v[138:141], v137
	ds_read_b128 v[142:145], v137 offset:1024
	ds_read_b128 v[146:149], v137 offset:2048
	ds_read_b128 v[150:153], v137 offset:3072
	s_add_u32 s64, s48, s64
	s_addc_u32 s65, s49, s65
	v_lshl_add_u64 v[186:187], v[132:133], 0, s[56:57]
	v_lshl_add_u64 v[188:189], v[186:187], 0, s[26:27]
	s_add_i32 m0, s37, 0xc000
	ds_read_b128 v[154:157], v136
	ds_read_b128 v[158:161], v136 offset:1024
	ds_read_b128 v[162:165], v136 offset:2048
	ds_read_b128 v[166:169], v136 offset:3072
	ds_read_b128 v[170:173], v136 offset:4096
	ds_read_b128 v[174:177], v136 offset:5120
	ds_read_b128 v[178:181], v136 offset:6144
	ds_read_b128 v[182:185], v136 offset:7168
	global_load_lds_dwordx4 v[188:189], off
	v_lshl_add_u64 v[186:187], v[186:187], 0, s[38:39]
	s_add_i32 m0, s37, 0xe000
	s_nop 0
	global_load_lds_dwordx4 v[186:187], off
	s_waitcnt lgkmcnt(8)
	s_barrier
	s_waitcnt lgkmcnt(0)
	s_setprio 1
	s_waitcnt lgkmcnt(0)
	v_mfma_f32_16x16x32_bf16 v[124:127], v[138:141], v[154:157], v[124:127]
	v_mfma_f32_16x16x32_bf16 v[120:123], v[146:149], v[154:157], v[120:123]
	v_mfma_f32_16x16x32_bf16 v[112:115], v[138:141], v[162:165], v[112:115]
	v_mfma_f32_16x16x32_bf16 v[104:107], v[146:149], v[162:165], v[104:107]
	v_mfma_f32_16x16x32_bf16 v[96:99], v[138:141], v[170:173], v[96:99]
	v_mfma_f32_16x16x32_bf16 v[88:91], v[146:149], v[170:173], v[88:91]
	v_mfma_f32_16x16x32_bf16 v[80:83], v[138:141], v[178:181], v[80:83]
	v_mfma_f32_16x16x32_bf16 v[72:75], v[146:149], v[178:181], v[72:75]
	v_mfma_f32_16x16x32_bf16 v[124:127], v[142:145], v[158:161], v[124:127]
	v_mfma_f32_16x16x32_bf16 v[120:123], v[150:153], v[158:161], v[120:123]
	v_mfma_f32_16x16x32_bf16 v[112:115], v[142:145], v[166:169], v[112:115]
	v_mfma_f32_16x16x32_bf16 v[104:107], v[150:153], v[166:169], v[104:107]
	v_mfma_f32_16x16x32_bf16 v[96:99], v[142:145], v[174:177], v[96:99]
	v_mfma_f32_16x16x32_bf16 v[88:91], v[150:153], v[174:177], v[88:91]
	v_mfma_f32_16x16x32_bf16 v[80:83], v[142:145], v[182:185], v[80:83]
	v_mfma_f32_16x16x32_bf16 v[72:75], v[150:153], v[182:185], v[72:75]
	s_setprio 0
	s_barrier
	s_add_i32 s67, 0, 0x14000
	v_lshl_add_u64 v[202:203], s[64:65], 0, v[128:129]
	s_add_i32 s64, s66, s36
	v_add_u32_e32 v137, s67, v135
	s_mov_b32 m0, s64
	ds_read_b128 v[186:189], v137
	ds_read_b128 v[190:193], v137 offset:1024
	ds_read_b128 v[194:197], v137 offset:2048
	ds_read_b128 v[198:201], v137 offset:3072
	global_load_lds_dwordx4 v[202:203], off
	v_lshl_add_u64 v[204:205], v[202:203], 0, s[4:5]
	s_add_i32 m0, s64, 0x2000
	s_nop 0
	global_load_lds_dwordx4 v[204:205], off
	s_barrier
	s_waitcnt lgkmcnt(0)
	s_setprio 1
	s_waitcnt lgkmcnt(0)
	v_mfma_f32_16x16x32_bf16 v[116:119], v[186:189], v[154:157], v[116:119]
	v_mfma_f32_16x16x32_bf16 v[108:111], v[194:197], v[154:157], v[108:111]
	v_mfma_f32_16x16x32_bf16 v[100:103], v[186:189], v[162:165], v[100:103]
	v_mfma_f32_16x16x32_bf16 v[92:95], v[194:197], v[162:165], v[92:95]
	v_mfma_f32_16x16x32_bf16 v[84:87], v[186:189], v[170:173], v[84:87]
	v_mfma_f32_16x16x32_bf16 v[76:79], v[194:197], v[170:173], v[76:79]
	v_mfma_f32_16x16x32_bf16 v[68:71], v[186:189], v[178:181], v[68:71]
	v_mfma_f32_16x16x32_bf16 v[64:67], v[194:197], v[178:181], v[64:67]
	v_mfma_f32_16x16x32_bf16 v[116:119], v[190:193], v[158:161], v[116:119]
	v_mfma_f32_16x16x32_bf16 v[108:111], v[198:201], v[158:161], v[108:111]
	v_mfma_f32_16x16x32_bf16 v[100:103], v[190:193], v[166:169], v[100:103]
	v_mfma_f32_16x16x32_bf16 v[92:95], v[198:201], v[166:169], v[92:95]
	v_mfma_f32_16x16x32_bf16 v[84:87], v[190:193], v[174:177], v[84:87]
	v_mfma_f32_16x16x32_bf16 v[76:79], v[198:201], v[174:177], v[76:79]
	v_mfma_f32_16x16x32_bf16 v[68:71], v[190:193], v[182:185], v[68:71]
	v_mfma_f32_16x16x32_bf16 v[64:67], v[198:201], v[182:185], v[64:67]
	s_setprio 0
	s_mov_b32 m0, s37
	v_lshl_add_u64 v[204:205], s[58:59], 0, v[130:131]
	s_barrier
	ds_read_b128 v[154:157], v136 offset:16384
	ds_read_b128 v[158:161], v136 offset:17408
	ds_read_b128 v[162:165], v136 offset:18432
	ds_read_b128 v[166:169], v136 offset:19456
	ds_read_b128 v[170:173], v136 offset:20480
	ds_read_b128 v[174:177], v136 offset:21504
	ds_read_b128 v[178:181], v136 offset:22528
	ds_read_b128 v[182:185], v136 offset:23552
	global_load_lds_dwordx4 v[204:205], off
	v_lshl_add_u64 v[206:207], v[204:205], 0, s[6:7]
	s_mov_b32 m0, s40
	s_nop 0
	global_load_lds_dwordx4 v[206:207], off
	s_barrier
	s_waitcnt lgkmcnt(0)
	s_setprio 1
	s_waitcnt lgkmcnt(0)
	v_mfma_f32_16x16x32_bf16 v[60:63], v[138:141], v[154:157], v[60:63]
	v_mfma_f32_16x16x32_bf16 v[56:59], v[146:149], v[154:157], v[56:59]
	v_mfma_f32_16x16x32_bf16 v[48:51], v[138:141], v[162:165], v[48:51]
	v_mfma_f32_16x16x32_bf16 v[40:43], v[146:149], v[162:165], v[40:43]
	v_mfma_f32_16x16x32_bf16 v[32:35], v[138:141], v[170:173], v[32:35]
	v_mfma_f32_16x16x32_bf16 v[24:27], v[146:149], v[170:173], v[24:27]
	v_mfma_f32_16x16x32_bf16 v[16:19], v[138:141], v[178:181], v[16:19]
	v_mfma_f32_16x16x32_bf16 v[8:11], v[146:149], v[178:181], v[8:11]
	v_mfma_f32_16x16x32_bf16 v[60:63], v[142:145], v[158:161], v[60:63]
	v_mfma_f32_16x16x32_bf16 v[56:59], v[150:153], v[158:161], v[56:59]
	v_mfma_f32_16x16x32_bf16 v[48:51], v[142:145], v[166:169], v[48:51]
	v_mfma_f32_16x16x32_bf16 v[40:43], v[150:153], v[166:169], v[40:43]
	v_mfma_f32_16x16x32_bf16 v[32:35], v[142:145], v[174:177], v[32:35]
	v_mfma_f32_16x16x32_bf16 v[24:27], v[150:153], v[174:177], v[24:27]
	v_mfma_f32_16x16x32_bf16 v[16:19], v[142:145], v[182:185], v[16:19]
	v_mfma_f32_16x16x32_bf16 v[8:11], v[150:153], v[182:185], v[8:11]
	s_setprio 0
	s_barrier
; #define PG8_STAGE(bufoff, gbase, voff) do { _Pragma("unroll") for (int _i = 0; _i < 2; ++_i) \
;         __builtin_amdgcn_global_load_lds((const unsigned*)((const char*)(gbase) + (size_t)_i * r64##voff + (voff)), (LAS unsigned*)(lds + (bufoff) + ldsw + _i * 8192), 16, 0, 0); } while (0)
; #define PG8_LDA(dst, b, h) do { _Pragma("unroll") for (int m = 0; m < 4; ++m) _Pragma("unroll") for (int k = 0; k < 2; ++k) dst[m][k] = *(const LAS bf16x8*)(lds + PG8_SA(b, h) + aoff + m * 2048 + k * 1024); } while (0)
; #define PG8_LDB(dst, b, h) do { _Pragma("unroll") for (int n = 0; n < 2; ++n) _Pragma("unroll") for (int k = 0; k < 2; ++k) dst[n][k] = *(const LAS bf16x8*)(lds + PG8_SB(b, h) + boff + n * 2048 + k * 1024); } while (0)
; #define PG8_MMA(ai, bj, At, Bt) do { __builtin_amdgcn_s_setprio(1); _Pragma("unroll") for (int m = 0; m < 4; ++m) _Pragma("unroll") for (int n = 0; n < 2; ++n) _Pragma("unroll") for (int k = 0; k < 2; ++k) \
;         acc[ai][bj][m][n] = __builtin_amdgcn_mfma_f32_16x16x32_bf16(Bt[n][k], At[m][k], acc[ai][bj][m][n], 0, 0, 0); __builtin_amdgcn_s_setprio(0); } while (0)
; #define PG8_WAIT_V(n) asm volatile("s_waitcnt vmcnt(" #n ")" ::: "memory")
; #define PG8_WAIT_L(n) asm volatile("s_waitcnt lgkmcnt(" #n ")" ::: "memory")
; #define PG8_BAR __builtin_amdgcn_s_barrier()
; #define PG8_SCHED __builtin_amdgcn_sched_barrier(0)
; template <class Epi, class Sched>
; __device__ __forceinline__ void gemm_phase(LAS unsigned char* lds, const Gemm g, const Sched& S, const Epi& E) {
;     ...
;             PG8_STAGE(PG8_SB(0, 1), b2 + hstepB, voffB);
;             PG8_WAIT_V(6); PG8_BAR; PG8_MMA(1, 1, At, B1); PG8_BAR;
;             PG8_LDB(B0, 1, 0); PG8_SCHED; PG8_LDA(At, 1, 0); PG8_STAGE(PG8_SA(0, 1), a2 + hstepA, voffA);
;             PG8_WAIT_L(8); PG8_BAR; PG8_WAIT_L(0); PG8_MMA(0, 0, At, B0); PG8_BAR; PG8_SCHED;
;             PG8_LDB(B1, 1, 1); PG8_STAGE(PG8_SB(1, 0), b3, voffB);
;             PG8_BAR; PG8_WAIT_L(0); PG8_MMA(0, 1, At, B1); PG8_BAR;
;             PG8_LDA(At, 1, 1); PG8_STAGE(PG8_SA(1, 0), a3, voffA);
;             PG8_BAR; PG8_WAIT_L(0); PG8_MMA(1, 0, At, B0); PG8_BAR; PG8_SCHED;
;             PG8_STAGE(PG8_SB(1, 1), b3 + hstepB, voffB);
	s_add_i32 s58, s67, s36
	v_lshl_add_u64 v[138:139], v[202:203], 0, s[6:7]
	s_mov_b32 m0, s58
	s_nop 0
	global_load_lds_dwordx4 v[138:139], off
	v_lshl_add_u64 v[138:139], v[202:203], 0, s[8:9]
	s_add_i32 m0, s58, 0x2000
	s_nop 0
	global_load_lds_dwordx4 v[138:139], off
	s_waitcnt vmcnt(6)
	s_barrier
	s_setprio 1
	v_mfma_f32_16x16x32_bf16 v[52:55], v[186:189], v[154:157], v[52:55]
	v_mfma_f32_16x16x32_bf16 v[44:47], v[194:197], v[154:157], v[44:47]
	v_mfma_f32_16x16x32_bf16 v[36:39], v[186:189], v[162:165], v[36:39]
	v_mfma_f32_16x16x32_bf16 v[28:31], v[194:197], v[162:165], v[28:31]
	v_mfma_f32_16x16x32_bf16 v[20:23], v[186:189], v[170:173], v[20:23]
	v_mfma_f32_16x16x32_bf16 v[12:15], v[194:197], v[170:173], v[12:15]
	v_mfma_f32_16x16x32_bf16 v[4:7], v[186:189], v[178:181], v[4:7]
	v_mfma_f32_16x16x32_bf16 v[0:3], v[194:197], v[178:181], v[0:3]
	v_mfma_f32_16x16x32_bf16 v[52:55], v[190:193], v[158:161], v[52:55]
	v_mfma_f32_16x16x32_bf16 v[44:47], v[198:201], v[158:161], v[44:47]
	v_mfma_f32_16x16x32_bf16 v[36:39], v[190:193], v[166:169], v[36:39]
	v_mfma_f32_16x16x32_bf16 v[28:31], v[198:201], v[166:169], v[28:31]
	v_mfma_f32_16x16x32_bf16 v[20:23], v[190:193], v[174:177], v[20:23]
	v_mfma_f32_16x16x32_bf16 v[12:15], v[198:201], v[174:177], v[12:15]
	v_mfma_f32_16x16x32_bf16 v[4:7], v[190:193], v[182:185], v[4:7]
	v_mfma_f32_16x16x32_bf16 v[0:3], v[198:201], v[182:185], v[0:3]
	s_setprio 0
	s_add_i32 s58, 0, 0x18000
	v_add_u32_e32 v137, s58, v135
	s_barrier
	ds_read_b128 v[138:141], v137
	ds_read_b128 v[142:145], v137 offset:1024
	ds_read_b128 v[146:149], v137 offset:2048
	ds_read_b128 v[150:153], v137 offset:3072
	s_mov_b32 m0, s41
	v_lshl_add_u64 v[186:187], v[204:205], 0, s[10:11]
	ds_read_b128 v[154:157], v136 offset:32768
	ds_read_b128 v[158:161], v136 offset:33792
	ds_read_b128 v[162:165], v136 offset:34816
	ds_read_b128 v[166:169], v136 offset:35840
	ds_read_b128 v[170:173], v136 offset:36864
	ds_read_b128 v[174:177], v136 offset:37888
	ds_read_b128 v[178:181], v136 offset:38912
	ds_read_b128 v[182:185], v136 offset:39936
	global_load_lds_dwordx4 v[186:187], off
	v_lshl_add_u64 v[186:187], v[204:205], 0, s[16:17]
	s_mov_b32 m0, s60
	s_nop 0
	global_load_lds_dwordx4 v[186:187], off
	s_waitcnt lgkmcnt(8)
	s_barrier
	s_waitcnt lgkmcnt(0)
	s_setprio 1
	s_waitcnt lgkmcnt(0)
	v_mfma_f32_16x16x32_bf16 v[124:127], v[138:141], v[154:157], v[124:127]
	v_mfma_f32_16x16x32_bf16 v[120:123], v[146:149], v[154:157], v[120:123]
	v_mfma_f32_16x16x32_bf16 v[112:115], v[138:141], v[162:165], v[112:115]
	v_mfma_f32_16x16x32_bf16 v[104:107], v[146:149], v[162:165], v[104:107]
	v_mfma_f32_16x16x32_bf16 v[96:99], v[138:141], v[170:173], v[96:99]
	v_mfma_f32_16x16x32_bf16 v[88:91], v[146:149], v[170:173], v[88:91]
	v_mfma_f32_16x16x32_bf16 v[80:83], v[138:141], v[178:181], v[80:83]
	v_mfma_f32_16x16x32_bf16 v[72:75], v[146:149], v[178:181], v[72:75]
	v_mfma_f32_16x16x32_bf16 v[124:127], v[142:145], v[158:161], v[124:127]
	v_mfma_f32_16x16x32_bf16 v[120:123], v[150:153], v[158:161], v[120:123]
	v_mfma_f32_16x16x32_bf16 v[112:115], v[142:145], v[166:169], v[112:115]
	v_mfma_f32_16x16x32_bf16 v[104:107], v[150:153], v[166:169], v[104:107]
	v_mfma_f32_16x16x32_bf16 v[96:99], v[142:145], v[174:177], v[96:99]
	v_mfma_f32_16x16x32_bf16 v[88:91], v[150:153], v[174:177], v[88:91]
	v_mfma_f32_16x16x32_bf16 v[80:83], v[142:145], v[182:185], v[80:83]
	v_mfma_f32_16x16x32_bf16 v[72:75], v[150:153], v[182:185], v[72:75]
	s_setprio 0
	s_barrier
	s_add_i32 s59, 0, 0x1c000
	s_add_i32 s58, s58, s36
	v_add_u32_e32 v137, s59, v135
	v_lshl_add_u64 v[206:207], v[202:203], 0, s[18:19]
	s_mov_b32 m0, s58
	ds_read_b128 v[186:189], v137
	ds_read_b128 v[190:193], v137 offset:1024
	ds_read_b128 v[194:197], v137 offset:2048
	ds_read_b128 v[198:201], v137 offset:3072
	global_load_lds_dwordx4 v[206:207], off
	v_lshl_add_u64 v[206:207], v[202:203], 0, s[20:21]
	s_add_i32 m0, s58, 0x2000
	s_nop 0
	global_load_lds_dwordx4 v[206:207], off
	s_barrier
	s_waitcnt lgkmcnt(0)
	s_setprio 1
	s_waitcnt lgkmcnt(0)
	v_mfma_f32_16x16x32_bf16 v[116:119], v[186:189], v[154:157], v[116:119]
	v_mfma_f32_16x16x32_bf16 v[108:111], v[194:197], v[154:157], v[108:111]
	v_mfma_f32_16x16x32_bf16 v[100:103], v[186:189], v[162:165], v[100:103]
	v_mfma_f32_16x16x32_bf16 v[92:95], v[194:197], v[162:165], v[92:95]
	v_mfma_f32_16x16x32_bf16 v[84:87], v[186:189], v[170:173], v[84:87]
	v_mfma_f32_16x16x32_bf16 v[76:79], v[194:197], v[170:173], v[76:79]
	v_mfma_f32_16x16x32_bf16 v[68:71], v[186:189], v[178:181], v[68:71]
	v_mfma_f32_16x16x32_bf16 v[64:67], v[194:197], v[178:181], v[64:67]
	v_mfma_f32_16x16x32_bf16 v[116:119], v[190:193], v[158:161], v[116:119]
	v_mfma_f32_16x16x32_bf16 v[108:111], v[198:201], v[158:161], v[108:111]
	v_mfma_f32_16x16x32_bf16 v[100:103], v[190:193], v[166:169], v[100:103]
	v_mfma_f32_16x16x32_bf16 v[92:95], v[198:201], v[166:169], v[92:95]
	v_mfma_f32_16x16x32_bf16 v[84:87], v[190:193], v[174:177], v[84:87]
	v_mfma_f32_16x16x32_bf16 v[76:79], v[198:201], v[174:177], v[76:79]
	v_mfma_f32_16x16x32_bf16 v[68:71], v[190:193], v[182:185], v[68:71]
	v_mfma_f32_16x16x32_bf16 v[64:67], v[198:201], v[182:185], v[64:67]
	s_setprio 0
	s_mov_b32 m0, s61
	v_lshl_add_u64 v[206:207], v[204:205], 0, s[18:19]
	s_barrier
	ds_read_b128 v[154:157], v136 offset:49152
	ds_read_b128 v[158:161], v136 offset:50176
	ds_read_b128 v[162:165], v136 offset:51200
	ds_read_b128 v[166:169], v136 offset:52224
	ds_read_b128 v[170:173], v136 offset:53248
	ds_read_b128 v[174:177], v136 offset:54272
	ds_read_b128 v[178:181], v136 offset:55296
	ds_read_b128 v[182:185], v136 offset:56320
	global_load_lds_dwordx4 v[206:207], off
	v_lshl_add_u64 v[204:205], v[204:205], 0, s[22:23]
	s_mov_b32 m0, s62
	s_nop 0
	global_load_lds_dwordx4 v[204:205], off
	s_barrier
; __device__ __forceinline__ int otid() { int t = (int)__builtin_amdgcn_workitem_id_x(); asm volatile("" : "+v"(t)); return t; }
;     __device__ __forceinline__ void operator()(const f32x4 (&acc)[2][2][4][2], const pg8::Unit& u, int wr_, int wc_, int fr_, int fq_) const {
;         const int t2_ = otid(), wr = t2_ >> 8, wc = (t2_ >> 6) & 3, fr = t2_ & 15, fq = (t2_ >> 4) & 3; (void)wr_; (void)wc_; (void)fr_; (void)fq_;
;         float* dst = dstC - (size_t)RL * 2048;
;         const int row0 = u.pm * 256 + wr * 64 + fr, col0 = u.pn * 256 + wc * 32 + 4 * fq;
; #pragma unroll
;         for (int ai = 0; ai < 2; ++ai)
; #pragma unroll
;             for (int m = 0; m < 4; ++m) { const size_t ro = (size_t)(row0 + ai * 128 + m * 16) * 2048;
; #pragma unroll
;                 for (int bj = 0; bj < 2; ++bj)
; #pragma unroll
;                     for (int n = 0; n < 2; ++n) { const int col = col0 + bj * 128 + n * 16;
;                         const f32x4 v = *(const f32x4*)(gate + col) * acc[ai][bj][m][n];
;                         __hip_atomic_fetch_add(dst + ro + col, v[0], __ATOMIC_RELAXED, __HIP_MEMORY_SCOPE_AGENT); __hip_atomic_fetch_add(dst + ro + col + 1, v[1], __ATOMIC_RELAXED, __HIP_MEMORY_SCOPE_AGENT);
;                         __hip_atomic_fetch_add(dst + ro + col + 2, v[2], __ATOMIC_RELAXED, __HIP_MEMORY_SCOPE_AGENT); __hip_atomic_fetch_add(dst + ro + col + 3, v[3], __ATOMIC_RELAXED, __HIP_MEMORY_SCOPE_AGENT); } }
	s_waitcnt lgkmcnt(0)
	s_setprio 1
	s_waitcnt lgkmcnt(0)
	v_mfma_f32_16x16x32_bf16 v[60:63], v[138:141], v[154:157], v[60:63]
	v_mfma_f32_16x16x32_bf16 v[56:59], v[146:149], v[154:157], v[56:59]
	v_mfma_f32_16x16x32_bf16 v[48:51], v[138:141], v[162:165], v[48:51]
	v_mfma_f32_16x16x32_bf16 v[40:43], v[146:149], v[162:165], v[40:43]
	v_mfma_f32_16x16x32_bf16 v[32:35], v[138:141], v[170:173], v[32:35]
	v_mfma_f32_16x16x32_bf16 v[24:27], v[146:149], v[170:173], v[24:27]
	v_mfma_f32_16x16x32_bf16 v[16:19], v[138:141], v[178:181], v[16:19]
	v_mfma_f32_16x16x32_bf16 v[8:11], v[146:149], v[178:181], v[8:11]
	v_mfma_f32_16x16x32_bf16 v[60:63], v[142:145], v[158:161], v[60:63]
	v_mfma_f32_16x16x32_bf16 v[56:59], v[150:153], v[158:161], v[56:59]
	v_mfma_f32_16x16x32_bf16 v[48:51], v[142:145], v[166:169], v[48:51]
	v_mfma_f32_16x16x32_bf16 v[40:43], v[150:153], v[166:169], v[40:43]
	v_mfma_f32_16x16x32_bf16 v[32:35], v[142:145], v[174:177], v[32:35]
	v_mfma_f32_16x16x32_bf16 v[24:27], v[150:153], v[174:177], v[24:27]
	v_mfma_f32_16x16x32_bf16 v[16:19], v[142:145], v[182:185], v[16:19]
	v_mfma_f32_16x16x32_bf16 v[8:11], v[150:153], v[182:185], v[8:11]
	s_setprio 0
	s_barrier
	s_add_i32 s58, s59, s36
	v_lshl_add_u64 v[138:139], v[202:203], 0, s[22:23]
	s_mov_b32 m0, s58
	s_nop 0
	global_load_lds_dwordx4 v[138:139], off
	v_lshl_add_u64 v[138:139], v[202:203], 0, s[24:25]
	s_add_i32 m0, s58, 0x2000
	s_nop 0
	global_load_lds_dwordx4 v[138:139], off
	s_waitcnt vmcnt(6)
	s_barrier
	s_setprio 1
	v_mfma_f32_16x16x32_bf16 v[52:55], v[186:189], v[154:157], v[52:55]
	v_mfma_f32_16x16x32_bf16 v[44:47], v[194:197], v[154:157], v[44:47]
	v_mfma_f32_16x16x32_bf16 v[36:39], v[186:189], v[162:165], v[36:39]
	v_mfma_f32_16x16x32_bf16 v[28:31], v[194:197], v[162:165], v[28:31]
	v_mfma_f32_16x16x32_bf16 v[20:23], v[186:189], v[170:173], v[20:23]
	v_mfma_f32_16x16x32_bf16 v[12:15], v[194:197], v[170:173], v[12:15]
	v_mfma_f32_16x16x32_bf16 v[4:7], v[186:189], v[178:181], v[4:7]
	v_mfma_f32_16x16x32_bf16 v[0:3], v[194:197], v[178:181], v[0:3]
	v_mfma_f32_16x16x32_bf16 v[52:55], v[190:193], v[158:161], v[52:55]
	v_mfma_f32_16x16x32_bf16 v[44:47], v[198:201], v[158:161], v[44:47]
	v_mfma_f32_16x16x32_bf16 v[36:39], v[190:193], v[166:169], v[36:39]
	v_mfma_f32_16x16x32_bf16 v[28:31], v[198:201], v[166:169], v[28:31]
	v_mfma_f32_16x16x32_bf16 v[20:23], v[190:193], v[174:177], v[20:23]
	v_mfma_f32_16x16x32_bf16 v[12:15], v[198:201], v[174:177], v[12:15]
	v_mfma_f32_16x16x32_bf16 v[4:7], v[190:193], v[182:185], v[4:7]
	v_mfma_f32_16x16x32_bf16 v[0:3], v[198:201], v[182:185], v[0:3]
	s_setprio 0
	s_add_i32 s63, s63, 2
	s_add_u32 s56, s56, 0x100
	s_addc_u32 s57, s57, 0
	s_cmp_gt_u32 s63, 19
	s_barrier
	s_cbranch_scc0 .LBB0_626
	s_add_u32 s48, s54, 0x66ba000
	s_addc_u32 s49, s55, 0
	v_mov_b32_e32 v130, v222
	s_add_u32 s50, s52, 0xfde80000
	s_addc_u32 s51, s53, -1
	v_lshrrev_b32_e32 v128, 1, v130
	v_lshrrev_b32_e32 v131, 2, v130
	s_lshl_b32 s35, s35, 8
	v_and_b32_e32 v128, 0x60, v128
	v_and_b32_e32 v131, 12, v131
	v_or3_b32 v128, v128, s35, v131
	v_lshlrev_b32_e32 v128, 2, v128
	v_ashrrev_i32_e32 v131, 2, v130
	s_lshl_b32 s12, s12, 8
	v_and_b32_e32 v131, 0xffffffc0, v131
	v_and_or_b32 v130, v130, 15, s12
	v_add_u32_e32 v132, v130, v131
	v_ashrrev_i32_e32 v133, 31, v132
	v_lshlrev_b64 v[130:131], 13, v[132:133]
	v_lshl_add_u64 v[130:131], s[50:51], 0, v[130:131]
	v_lshl_add_u64 v[130:131], v[130:131], 0, v[128:129]
	v_or_b32_e32 v135, 64, v128
	v_or_b32_e32 v133, 0x200, v128
	s_cmpk_lt_u32 s34, 0x100
	s_mov_b32 s98, 0x20000
	s_mov_b32 s99, 0
	s_mov_b32 s100, 0xa0000
	s_mov_b32 s101, 0
	global_load_dwordx4 v[136:139], v128, s[48:49]
	global_load_dwordx4 v[140:143], v128, s[48:49] offset:64
	global_load_dwordx4 v[144:147], v128, s[48:49] offset:512
	global_load_dwordx4 v[148:151], v128, s[48:49] offset:576
	s_waitcnt vmcnt(0)
	v_pk_mul_f32 v[124:125], v[124:125], v[136:137]
	v_pk_mul_f32 v[126:127], v[126:127], v[138:139]
	global_atomic_add_f32 v[130:131], v124, off
	global_atomic_add_f32 v[130:131], v125, off offset:4
	global_atomic_add_f32 v[130:131], v126, off offset:8
	global_atomic_add_f32 v[130:131], v127, off offset:12
	v_pk_mul_f32 v[120:121], v[120:121], v[140:141]
	v_pk_mul_f32 v[122:123], v[122:123], v[142:143]
	global_atomic_add_f32 v[130:131], v120, off offset:64
	global_atomic_add_f32 v[130:131], v121, off offset:68
	global_atomic_add_f32 v[130:131], v122, off offset:72
	global_atomic_add_f32 v[130:131], v123, off offset:76
	v_pk_mul_f32 v[116:117], v[116:117], v[144:145]
	v_pk_mul_f32 v[118:119], v[118:119], v[146:147]
	global_atomic_add_f32 v[130:131], v116, off offset:512
	global_atomic_add_f32 v[130:131], v117, off offset:516
	global_atomic_add_f32 v[130:131], v118, off offset:520
	global_atomic_add_f32 v[130:131], v119, off offset:524
	v_pk_mul_f32 v[108:109], v[108:109], v[148:149]
	v_pk_mul_f32 v[110:111], v[110:111], v[150:151]
	global_atomic_add_f32 v[130:131], v108, off offset:576
	global_atomic_add_f32 v[130:131], v109, off offset:580
	global_atomic_add_f32 v[130:131], v110, off offset:584
	global_atomic_add_f32 v[130:131], v111, off offset:588
	v_lshl_add_u64 v[130:131], v[130:131], 0, s[98:99]
	v_pk_mul_f32 v[112:113], v[112:113], v[136:137]
	v_pk_mul_f32 v[114:115], v[114:115], v[138:139]
	global_atomic_add_f32 v[130:131], v112, off
	global_atomic_add_f32 v[130:131], v113, off offset:4
	global_atomic_add_f32 v[130:131], v114, off offset:8
	global_atomic_add_f32 v[130:131], v115, off offset:12
	v_pk_mul_f32 v[104:105], v[104:105], v[140:141]
	v_pk_mul_f32 v[106:107], v[106:107], v[142:143]
	global_atomic_add_f32 v[130:131], v104, off offset:64
;     __device__ __forceinline__ void operator()(const f32x4 (&acc)[2][2][4][2], const pg8::Unit& u, int wr_, int wc_, int fr_, int fq_) const {
;     ...
; #pragma unroll
;         for (int ai = 0; ai < 2; ++ai)
; #pragma unroll
;             for (int m = 0; m < 4; ++m) { const size_t ro = (size_t)(row0 + ai * 128 + m * 16) * 2048;
; #pragma unroll
;                 for (int bj = 0; bj < 2; ++bj)
; #pragma unroll
;                     for (int n = 0; n < 2; ++n) { const int col = col0 + bj * 128 + n * 16;
;                         const f32x4 v = *(const f32x4*)(gate + col) * acc[ai][bj][m][n];
;                         __hip_atomic_fetch_add(dst + ro + col, v[0], __ATOMIC_RELAXED, __HIP_MEMORY_SCOPE_AGENT); __hip_atomic_fetch_add(dst + ro + col + 1, v[1], __ATOMIC_RELAXED, __HIP_MEMORY_SCOPE_AGENT);
;                         __hip_atomic_fetch_add(dst + ro + col + 2, v[2], __ATOMIC_RELAXED, __HIP_MEMORY_SCOPE_AGENT); __hip_atomic_fetch_add(dst + ro + col + 3, v[3], __ATOMIC_RELAXED, __HIP_MEMORY_SCOPE_AGENT); } }
	global_atomic_add_f32 v[130:131], v105, off offset:68
	global_atomic_add_f32 v[130:131], v106, off offset:72
	global_atomic_add_f32 v[130:131], v107, off offset:76
	v_pk_mul_f32 v[100:101], v[100:101], v[144:145]
	v_pk_mul_f32 v[102:103], v[102:103], v[146:147]
	global_atomic_add_f32 v[130:131], v100, off offset:512
	global_atomic_add_f32 v[130:131], v101, off offset:516
	global_atomic_add_f32 v[130:131], v102, off offset:520
	global_atomic_add_f32 v[130:131], v103, off offset:524
	v_pk_mul_f32 v[92:93], v[92:93], v[148:149]
	v_pk_mul_f32 v[94:95], v[94:95], v[150:151]
	global_atomic_add_f32 v[130:131], v92, off offset:576
	global_atomic_add_f32 v[130:131], v93, off offset:580
	global_atomic_add_f32 v[130:131], v94, off offset:584
	global_atomic_add_f32 v[130:131], v95, off offset:588
	v_lshl_add_u64 v[130:131], v[130:131], 0, s[98:99]
	v_pk_mul_f32 v[96:97], v[96:97], v[136:137]
	v_pk_mul_f32 v[98:99], v[98:99], v[138:139]
	global_atomic_add_f32 v[130:131], v96, off
	global_atomic_add_f32 v[130:131], v97, off offset:4
	global_atomic_add_f32 v[130:131], v98, off offset:8
	global_atomic_add_f32 v[130:131], v99, off offset:12
	v_pk_mul_f32 v[88:89], v[88:89], v[140:141]
	v_pk_mul_f32 v[90:91], v[90:91], v[142:143]
	global_atomic_add_f32 v[130:131], v88, off offset:64
	global_atomic_add_f32 v[130:131], v89, off offset:68
	global_atomic_add_f32 v[130:131], v90, off offset:72
	global_atomic_add_f32 v[130:131], v91, off offset:76
	v_pk_mul_f32 v[84:85], v[84:85], v[144:145]
	v_pk_mul_f32 v[86:87], v[86:87], v[146:147]
	global_atomic_add_f32 v[130:131], v84, off offset:512
	global_atomic_add_f32 v[130:131], v85, off offset:516
	global_atomic_add_f32 v[130:131], v86, off offset:520
	global_atomic_add_f32 v[130:131], v87, off offset:524
	v_pk_mul_f32 v[76:77], v[76:77], v[148:149]
	v_pk_mul_f32 v[78:79], v[78:79], v[150:151]
	global_atomic_add_f32 v[130:131], v76, off offset:576
	global_atomic_add_f32 v[130:131], v77, off offset:580
	global_atomic_add_f32 v[130:131], v78, off offset:584
	global_atomic_add_f32 v[130:131], v79, off offset:588
	v_lshl_add_u64 v[130:131], v[130:131], 0, s[98:99]
	v_pk_mul_f32 v[80:81], v[80:81], v[136:137]
	v_pk_mul_f32 v[82:83], v[82:83], v[138:139]
	global_atomic_add_f32 v[130:131], v80, off
	global_atomic_add_f32 v[130:131], v81, off offset:4
	global_atomic_add_f32 v[130:131], v82, off offset:8
	global_atomic_add_f32 v[130:131], v83, off offset:12
	v_pk_mul_f32 v[72:73], v[72:73], v[140:141]
	v_pk_mul_f32 v[74:75], v[74:75], v[142:143]
	global_atomic_add_f32 v[130:131], v72, off offset:64
	global_atomic_add_f32 v[130:131], v73, off offset:68
	global_atomic_add_f32 v[130:131], v74, off offset:72
	global_atomic_add_f32 v[130:131], v75, off offset:76
	v_pk_mul_f32 v[68:69], v[68:69], v[144:145]
	v_pk_mul_f32 v[70:71], v[70:71], v[146:147]
	global_atomic_add_f32 v[130:131], v68, off offset:512
	global_atomic_add_f32 v[130:131], v69, off offset:516
	global_atomic_add_f32 v[130:131], v70, off offset:520
	global_atomic_add_f32 v[130:131], v71, off offset:524
	v_pk_mul_f32 v[64:65], v[64:65], v[148:149]
	v_pk_mul_f32 v[66:67], v[66:67], v[150:151]
	global_atomic_add_f32 v[130:131], v64, off offset:576
	global_atomic_add_f32 v[130:131], v65, off offset:580
	global_atomic_add_f32 v[130:131], v66, off offset:584
	global_atomic_add_f32 v[130:131], v67, off offset:588
	v_lshl_add_u64 v[130:131], v[130:131], 0, s[100:101]
	v_pk_mul_f32 v[60:61], v[60:61], v[136:137]
	v_pk_mul_f32 v[62:63], v[62:63], v[138:139]
	global_atomic_add_f32 v[130:131], v60, off
	global_atomic_add_f32 v[130:131], v61, off offset:4
	global_atomic_add_f32 v[130:131], v62, off offset:8
	global_atomic_add_f32 v[130:131], v63, off offset:12
	v_pk_mul_f32 v[56:57], v[56:57], v[140:141]
	v_pk_mul_f32 v[58:59], v[58:59], v[142:143]
	global_atomic_add_f32 v[130:131], v56, off offset:64
	global_atomic_add_f32 v[130:131], v57, off offset:68
	global_atomic_add_f32 v[130:131], v58, off offset:72
	global_atomic_add_f32 v[130:131], v59, off offset:76
	v_pk_mul_f32 v[52:53], v[52:53], v[144:145]
	v_pk_mul_f32 v[54:55], v[54:55], v[146:147]
	global_atomic_add_f32 v[130:131], v52, off offset:512
	global_atomic_add_f32 v[130:131], v53, off offset:516
	global_atomic_add_f32 v[130:131], v54, off offset:520
;     __device__ __forceinline__ void operator()(const f32x4 (&acc)[2][2][4][2], const pg8::Unit& u, int wr_, int wc_, int fr_, int fq_) const {
;     ...
; #pragma unroll
;         for (int ai = 0; ai < 2; ++ai)
; #pragma unroll
;             for (int m = 0; m < 4; ++m) { const size_t ro = (size_t)(row0 + ai * 128 + m * 16) * 2048;
; #pragma unroll
;                 for (int bj = 0; bj < 2; ++bj)
; #pragma unroll
;                     for (int n = 0; n < 2; ++n) { const int col = col0 + bj * 128 + n * 16;
;                         const f32x4 v = *(const f32x4*)(gate + col) * acc[ai][bj][m][n];
;                         __hip_atomic_fetch_add(dst + ro + col, v[0], __ATOMIC_RELAXED, __HIP_MEMORY_SCOPE_AGENT); __hip_atomic_fetch_add(dst + ro + col + 1, v[1], __ATOMIC_RELAXED, __HIP_MEMORY_SCOPE_AGENT);
;                         __hip_atomic_fetch_add(dst + ro + col + 2, v[2], __ATOMIC_RELAXED, __HIP_MEMORY_SCOPE_AGENT); __hip_atomic_fetch_add(dst + ro + col + 3, v[3], __ATOMIC_RELAXED, __HIP_MEMORY_SCOPE_AGENT); } }
	global_atomic_add_f32 v[130:131], v55, off offset:524
	v_pk_mul_f32 v[44:45], v[44:45], v[148:149]
	v_pk_mul_f32 v[46:47], v[46:47], v[150:151]
	global_atomic_add_f32 v[130:131], v44, off offset:576
	global_atomic_add_f32 v[130:131], v45, off offset:580
	global_atomic_add_f32 v[130:131], v46, off offset:584
	global_atomic_add_f32 v[130:131], v47, off offset:588
	v_lshl_add_u64 v[130:131], v[130:131], 0, s[98:99]
	v_pk_mul_f32 v[48:49], v[48:49], v[136:137]
	v_pk_mul_f32 v[50:51], v[50:51], v[138:139]
	global_atomic_add_f32 v[130:131], v48, off
	global_atomic_add_f32 v[130:131], v49, off offset:4
	global_atomic_add_f32 v[130:131], v50, off offset:8
	global_atomic_add_f32 v[130:131], v51, off offset:12
	v_pk_mul_f32 v[40:41], v[40:41], v[140:141]
	v_pk_mul_f32 v[42:43], v[42:43], v[142:143]
	global_atomic_add_f32 v[130:131], v40, off offset:64
	global_atomic_add_f32 v[130:131], v41, off offset:68
	global_atomic_add_f32 v[130:131], v42, off offset:72
	global_atomic_add_f32 v[130:131], v43, off offset:76
	v_pk_mul_f32 v[36:37], v[36:37], v[144:145]
	v_pk_mul_f32 v[38:39], v[38:39], v[146:147]
	global_atomic_add_f32 v[130:131], v36, off offset:512
	global_atomic_add_f32 v[130:131], v37, off offset:516
	global_atomic_add_f32 v[130:131], v38, off offset:520
	global_atomic_add_f32 v[130:131], v39, off offset:524
	v_pk_mul_f32 v[28:29], v[28:29], v[148:149]
	v_pk_mul_f32 v[30:31], v[30:31], v[150:151]
	global_atomic_add_f32 v[130:131], v28, off offset:576
	global_atomic_add_f32 v[130:131], v29, off offset:580
	global_atomic_add_f32 v[130:131], v30, off offset:584
	global_atomic_add_f32 v[130:131], v31, off offset:588
	v_lshl_add_u64 v[130:131], v[130:131], 0, s[98:99]
	v_pk_mul_f32 v[32:33], v[32:33], v[136:137]
	v_pk_mul_f32 v[34:35], v[34:35], v[138:139]
	global_atomic_add_f32 v[130:131], v32, off
	global_atomic_add_f32 v[130:131], v33, off offset:4
	global_atomic_add_f32 v[130:131], v34, off offset:8
	global_atomic_add_f32 v[130:131], v35, off offset:12
	v_pk_mul_f32 v[24:25], v[24:25], v[140:141]
	v_pk_mul_f32 v[26:27], v[26:27], v[142:143]
	global_atomic_add_f32 v[130:131], v24, off offset:64
	global_atomic_add_f32 v[130:131], v25, off offset:68
	global_atomic_add_f32 v[130:131], v26, off offset:72
	global_atomic_add_f32 v[130:131], v27, off offset:76
	v_pk_mul_f32 v[20:21], v[20:21], v[144:145]
	v_pk_mul_f32 v[22:23], v[22:23], v[146:147]
	global_atomic_add_f32 v[130:131], v20, off offset:512
	global_atomic_add_f32 v[130:131], v21, off offset:516
	global_atomic_add_f32 v[130:131], v22, off offset:520
	global_atomic_add_f32 v[130:131], v23, off offset:524
	v_pk_mul_f32 v[12:13], v[12:13], v[148:149]
	v_pk_mul_f32 v[14:15], v[14:15], v[150:151]
	global_atomic_add_f32 v[130:131], v12, off offset:576
	global_atomic_add_f32 v[130:131], v13, off offset:580
	global_atomic_add_f32 v[130:131], v14, off offset:584
	global_atomic_add_f32 v[130:131], v15, off offset:588
	v_lshl_add_u64 v[130:131], v[130:131], 0, s[98:99]
	v_pk_mul_f32 v[16:17], v[16:17], v[136:137]
	v_pk_mul_f32 v[18:19], v[18:19], v[138:139]
	global_atomic_add_f32 v[130:131], v16, off
	global_atomic_add_f32 v[130:131], v17, off offset:4
	global_atomic_add_f32 v[130:131], v18, off offset:8
	global_atomic_add_f32 v[130:131], v19, off offset:12
	v_pk_mul_f32 v[8:9], v[8:9], v[140:141]
	v_pk_mul_f32 v[10:11], v[10:11], v[142:143]
	global_atomic_add_f32 v[130:131], v8, off offset:64
	global_atomic_add_f32 v[130:131], v9, off offset:68
	global_atomic_add_f32 v[130:131], v10, off offset:72
	global_atomic_add_f32 v[130:131], v11, off offset:76
	v_pk_mul_f32 v[4:5], v[4:5], v[144:145]
	v_pk_mul_f32 v[6:7], v[6:7], v[146:147]
	global_atomic_add_f32 v[130:131], v4, off offset:512
	global_atomic_add_f32 v[130:131], v5, off offset:516
	global_atomic_add_f32 v[130:131], v6, off offset:520
	global_atomic_add_f32 v[130:131], v7, off offset:524
	v_pk_mul_f32 v[0:1], v[0:1], v[148:149]
	v_pk_mul_f32 v[2:3], v[2:3], v[150:151]
	global_atomic_add_f32 v[130:131], v0, off offset:576
	global_atomic_add_f32 v[130:131], v1, off offset:580
	global_atomic_add_f32 v[130:131], v2, off offset:584
	global_atomic_add_f32 v[130:131], v3, off offset:588
	s_cbranch_scc0 .LBB0_622
	s_barrier
	s_branch .LBB0_622

; #define PG8_STAGE(bufoff, gbase, voff) do { _Pragma("unroll") for (int _i = 0; _i < 2; ++_i) \
;         __builtin_amdgcn_global_load_lds((const unsigned*)((const char*)(gbase) + (size_t)_i * r64##voff + (voff)), (LAS unsigned*)(lds + (bufoff) + ldsw + _i * 8192), 16, 0, 0); } while (0)
; #define PG8_LDA(dst, b, h) do { _Pragma("unroll") for (int m = 0; m < 4; ++m) _Pragma("unroll") for (int k = 0; k < 2; ++k) dst[m][k] = *(const LAS bf16x8*)(lds + PG8_SA(b, h) + aoff + m * 2048 + k * 1024); } while (0)
; #define PG8_LDB(dst, b, h) do { _Pragma("unroll") for (int n = 0; n < 2; ++n) _Pragma("unroll") for (int k = 0; k < 2; ++k) dst[n][k] = *(const LAS bf16x8*)(lds + PG8_SB(b, h) + boff + n * 2048 + k * 1024); } while (0)
; #define PG8_MMA(ai, bj, At, Bt) do { __builtin_amdgcn_s_setprio(1); _Pragma("unroll") for (int m = 0; m < 4; ++m) _Pragma("unroll") for (int n = 0; n < 2; ++n) _Pragma("unroll") for (int k = 0; k < 2; ++k) \
;         acc[ai][bj][m][n] = __builtin_amdgcn_mfma_f32_16x16x32_bf16(Bt[n][k], At[m][k], acc[ai][bj][m][n], 0, 0, 0); __builtin_amdgcn_s_setprio(0); } while (0)
; #define PG8_WAIT_L(n) asm volatile("s_waitcnt lgkmcnt(" #n ")" ::: "memory")
; #define PG8_BAR __builtin_amdgcn_s_barrier()
; #define PG8_SCHED __builtin_amdgcn_sched_barrier(0)
; template <class Epi, class Sched>
; __device__ __forceinline__ void gemm_phase(LAS unsigned char* lds, const Gemm g, const Sched& S, const Epi& E) {
;     ...
;         for (int t = 0; t < nt; t += 2) {
;             const bool last = (t == nt - 2);
;             const char* a1 = cA + (size_t)(t + 1) * kstep;
;             const char* a2 = last ? nA : cA + (size_t)(t + 2) * kstep; const char* b2 = last ? nB : cB + (size_t)(t + 2) * kstep;
;             const char* a3 = a2 + kstep; const char* b3 = b2 + kstep;
;             PG8_LDB(B0, 0, 0); PG8_SCHED; PG8_LDA(At, 0, 0); PG8_STAGE(PG8_SA(1, 1), a1 + hstepA, voffA);
;             PG8_WAIT_L(8); PG8_BAR; PG8_WAIT_L(0); PG8_MMA(0, 0, At, B0); PG8_BAR; PG8_SCHED;
;             PG8_LDB(B1, 0, 1); PG8_STAGE(PG8_SB(0, 0), b2, voffB);
;             PG8_BAR; PG8_WAIT_L(0); PG8_MMA(0, 1, At, B1); PG8_BAR;
;             PG8_LDA(At, 0, 1); PG8_STAGE(PG8_SA(0, 0), a2, voffA);
;             PG8_BAR; PG8_WAIT_L(0); PG8_MMA(1, 0, At, B0); PG8_BAR; PG8_SCHED;
.LBB0_982:
	ds_read_b128 v[136:139], v143
	ds_read_b128 v[146:149], v143 offset:1024
	ds_read_b128 v[150:153], v143 offset:2048
	ds_read_b128 v[154:157], v143 offset:3072
	s_add_u32 s53, s50, 0xfff80080
	s_addc_u32 s71, s51, -1
	s_cmp_eq_u32 s52, 28
	s_cselect_b32 s73, s43, s71
	s_cselect_b32 s72, s49, s53
	s_cselect_b32 s75, s41, s70
	s_cselect_b32 s74, s68, s69
	v_lshl_add_u64 v[140:141], s[50:51], 0, v[130:131]
	s_add_i32 m0, s33, 0xc000
	ds_read_b128 v[158:161], v144
	ds_read_b128 v[162:165], v144 offset:1024
	ds_read_b128 v[166:169], v144 offset:2048
	ds_read_b128 v[170:173], v144 offset:3072
	ds_read_b128 v[174:177], v144 offset:4096
	ds_read_b128 v[178:181], v144 offset:5120
	ds_read_b128 v[182:185], v144 offset:6144
	ds_read_b128 v[186:189], v144 offset:7168
	global_load_lds_dwordx4 v[140:141], off
	v_lshl_add_u64 v[140:141], v[140:141], 0, s[6:7]
	s_add_i32 m0, s33, 0xe000
	s_nop 0
	global_load_lds_dwordx4 v[140:141], off
	s_waitcnt lgkmcnt(8)
	s_barrier
	s_waitcnt lgkmcnt(0)
	s_setprio 1
	s_waitcnt lgkmcnt(0)
	v_mfma_f32_16x16x32_bf16 v[124:127], v[136:139], v[158:161], v[124:127]
	v_mfma_f32_16x16x32_bf16 v[120:123], v[150:153], v[158:161], v[120:123]
	v_mfma_f32_16x16x32_bf16 v[112:115], v[136:139], v[166:169], v[112:115]
	v_mfma_f32_16x16x32_bf16 v[104:107], v[150:153], v[166:169], v[104:107]
	v_mfma_f32_16x16x32_bf16 v[96:99], v[136:139], v[174:177], v[96:99]
	v_mfma_f32_16x16x32_bf16 v[88:91], v[150:153], v[174:177], v[88:91]
	v_mfma_f32_16x16x32_bf16 v[80:83], v[136:139], v[182:185], v[80:83]
	v_mfma_f32_16x16x32_bf16 v[72:75], v[150:153], v[182:185], v[72:75]
	v_mfma_f32_16x16x32_bf16 v[124:127], v[146:149], v[162:165], v[124:127]
	v_mfma_f32_16x16x32_bf16 v[120:123], v[154:157], v[162:165], v[120:123]
	v_mfma_f32_16x16x32_bf16 v[112:115], v[146:149], v[170:173], v[112:115]
	v_mfma_f32_16x16x32_bf16 v[104:107], v[154:157], v[170:173], v[104:107]
	v_mfma_f32_16x16x32_bf16 v[96:99], v[146:149], v[178:181], v[96:99]
	v_mfma_f32_16x16x32_bf16 v[88:91], v[154:157], v[178:181], v[88:91]
	v_mfma_f32_16x16x32_bf16 v[80:83], v[146:149], v[186:189], v[80:83]
	v_mfma_f32_16x16x32_bf16 v[72:75], v[154:157], v[186:189], v[72:75]
	s_setprio 0
	s_barrier
	s_add_i32 s53, s66, s29
	v_lshl_add_u64 v[140:141], s[74:75], 0, v[128:129]
	s_mov_b32 m0, s53
	ds_read_b128 v[190:193], v145
	ds_read_b128 v[194:197], v145 offset:1024
	ds_read_b128 v[198:201], v145 offset:2048
	ds_read_b128 v[202:205], v145 offset:3072
	global_load_lds_dwordx4 v[140:141], off
	v_lshl_add_u64 v[206:207], v[140:141], 0, s[6:7]
	s_add_i32 m0, s53, 0x2000
	s_nop 0
	global_load_lds_dwordx4 v[206:207], off
	s_barrier
	s_waitcnt lgkmcnt(0)
	s_setprio 1
	s_waitcnt lgkmcnt(0)
	v_mfma_f32_16x16x32_bf16 v[116:119], v[190:193], v[158:161], v[116:119]
	v_mfma_f32_16x16x32_bf16 v[108:111], v[198:201], v[158:161], v[108:111]
	v_mfma_f32_16x16x32_bf16 v[100:103], v[190:193], v[166:169], v[100:103]
	v_mfma_f32_16x16x32_bf16 v[92:95], v[198:201], v[166:169], v[92:95]
	v_mfma_f32_16x16x32_bf16 v[84:87], v[190:193], v[174:177], v[84:87]
	v_mfma_f32_16x16x32_bf16 v[76:79], v[198:201], v[174:177], v[76:79]
	v_mfma_f32_16x16x32_bf16 v[68:71], v[190:193], v[182:185], v[68:71]
	v_mfma_f32_16x16x32_bf16 v[64:67], v[198:201], v[182:185], v[64:67]
	v_mfma_f32_16x16x32_bf16 v[116:119], v[194:197], v[162:165], v[116:119]
	v_mfma_f32_16x16x32_bf16 v[108:111], v[202:205], v[162:165], v[108:111]
	v_mfma_f32_16x16x32_bf16 v[100:103], v[194:197], v[170:173], v[100:103]
	v_mfma_f32_16x16x32_bf16 v[92:95], v[202:205], v[170:173], v[92:95]
	v_mfma_f32_16x16x32_bf16 v[84:87], v[194:197], v[178:181], v[84:87]
	v_mfma_f32_16x16x32_bf16 v[76:79], v[202:205], v[178:181], v[76:79]
	v_mfma_f32_16x16x32_bf16 v[68:71], v[194:197], v[186:189], v[68:71]
	v_mfma_f32_16x16x32_bf16 v[64:67], v[202:205], v[186:189], v[64:67]
	s_setprio 0
	s_mov_b32 m0, s33
	v_lshl_add_u64 v[206:207], s[72:73], 0, v[128:129]
	s_barrier
	ds_read_b128 v[158:161], v144 offset:16384
	ds_read_b128 v[162:165], v144 offset:17408
	ds_read_b128 v[166:169], v144 offset:18432
	ds_read_b128 v[170:173], v144 offset:19456
	ds_read_b128 v[174:177], v144 offset:20480
	ds_read_b128 v[178:181], v144 offset:21504
	ds_read_b128 v[182:185], v144 offset:22528
	ds_read_b128 v[186:189], v144 offset:23552
	global_load_lds_dwordx4 v[206:207], off
	v_lshl_add_u64 v[208:209], v[206:207], 0, s[6:7]
	s_mov_b32 m0, s54
	s_nop 0
	global_load_lds_dwordx4 v[208:209], off
	s_barrier
	s_waitcnt lgkmcnt(0)
	s_setprio 1
	s_waitcnt lgkmcnt(0)
	v_mfma_f32_16x16x32_bf16 v[60:63], v[136:139], v[158:161], v[60:63]
	v_mfma_f32_16x16x32_bf16 v[56:59], v[150:153], v[158:161], v[56:59]
	v_mfma_f32_16x16x32_bf16 v[48:51], v[136:139], v[166:169], v[48:51]
	v_mfma_f32_16x16x32_bf16 v[40:43], v[150:153], v[166:169], v[40:43]
	v_mfma_f32_16x16x32_bf16 v[32:35], v[136:139], v[174:177], v[32:35]
	v_mfma_f32_16x16x32_bf16 v[24:27], v[150:153], v[174:177], v[24:27]
	v_mfma_f32_16x16x32_bf16 v[16:19], v[136:139], v[182:185], v[16:19]
	v_mfma_f32_16x16x32_bf16 v[8:11], v[150:153], v[182:185], v[8:11]
	v_mfma_f32_16x16x32_bf16 v[60:63], v[146:149], v[162:165], v[60:63]
	v_mfma_f32_16x16x32_bf16 v[56:59], v[154:157], v[162:165], v[56:59]
	v_mfma_f32_16x16x32_bf16 v[48:51], v[146:149], v[170:173], v[48:51]
	v_mfma_f32_16x16x32_bf16 v[40:43], v[154:157], v[170:173], v[40:43]
	v_mfma_f32_16x16x32_bf16 v[32:35], v[146:149], v[178:181], v[32:35]
	v_mfma_f32_16x16x32_bf16 v[24:27], v[154:157], v[178:181], v[24:27]
	v_mfma_f32_16x16x32_bf16 v[16:19], v[146:149], v[186:189], v[16:19]
	v_mfma_f32_16x16x32_bf16 v[8:11], v[154:157], v[186:189], v[8:11]
	s_setprio 0
	s_barrier
; #define PG8_STAGE(bufoff, gbase, voff) do { _Pragma("unroll") for (int _i = 0; _i < 2; ++_i) \
;         __builtin_amdgcn_global_load_lds((const unsigned*)((const char*)(gbase) + (size_t)_i * r64##voff + (voff)), (LAS unsigned*)(lds + (bufoff) + ldsw + _i * 8192), 16, 0, 0); } while (0)
; #define PG8_LDA(dst, b, h) do { _Pragma("unroll") for (int m = 0; m < 4; ++m) _Pragma("unroll") for (int k = 0; k < 2; ++k) dst[m][k] = *(const LAS bf16x8*)(lds + PG8_SA(b, h) + aoff + m * 2048 + k * 1024); } while (0)
; #define PG8_LDB(dst, b, h) do { _Pragma("unroll") for (int n = 0; n < 2; ++n) _Pragma("unroll") for (int k = 0; k < 2; ++k) dst[n][k] = *(const LAS bf16x8*)(lds + PG8_SB(b, h) + boff + n * 2048 + k * 1024); } while (0)
; #define PG8_MMA(ai, bj, At, Bt) do { __builtin_amdgcn_s_setprio(1); _Pragma("unroll") for (int m = 0; m < 4; ++m) _Pragma("unroll") for (int n = 0; n < 2; ++n) _Pragma("unroll") for (int k = 0; k < 2; ++k) \
;         acc[ai][bj][m][n] = __builtin_amdgcn_mfma_f32_16x16x32_bf16(Bt[n][k], At[m][k], acc[ai][bj][m][n], 0, 0, 0); __builtin_amdgcn_s_setprio(0); } while (0)
; #define PG8_WAIT_V(n) asm volatile("s_waitcnt vmcnt(" #n ")" ::: "memory")
; #define PG8_WAIT_L(n) asm volatile("s_waitcnt lgkmcnt(" #n ")" ::: "memory")
; #define PG8_BAR __builtin_amdgcn_s_barrier()
; #define PG8_SCHED __builtin_amdgcn_sched_barrier(0)
; template <class Epi, class Sched>
; __device__ __forceinline__ void gemm_phase(LAS unsigned char* lds, const Gemm g, const Sched& S, const Epi& E) {
;     ...
;             PG8_STAGE(PG8_SB(0, 1), b2 + hstepB, voffB);
;             PG8_WAIT_V(6); PG8_BAR; PG8_MMA(1, 1, At, B1); PG8_BAR;
;             PG8_LDB(B0, 1, 0); PG8_SCHED; PG8_LDA(At, 1, 0); PG8_STAGE(PG8_SA(0, 1), a2 + hstepA, voffA);
;             PG8_WAIT_L(8); PG8_BAR; PG8_WAIT_L(0); PG8_MMA(0, 0, At, B0); PG8_BAR; PG8_SCHED;
;             PG8_LDB(B1, 1, 1); PG8_STAGE(PG8_SB(1, 0), b3, voffB);
;             PG8_BAR; PG8_WAIT_L(0); PG8_MMA(0, 1, At, B1); PG8_BAR;
;             PG8_LDA(At, 1, 1); PG8_STAGE(PG8_SA(1, 0), a3, voffA);
;             PG8_BAR; PG8_WAIT_L(0); PG8_MMA(1, 0, At, B0); PG8_BAR; PG8_SCHED;
;             PG8_STAGE(PG8_SB(1, 1), b3 + hstepB, voffB);
	s_add_i32 s53, s67, s29
	v_lshl_add_u64 v[136:137], v[140:141], 0, s[8:9]
	s_mov_b32 m0, s53
	s_nop 0
	global_load_lds_dwordx4 v[136:137], off
	v_lshl_add_u64 v[136:137], v[140:141], 0, s[10:11]
	s_add_i32 m0, s53, 0x2000
	s_nop 0
	global_load_lds_dwordx4 v[136:137], off
	s_waitcnt vmcnt(6)
	s_barrier
	s_setprio 1
	v_mfma_f32_16x16x32_bf16 v[52:55], v[190:193], v[158:161], v[52:55]
	v_mfma_f32_16x16x32_bf16 v[44:47], v[198:201], v[158:161], v[44:47]
	v_mfma_f32_16x16x32_bf16 v[36:39], v[190:193], v[166:169], v[36:39]
	v_mfma_f32_16x16x32_bf16 v[28:31], v[198:201], v[166:169], v[28:31]
	v_mfma_f32_16x16x32_bf16 v[20:23], v[190:193], v[174:177], v[20:23]
	v_mfma_f32_16x16x32_bf16 v[12:15], v[198:201], v[174:177], v[12:15]
	v_mfma_f32_16x16x32_bf16 v[4:7], v[190:193], v[182:185], v[4:7]
	v_mfma_f32_16x16x32_bf16 v[0:3], v[198:201], v[182:185], v[0:3]
	v_mfma_f32_16x16x32_bf16 v[52:55], v[194:197], v[162:165], v[52:55]
	v_mfma_f32_16x16x32_bf16 v[44:47], v[202:205], v[162:165], v[44:47]
	v_mfma_f32_16x16x32_bf16 v[36:39], v[194:197], v[170:173], v[36:39]
	v_mfma_f32_16x16x32_bf16 v[28:31], v[202:205], v[170:173], v[28:31]
	v_mfma_f32_16x16x32_bf16 v[20:23], v[194:197], v[178:181], v[20:23]
	v_mfma_f32_16x16x32_bf16 v[12:15], v[202:205], v[178:181], v[12:15]
	v_mfma_f32_16x16x32_bf16 v[4:7], v[194:197], v[186:189], v[4:7]
	v_mfma_f32_16x16x32_bf16 v[0:3], v[202:205], v[186:189], v[0:3]
	s_setprio 0
	s_add_i32 s53, 0, 0x18000
	v_add_u32_e32 v154, s53, v142
	s_barrier
	ds_read_b128 v[136:139], v154
	ds_read_b128 v[146:149], v154 offset:1024
	ds_read_b128 v[150:153], v154 offset:2048
	ds_read_b128 v[154:157], v154 offset:3072
	s_mov_b32 m0, s55
	v_lshl_add_u64 v[190:191], v[206:207], 0, s[8:9]
	ds_read_b128 v[158:161], v144 offset:32768
	ds_read_b128 v[162:165], v144 offset:33792
	ds_read_b128 v[166:169], v144 offset:34816
	ds_read_b128 v[170:173], v144 offset:35840
	ds_read_b128 v[174:177], v144 offset:36864
	ds_read_b128 v[178:181], v144 offset:37888
	ds_read_b128 v[182:185], v144 offset:38912
	ds_read_b128 v[186:189], v144 offset:39936
	global_load_lds_dwordx4 v[190:191], off
	v_lshl_add_u64 v[190:191], v[206:207], 0, s[10:11]
	s_mov_b32 m0, s56
	s_nop 0
	global_load_lds_dwordx4 v[190:191], off
	s_waitcnt lgkmcnt(8)
	s_barrier
	s_waitcnt lgkmcnt(0)
	s_setprio 1
	s_waitcnt lgkmcnt(0)
	v_mfma_f32_16x16x32_bf16 v[124:127], v[136:139], v[158:161], v[124:127]
	v_mfma_f32_16x16x32_bf16 v[120:123], v[150:153], v[158:161], v[120:123]
	v_mfma_f32_16x16x32_bf16 v[112:115], v[136:139], v[166:169], v[112:115]
	v_mfma_f32_16x16x32_bf16 v[104:107], v[150:153], v[166:169], v[104:107]
	v_mfma_f32_16x16x32_bf16 v[96:99], v[136:139], v[174:177], v[96:99]
	v_mfma_f32_16x16x32_bf16 v[88:91], v[150:153], v[174:177], v[88:91]
	v_mfma_f32_16x16x32_bf16 v[80:83], v[136:139], v[182:185], v[80:83]
	v_mfma_f32_16x16x32_bf16 v[72:75], v[150:153], v[182:185], v[72:75]
	v_mfma_f32_16x16x32_bf16 v[124:127], v[146:149], v[162:165], v[124:127]
	v_mfma_f32_16x16x32_bf16 v[120:123], v[154:157], v[162:165], v[120:123]
	v_mfma_f32_16x16x32_bf16 v[112:115], v[146:149], v[170:173], v[112:115]
	v_mfma_f32_16x16x32_bf16 v[104:107], v[154:157], v[170:173], v[104:107]
	v_mfma_f32_16x16x32_bf16 v[96:99], v[146:149], v[178:181], v[96:99]
	v_mfma_f32_16x16x32_bf16 v[88:91], v[154:157], v[178:181], v[88:91]
	v_mfma_f32_16x16x32_bf16 v[80:83], v[146:149], v[186:189], v[80:83]
	v_mfma_f32_16x16x32_bf16 v[72:75], v[154:157], v[186:189], v[72:75]
	s_setprio 0
	s_barrier
	s_add_i32 s71, 0, 0x1c000
	s_add_i32 s53, s53, s29
	v_add_u32_e32 v202, s71, v142
	v_lshl_add_u64 v[208:209], v[140:141], 0, s[20:21]
	s_mov_b32 m0, s53
	ds_read_b128 v[190:193], v202
	ds_read_b128 v[194:197], v202 offset:1024
	ds_read_b128 v[198:201], v202 offset:2048
	ds_read_b128 v[202:205], v202 offset:3072
	global_load_lds_dwordx4 v[208:209], off
	v_lshl_add_u64 v[208:209], v[140:141], 0, s[22:23]
	s_add_i32 m0, s53, 0x2000
	s_nop 0
	global_load_lds_dwordx4 v[208:209], off
	s_barrier
	s_waitcnt lgkmcnt(0)
	s_setprio 1
	s_waitcnt lgkmcnt(0)
	v_mfma_f32_16x16x32_bf16 v[116:119], v[190:193], v[158:161], v[116:119]
	v_mfma_f32_16x16x32_bf16 v[108:111], v[198:201], v[158:161], v[108:111]
	v_mfma_f32_16x16x32_bf16 v[100:103], v[190:193], v[166:169], v[100:103]
	v_mfma_f32_16x16x32_bf16 v[92:95], v[198:201], v[166:169], v[92:95]
	v_mfma_f32_16x16x32_bf16 v[84:87], v[190:193], v[174:177], v[84:87]
	v_mfma_f32_16x16x32_bf16 v[76:79], v[198:201], v[174:177], v[76:79]
	v_mfma_f32_16x16x32_bf16 v[68:71], v[190:193], v[182:185], v[68:71]
	v_mfma_f32_16x16x32_bf16 v[64:67], v[198:201], v[182:185], v[64:67]
	v_mfma_f32_16x16x32_bf16 v[116:119], v[194:197], v[162:165], v[116:119]
	v_mfma_f32_16x16x32_bf16 v[108:111], v[202:205], v[162:165], v[108:111]
	v_mfma_f32_16x16x32_bf16 v[100:103], v[194:197], v[170:173], v[100:103]
	v_mfma_f32_16x16x32_bf16 v[92:95], v[202:205], v[170:173], v[92:95]
	v_mfma_f32_16x16x32_bf16 v[84:87], v[194:197], v[178:181], v[84:87]
	v_mfma_f32_16x16x32_bf16 v[76:79], v[202:205], v[178:181], v[76:79]
	v_mfma_f32_16x16x32_bf16 v[68:71], v[194:197], v[186:189], v[68:71]
	v_mfma_f32_16x16x32_bf16 v[64:67], v[202:205], v[186:189], v[64:67]
	s_setprio 0
	s_mov_b32 m0, s60
	v_lshl_add_u64 v[208:209], v[206:207], 0, s[20:21]
	s_barrier
	ds_read_b128 v[158:161], v144 offset:49152
	ds_read_b128 v[162:165], v144 offset:50176
	ds_read_b128 v[166:169], v144 offset:51200
	ds_read_b128 v[170:173], v144 offset:52224
	ds_read_b128 v[174:177], v144 offset:53248
	ds_read_b128 v[178:181], v144 offset:54272
	ds_read_b128 v[182:185], v144 offset:55296
	ds_read_b128 v[186:189], v144 offset:56320
	global_load_lds_dwordx4 v[208:209], off
	v_lshl_add_u64 v[206:207], v[206:207], 0, s[22:23]
	s_mov_b32 m0, s61
	s_nop 0
	global_load_lds_dwordx4 v[206:207], off
	s_barrier
; #define PG8_STAGE(bufoff, gbase, voff) do { _Pragma("unroll") for (int _i = 0; _i < 2; ++_i) \
;         __builtin_amdgcn_global_load_lds((const unsigned*)((const char*)(gbase) + (size_t)_i * r64##voff + (voff)), (LAS unsigned*)(lds + (bufoff) + ldsw + _i * 8192), 16, 0, 0); } while (0)
; #define PG8_LDA(dst, b, h) do { _Pragma("unroll") for (int m = 0; m < 4; ++m) _Pragma("unroll") for (int k = 0; k < 2; ++k) dst[m][k] = *(const LAS bf16x8*)(lds + PG8_SA(b, h) + aoff + m * 2048 + k * 1024); } while (0)
; #define PG8_WAIT_V(n) asm volatile("s_waitcnt vmcnt(" #n ")" ::: "memory")
; #define PG8_WAIT_L(n) asm volatile("s_waitcnt lgkmcnt(" #n ")" ::: "memory")
; #define PG8_BAR __builtin_amdgcn_s_barrier()
; #define PG8_SCHED __builtin_amdgcn_sched_barrier(0)
; template <class Epi, class Sched>
; __device__ __forceinline__ void gemm_phase(LAS unsigned char* lds, const Gemm g, const Sched& S, const Epi& E) {
;     ...
;             PG8_BAR; PG8_WAIT_L(0); PG8_MMA(0, 1, At, B1); PG8_BAR;
;             PG8_LDA(At, 1, 1); PG8_STAGE(PG8_SA(1, 0), a3, voffA);
;             PG8_BAR; PG8_WAIT_L(0); PG8_MMA(1, 0, At, B0); PG8_BAR; PG8_SCHED;
;             PG8_STAGE(PG8_SB(1, 1), b3 + hstepB, voffB);
;             PG8_WAIT_V(6); PG8_BAR; PG8_MMA(1, 1, At, B1); PG8_BAR;
;         }
;         E(acc, cur, wr, wc, fr, fq);
;     __device__ __forceinline__ void operator()(const f32x4 (&acc)[2][2][4][2], const pg8::Unit& u, int wr_, int wc_, int fr_, int fq_) const {
;     ...
;         const int rbase = u.pm * 256;
;         const bool isc = rbase >= RL;
;         const int mr = isc ? 4 : (rbase >> 12);
;         const float* gate = modsel + (size_t)mr * 12288;
;         const float* src = isc ? srcC - (size_t)RL * 2048 : srcL;
;         float* dst = isc ? dstC - (size_t)RL * 2048 : dstL;
;         const int row0 = rbase + wr * 64 + fr, col0 = u.pn * 256 + wc * 32 + 4 * fq;
; #pragma unroll
;         for (int ai = 0; ai < 2; ++ai)
; #pragma unroll
;             for (int m = 0; m < 4; ++m) { const size_t ro = (size_t)(row0 + ai * 128 + m * 16) * 2048;
; #pragma unroll
;                 for (int bj = 0; bj < 2; ++bj)
; #pragma unroll
;                     for (int n = 0; n < 2; ++n) { const int col = col0 + bj * 128 + n * 16;
;                         const f32x4 gg = *(const f32x4*)(gate + col), s = *(const f32x4*)(src + ro + col);
	s_waitcnt lgkmcnt(0)
	s_setprio 1
	s_waitcnt lgkmcnt(0)
	v_mfma_f32_16x16x32_bf16 v[60:63], v[136:139], v[158:161], v[60:63]
	v_mfma_f32_16x16x32_bf16 v[56:59], v[150:153], v[158:161], v[56:59]
	v_mfma_f32_16x16x32_bf16 v[48:51], v[136:139], v[166:169], v[48:51]
	v_mfma_f32_16x16x32_bf16 v[40:43], v[150:153], v[166:169], v[40:43]
	v_mfma_f32_16x16x32_bf16 v[32:35], v[136:139], v[174:177], v[32:35]
	v_mfma_f32_16x16x32_bf16 v[24:27], v[150:153], v[174:177], v[24:27]
	v_mfma_f32_16x16x32_bf16 v[16:19], v[136:139], v[182:185], v[16:19]
	v_mfma_f32_16x16x32_bf16 v[8:11], v[150:153], v[182:185], v[8:11]
	v_mfma_f32_16x16x32_bf16 v[60:63], v[146:149], v[162:165], v[60:63]
	v_mfma_f32_16x16x32_bf16 v[56:59], v[154:157], v[162:165], v[56:59]
	v_mfma_f32_16x16x32_bf16 v[48:51], v[146:149], v[170:173], v[48:51]
	v_mfma_f32_16x16x32_bf16 v[40:43], v[154:157], v[170:173], v[40:43]
	v_mfma_f32_16x16x32_bf16 v[32:35], v[146:149], v[178:181], v[32:35]
	v_mfma_f32_16x16x32_bf16 v[24:27], v[154:157], v[178:181], v[24:27]
	v_mfma_f32_16x16x32_bf16 v[16:19], v[146:149], v[186:189], v[16:19]
	v_mfma_f32_16x16x32_bf16 v[8:11], v[154:157], v[186:189], v[8:11]
	s_setprio 0
	s_barrier
	s_add_i32 s53, s71, s29
	v_lshl_add_u64 v[136:137], v[140:141], 0, s[24:25]
	s_mov_b32 m0, s53
	s_nop 0
	global_load_lds_dwordx4 v[136:137], off
	v_lshl_add_u64 v[136:137], v[140:141], 0, s[26:27]
	s_add_i32 m0, s53, 0x2000
	s_nop 0
	global_load_lds_dwordx4 v[136:137], off
	s_waitcnt vmcnt(6)
	s_barrier
	s_setprio 1
	v_mfma_f32_16x16x32_bf16 v[52:55], v[190:193], v[158:161], v[52:55]
	v_mfma_f32_16x16x32_bf16 v[44:47], v[198:201], v[158:161], v[44:47]
	v_mfma_f32_16x16x32_bf16 v[36:39], v[190:193], v[166:169], v[36:39]
	v_mfma_f32_16x16x32_bf16 v[28:31], v[198:201], v[166:169], v[28:31]
	v_mfma_f32_16x16x32_bf16 v[20:23], v[190:193], v[174:177], v[20:23]
	v_mfma_f32_16x16x32_bf16 v[12:15], v[198:201], v[174:177], v[12:15]
	v_mfma_f32_16x16x32_bf16 v[4:7], v[190:193], v[182:185], v[4:7]
	v_mfma_f32_16x16x32_bf16 v[0:3], v[198:201], v[182:185], v[0:3]
	v_mfma_f32_16x16x32_bf16 v[52:55], v[194:197], v[162:165], v[52:55]
	v_mfma_f32_16x16x32_bf16 v[44:47], v[202:205], v[162:165], v[44:47]
	v_mfma_f32_16x16x32_bf16 v[36:39], v[194:197], v[170:173], v[36:39]
	v_mfma_f32_16x16x32_bf16 v[28:31], v[202:205], v[170:173], v[28:31]
	v_mfma_f32_16x16x32_bf16 v[20:23], v[194:197], v[178:181], v[20:23]
	v_mfma_f32_16x16x32_bf16 v[12:15], v[202:205], v[178:181], v[12:15]
	v_mfma_f32_16x16x32_bf16 v[4:7], v[194:197], v[186:189], v[4:7]
	v_mfma_f32_16x16x32_bf16 v[0:3], v[202:205], v[186:189], v[0:3]
	s_setprio 0
	s_add_i32 s52, s52, 2
	s_add_u32 s69, s69, 0x100
	s_addc_u32 s70, s70, 0
	s_add_u32 s50, s50, 0x100
	s_addc_u32 s51, s51, 0
	s_cmp_lt_u32 s52, 30
	s_barrier
	s_cbranch_scc1 .LBB0_982
	s_min_i32 s43, s48, 64
	s_ashr_i32 s43, s43, 4
	s_lshl_b32 s41, s48, 8
	s_mul_hi_i32 s49, s43, 0xc000
	s_mul_i32 s43, s43, 0xc000
	v_mov_b32_e32 v137, v222
	s_add_u32 s52, s58, s43
	s_addc_u32 s53, s59, s49
	v_ashrrev_i32_e32 v136, 2, v137
	s_cmp_gt_i32 s48, 63
	v_and_b32_e32 v138, 0xffffffc0, v136
	v_lshrrev_b32_e32 v136, 1, v137
	v_lshrrev_b32_e32 v139, 2, v137
	v_and_or_b32 v137, v137, 15, s41
	s_cselect_b32 s51, s63, s17
	s_cselect_b32 s50, s62, s16
	s_cselect_b32 s49, s65, s19
	s_cselect_b32 s48, s64, s18
	s_lshl_b32 s12, s12, 8
	v_and_b32_e32 v136, 0x60, v136
	v_and_b32_e32 v139, 12, v139
	v_add_u32_e32 v154, v137, v138
	v_or3_b32 v136, v136, s12, v139
	v_ashrrev_i32_e32 v155, 31, v154
	v_ashrrev_i32_e32 v137, 31, v136
	v_lshlrev_b64 v[140:141], 13, v[154:155]
	v_lshlrev_b64 v[138:139], 2, v[136:137]
	v_lshl_add_u64 v[150:151], s[50:51], 0, v[140:141]
	v_lshl_add_u64 v[136:137], s[52:53], 0, v[138:139]
	v_lshl_add_u64 v[156:157], v[150:151], 0, v[138:139]
	v_lshl_add_u64 v[158:159], s[48:49], 0, v[140:141]
	v_lshl_add_u64 v[158:159], v[158:159], 0, v[138:139]
	s_andn2_b64 vcc, exec, s[4:5]
	s_mov_b32 s12, s40
	s_mov_b64 s[52:53], s[44:45]
	s_mov_b64 s[50:51], s[46:47]
	s_mov_b32 s48, s42
	s_mov_b32 s98, 0x20000
	s_mov_b32 s99, 0
	s_mov_b32 s100, 0xa0000
	s_mov_b32 s101, 0
	global_load_dwordx4 v[146:149], v[136:137], off
	global_load_dwordx4 v[160:163], v[136:137], off offset:64
	global_load_dwordx4 v[164:167], v[136:137], off offset:512
	global_load_dwordx4 v[168:171], v[136:137], off offset:576
	global_load_dwordx4 v[172:175], v[156:157], off
	global_load_dwordx4 v[176:179], v[156:157], off offset:64
	global_load_dwordx4 v[180:183], v[156:157], off offset:512
	global_load_dwordx4 v[184:187], v[156:157], off offset:576
	v_lshl_add_u64 v[156:157], v[156:157], 0, s[98:99]
	global_load_dwordx4 v[188:191], v[156:157], off
	global_load_dwordx4 v[192:195], v[156:157], off offset:64
	global_load_dwordx4 v[196:199], v[156:157], off offset:512
	global_load_dwordx4 v[200:203], v[156:157], off offset:576
	v_lshl_add_u64 v[156:157], v[156:157], 0, s[98:99]
	global_load_dwordx4 v[204:207], v[156:157], off
	global_load_dwordx4 v[208:211], v[156:157], off offset:64
	global_load_dwordx4 v[212:215], v[156:157], off offset:512
	global_load_dwordx4 v[216:219], v[156:157], off offset:576
	v_lshl_add_u64 v[156:157], v[156:157], 0, s[98:99]
	global_load_dwordx4 v[224:227], v[156:157], off
	global_load_dwordx4 v[228:231], v[156:157], off offset:64
	global_load_dwordx4 v[232:235], v[156:157], off offset:512
	global_load_dwordx4 v[236:239], v[156:157], off offset:576
	v_lshl_add_u64 v[156:157], v[156:157], 0, s[100:101]
	s_waitcnt vmcnt(0)
;     __device__ __forceinline__ void operator()(const f32x4 (&acc)[2][2][4][2], const pg8::Unit& u, int wr_, int wc_, int fr_, int fq_) const {
;     ...
;         const int rbase = u.pm * 256;
;         const bool isc = rbase >= RL;
;         const int mr = isc ? 4 : (rbase >> 12);
;         const float* gate = modsel + (size_t)mr * 12288;
;         const float* src = isc ? srcC - (size_t)RL * 2048 : srcL;
;         float* dst = isc ? dstC - (size_t)RL * 2048 : dstL;
;         const int row0 = rbase + wr * 64 + fr, col0 = u.pn * 256 + wc * 32 + 4 * fq;
; #pragma unroll
;         for (int ai = 0; ai < 2; ++ai)
; #pragma unroll
;             for (int m = 0; m < 4; ++m) { const size_t ro = (size_t)(row0 + ai * 128 + m * 16) * 2048;
; #pragma unroll
;                 for (int bj = 0; bj < 2; ++bj)
; #pragma unroll
;                     for (int n = 0; n < 2; ++n) { const int col = col0 + bj * 128 + n * 16;
;                         const f32x4 gg = *(const f32x4*)(gate + col), s = *(const f32x4*)(src + ro + col);
;                         *(f32x4*)(dst + ro + col) = s + gg * acc[ai][bj][m][n]; } }
	v_pk_fma_f32 v[124:125], v[124:125], v[146:147], v[172:173]
	v_pk_fma_f32 v[126:127], v[126:127], v[148:149], v[174:175]
	v_pk_fma_f32 v[120:121], v[120:121], v[160:161], v[176:177]
	v_pk_fma_f32 v[122:123], v[122:123], v[162:163], v[178:179]
	v_pk_fma_f32 v[116:117], v[116:117], v[164:165], v[180:181]
	v_pk_fma_f32 v[118:119], v[118:119], v[166:167], v[182:183]
	v_pk_fma_f32 v[108:109], v[108:109], v[168:169], v[184:185]
	v_pk_fma_f32 v[110:111], v[110:111], v[170:171], v[186:187]
	v_pk_fma_f32 v[112:113], v[112:113], v[146:147], v[188:189]
	v_pk_fma_f32 v[114:115], v[114:115], v[148:149], v[190:191]
	v_pk_fma_f32 v[104:105], v[104:105], v[160:161], v[192:193]
	v_pk_fma_f32 v[106:107], v[106:107], v[162:163], v[194:195]
	v_pk_fma_f32 v[100:101], v[100:101], v[164:165], v[196:197]
	v_pk_fma_f32 v[102:103], v[102:103], v[166:167], v[198:199]
	v_pk_fma_f32 v[92:93], v[92:93], v[168:169], v[200:201]
	v_pk_fma_f32 v[94:95], v[94:95], v[170:171], v[202:203]
	v_pk_fma_f32 v[96:97], v[96:97], v[146:147], v[204:205]
	v_pk_fma_f32 v[98:99], v[98:99], v[148:149], v[206:207]
	v_pk_fma_f32 v[88:89], v[88:89], v[160:161], v[208:209]
	v_pk_fma_f32 v[90:91], v[90:91], v[162:163], v[210:211]
	v_pk_fma_f32 v[84:85], v[84:85], v[164:165], v[212:213]
	v_pk_fma_f32 v[86:87], v[86:87], v[166:167], v[214:215]
	v_pk_fma_f32 v[76:77], v[76:77], v[168:169], v[216:217]
	v_pk_fma_f32 v[78:79], v[78:79], v[170:171], v[218:219]
	v_pk_fma_f32 v[80:81], v[80:81], v[146:147], v[224:225]
	v_pk_fma_f32 v[82:83], v[82:83], v[148:149], v[226:227]
	v_pk_fma_f32 v[72:73], v[72:73], v[160:161], v[228:229]
	v_pk_fma_f32 v[74:75], v[74:75], v[162:163], v[230:231]
	v_pk_fma_f32 v[68:69], v[68:69], v[164:165], v[232:233]
	v_pk_fma_f32 v[70:71], v[70:71], v[166:167], v[234:235]
	v_pk_fma_f32 v[64:65], v[64:65], v[168:169], v[236:237]
	v_pk_fma_f32 v[66:67], v[66:67], v[170:171], v[238:239]
	global_load_dwordx4 v[172:175], v[156:157], off
	global_load_dwordx4 v[176:179], v[156:157], off offset:64
	global_load_dwordx4 v[180:183], v[156:157], off offset:512
	global_load_dwordx4 v[184:187], v[156:157], off offset:576
	v_lshl_add_u64 v[156:157], v[156:157], 0, s[98:99]
	global_load_dwordx4 v[188:191], v[156:157], off
	global_load_dwordx4 v[192:195], v[156:157], off offset:64
	global_load_dwordx4 v[196:199], v[156:157], off offset:512
	global_load_dwordx4 v[200:203], v[156:157], off offset:576
	v_lshl_add_u64 v[156:157], v[156:157], 0, s[98:99]
	global_load_dwordx4 v[204:207], v[156:157], off
	global_load_dwordx4 v[208:211], v[156:157], off offset:64
	global_load_dwordx4 v[212:215], v[156:157], off offset:512
	global_load_dwordx4 v[216:219], v[156:157], off offset:576
	v_lshl_add_u64 v[156:157], v[156:157], 0, s[98:99]
	global_load_dwordx4 v[224:227], v[156:157], off
	global_load_dwordx4 v[228:231], v[156:157], off offset:64
	global_load_dwordx4 v[232:235], v[156:157], off offset:512
	global_load_dwordx4 v[236:239], v[156:157], off offset:576
	global_store_dwordx4 v[158:159], v[124:127], off
	global_store_dwordx4 v[158:159], v[120:123], off offset:64
	global_store_dwordx4 v[158:159], v[116:119], off offset:512
	global_store_dwordx4 v[158:159], v[108:111], off offset:576
	v_lshl_add_u64 v[158:159], v[158:159], 0, s[98:99]
	global_store_dwordx4 v[158:159], v[112:115], off
	global_store_dwordx4 v[158:159], v[104:107], off offset:64
	global_store_dwordx4 v[158:159], v[100:103], off offset:512
	global_store_dwordx4 v[158:159], v[92:95], off offset:576
	v_lshl_add_u64 v[158:159], v[158:159], 0, s[98:99]
	global_store_dwordx4 v[158:159], v[96:99], off
	global_store_dwordx4 v[158:159], v[88:91], off offset:64
	global_store_dwordx4 v[158:159], v[84:87], off offset:512
	global_store_dwordx4 v[158:159], v[76:79], off offset:576
	v_lshl_add_u64 v[158:159], v[158:159], 0, s[98:99]
	global_store_dwordx4 v[158:159], v[80:83], off
	global_store_dwordx4 v[158:159], v[72:75], off offset:64
	global_store_dwordx4 v[158:159], v[68:71], off offset:512
	global_store_dwordx4 v[158:159], v[64:67], off offset:576
	v_lshl_add_u64 v[158:159], v[158:159], 0, s[100:101]
	s_waitcnt vmcnt(16)
	v_pk_fma_f32 v[60:61], v[60:61], v[146:147], v[172:173]
	v_pk_fma_f32 v[62:63], v[62:63], v[148:149], v[174:175]
	v_pk_fma_f32 v[56:57], v[56:57], v[160:161], v[176:177]
	v_pk_fma_f32 v[58:59], v[58:59], v[162:163], v[178:179]
	v_pk_fma_f32 v[52:53], v[52:53], v[164:165], v[180:181]
	v_pk_fma_f32 v[54:55], v[54:55], v[166:167], v[182:183]
	v_pk_fma_f32 v[44:45], v[44:45], v[168:169], v[184:185]
	v_pk_fma_f32 v[46:47], v[46:47], v[170:171], v[186:187]
	v_pk_fma_f32 v[48:49], v[48:49], v[146:147], v[188:189]
	v_pk_fma_f32 v[50:51], v[50:51], v[148:149], v[190:191]
	v_pk_fma_f32 v[40:41], v[40:41], v[160:161], v[192:193]
	v_pk_fma_f32 v[42:43], v[42:43], v[162:163], v[194:195]
	v_pk_fma_f32 v[36:37], v[36:37], v[164:165], v[196:197]
	v_pk_fma_f32 v[38:39], v[38:39], v[166:167], v[198:199]
	v_pk_fma_f32 v[28:29], v[28:29], v[168:169], v[200:201]
	v_pk_fma_f32 v[30:31], v[30:31], v[170:171], v[202:203]
	v_pk_fma_f32 v[32:33], v[32:33], v[146:147], v[204:205]
	v_pk_fma_f32 v[34:35], v[34:35], v[148:149], v[206:207]
	v_pk_fma_f32 v[24:25], v[24:25], v[160:161], v[208:209]
	v_pk_fma_f32 v[26:27], v[26:27], v[162:163], v[210:211]
	v_pk_fma_f32 v[20:21], v[20:21], v[164:165], v[212:213]
	v_pk_fma_f32 v[22:23], v[22:23], v[166:167], v[214:215]
	v_pk_fma_f32 v[12:13], v[12:13], v[168:169], v[216:217]
	v_pk_fma_f32 v[14:15], v[14:15], v[170:171], v[218:219]
	v_pk_fma_f32 v[16:17], v[16:17], v[146:147], v[224:225]
	v_pk_fma_f32 v[18:19], v[18:19], v[148:149], v[226:227]
	v_pk_fma_f32 v[8:9], v[8:9], v[160:161], v[228:229]
	v_pk_fma_f32 v[10:11], v[10:11], v[162:163], v[230:231]
	v_pk_fma_f32 v[4:5], v[4:5], v[164:165], v[232:233]
	v_pk_fma_f32 v[6:7], v[6:7], v[166:167], v[234:235]
	v_pk_fma_f32 v[0:1], v[0:1], v[168:169], v[236:237]
	v_pk_fma_f32 v[2:3], v[2:3], v[170:171], v[238:239]
	global_store_dwordx4 v[158:159], v[60:63], off
	global_store_dwordx4 v[158:159], v[56:59], off offset:64
	global_store_dwordx4 v[158:159], v[52:55], off offset:512
	global_store_dwordx4 v[158:159], v[44:47], off offset:576
	v_lshl_add_u64 v[158:159], v[158:159], 0, s[98:99]
	global_store_dwordx4 v[158:159], v[48:51], off
	global_store_dwordx4 v[158:159], v[40:43], off offset:64
	global_store_dwordx4 v[158:159], v[36:39], off offset:512
	global_store_dwordx4 v[158:159], v[28:31], off offset:576
	v_lshl_add_u64 v[158:159], v[158:159], 0, s[98:99]
	global_store_dwordx4 v[158:159], v[32:35], off
	global_store_dwordx4 v[158:159], v[24:27], off offset:64
	global_store_dwordx4 v[158:159], v[20:23], off offset:512
	global_store_dwordx4 v[158:159], v[12:15], off offset:576
	v_lshl_add_u64 v[158:159], v[158:159], 0, s[98:99]
	global_store_dwordx4 v[158:159], v[16:19], off
	global_store_dwordx4 v[158:159], v[8:11], off offset:64
	global_store_dwordx4 v[158:159], v[4:7], off offset:512
	global_store_dwordx4 v[158:159], v[0:3], off offset:576
	s_cbranch_vccnz .LBB0_975
	s_waitcnt vmcnt(0)
	s_cmpk_gt_u32 s2, 0xff
	s_cbranch_scc1 .LBB0_986
	s_barrier

; __device__ __forceinline__ unsigned cvt_pk_bf16(float lo, float hi) { unsigned r; asm("v_cvt_pk_bf16_f32 %0, %1, %2" : "=v"(r) : "v"(lo), "v"(hi)); return r; }
; #define mod ((const float*)(getp().ws + O_MOD))
; #define hL (layer == 0 ? getp().in[0] : (const float*)getp().out)
; #define hC (layer == 0 ? getp().in[2] : (const float*)hctx)
; __device__ __forceinline__ void xn_row(const float* hrow, const float* g, const float* shift, const float* scale, bf16_t* orow, int lane) {
;     const float4* xr = (const float4*)hrow + lane;
;     float4 v[8]; float s = 0.f;
; #pragma unroll
;     for (int j = 0; j < 8; ++j) { v[j] = xr[64 * j]; s += v[j].x * v[j].x + v[j].y * v[j].y + v[j].z * v[j].z + v[j].w * v[j].w; }
;     const float r = rsqrtf(wave_sum(s) * (1.f / D) + 1e-6f);
;     u32x2* o = (u32x2*)orow + lane;
; #pragma unroll
;     for (int j = 0; j < 8; ++j) { const float4 gg = ((const float4*)g)[lane + 64 * j], sh = ((const float4*)shift)[lane + 64 * j], sc = ((const float4*)scale)[lane + 64 * j];
;         u32x2 w; w.x = cvt_pk_bf16(v[j].x * r * gg.x * (1.f + sc.x) + sh.x, v[j].y * r * gg.y * (1.f + sc.y) + sh.y);
;         w.y = cvt_pk_bf16(v[j].z * r * gg.z * (1.f + sc.z) + sh.z, v[j].w * r * gg.w * (1.f + sc.w) + sh.w);
;         o[64 * j] = w; }
; }
; __device__ __forceinline__ void xn_row1(PRef p, int layer, int which  , int row, int lane, const float* hL, const float* hC) {
;     const float* mod = (const float*)(p.ws + O_MOD);
;     const bool isc = row >= RL; const int mr = isc ? 4 : (row >> 12);
;     const float* m = mod + (size_t)(layer * 5 + mr) * 12288 + (which ? 3 * 2048 : 0);
;     const float* hrow = isc ? hC + (size_t)(row - RL) * 2048 : hL + (size_t)row * 2048;
;     xn_row(hrow, p.in[which ? 29 : 6] + layer * 2048, m, m + 2048, (bf16_t*)(p.ws + O_XN) + (size_t)row * 2048, lane);
.LBB0_1001:
	s_mov_b64 s[18:19], s[0:1]
	s_mov_b64 s[20:21], s[0:1]
	s_load_dwordx2 s[20:21], s[20:21], 0x118
	v_ashrrev_i32_e32 v33, 31, v32
	v_lshlrev_b64 v[0:1], 13, v[32:33]
	s_mov_b64 s[22:23], s[0:1]
	s_waitcnt lgkmcnt(0)
	v_lshl_add_u64 v[0:1], s[20:21], 0, v[0:1]
	v_lshl_add_u64 v[0:1], v[0:1], 0, v[34:35]
	v_add_co_u32_e32 v52, vcc, s2, v0
	global_load_dwordx4 v[28:31], v[0:1], off
	global_load_dwordx4 v[24:27], v[0:1], off offset:1024
	global_load_dwordx4 v[20:23], v[0:1], off offset:2048
	global_load_dwordx4 v[16:19], v[0:1], off offset:3072
	v_addc_co_u32_e32 v53, vcc, 0, v1, vcc
	global_load_dwordx4 v[12:15], v[52:53], off
	global_load_dwordx4 v[8:11], v[52:53], off offset:1024
	global_load_dwordx4 v[4:7], v[52:53], off offset:2048
	global_load_dwordx4 v[0:3], v[52:53], off offset:3072
	s_load_dwordx2 s[22:23], s[18:19], 0xe8
	s_load_dwordx2 s[20:21], s[18:19], 0x120
	v_ashrrev_i32_e32 v52, 12, v32
	v_cmp_lt_i32_e32 vcc, v58, v57
	v_add_u32_e32 v52, 5, v52
	s_waitcnt lgkmcnt(0)
	s_add_u32 s18, s22, 0x2000
	v_cndmask_b32_e32 v53, v56, v58, vcc
	v_lshlrev_b32_e32 v65, 2, v53
	v_mul_hi_i32_i24_e32 v53, 0xc000, v52
	v_mul_i32_i24_e32 v52, 0xc000, v52
	v_lshl_add_u64 v[54:55], s[20:21], 0, v[52:53]
	v_lshl_add_u64 v[52:53], v[54:55], 0, s[8:9]
	s_addc_u32 s19, s23, 0
	v_lshl_add_u64 v[54:55], v[54:55], 0, s[10:11]
	v_lshl_add_u64 v[78:79], v[52:53], 0, v[34:35]
	global_load_dwordx4 v[66:69], v34, s[18:19]
	v_lshl_add_u64 v[80:81], v[54:55], 0, v[34:35]
	global_load_dwordx4 v[70:73], v[78:79], off
	global_load_dwordx4 v[74:77], v[80:81], off
	global_load_dwordx4 v[100:103], v38, s[18:19]
	v_lshl_add_u64 v[98:99], v[54:55], 0, v[38:39]
	global_load_dwordx4 v[104:107], v[98:99], off
	v_lshl_add_u64 v[98:99], v[52:53], 0, v[38:39]
	global_load_dwordx4 v[108:111], v[98:99], off
	global_load_dwordx4 v[112:115], v40, s[18:19]
	v_lshl_add_u64 v[98:99], v[54:55], 0, v[40:41]
	global_load_dwordx4 v[116:119], v[98:99], off
	v_lshl_add_u64 v[98:99], v[52:53], 0, v[40:41]
	global_load_dwordx4 v[120:123], v[98:99], off
	global_load_dwordx4 v[124:127], v42, s[18:19]
	v_lshl_add_u64 v[98:99], v[54:55], 0, v[42:43]
	global_load_dwordx4 v[128:131], v[98:99], off
	v_lshl_add_u64 v[98:99], v[52:53], 0, v[42:43]
	global_load_dwordx4 v[132:135], v[98:99], off
	global_load_dwordx4 v[136:139], v44, s[18:19]
	v_lshl_add_u64 v[98:99], v[54:55], 0, v[44:45]
	global_load_dwordx4 v[140:143], v[98:99], off
	v_lshl_add_u64 v[98:99], v[52:53], 0, v[44:45]
	global_load_dwordx4 v[144:147], v[98:99], off
	global_load_dwordx4 v[148:151], v46, s[18:19]
	v_lshl_add_u64 v[98:99], v[54:55], 0, v[46:47]
	global_load_dwordx4 v[152:155], v[98:99], off
	v_lshl_add_u64 v[98:99], v[52:53], 0, v[46:47]
	global_load_dwordx4 v[156:159], v[98:99], off
	global_load_dwordx4 v[160:163], v48, s[18:19]
	v_lshl_add_u64 v[98:99], v[54:55], 0, v[48:49]
	global_load_dwordx4 v[164:167], v[98:99], off
	v_lshl_add_u64 v[98:99], v[52:53], 0, v[48:49]
	global_load_dwordx4 v[168:171], v[98:99], off
	global_load_dwordx4 v[172:175], v50, s[18:19]
	v_lshl_add_u64 v[98:99], v[54:55], 0, v[50:51]
	global_load_dwordx4 v[176:179], v[98:99], off
	v_lshl_add_u64 v[98:99], v[52:53], 0, v[50:51]
	global_load_dwordx4 v[180:183], v[98:99], off
	v_cmp_lt_i32_e32 vcc, v59, v57
	s_waitcnt vmcnt(31)
	v_mul_f32_e32 v94, v29, v29
	s_waitcnt vmcnt(30)
	v_mul_f32_e32 v95, v25, v25
	s_waitcnt vmcnt(29)
	v_mul_f32_e32 v96, v21, v21
	v_fmac_f32_e32 v94, v28, v28
	v_fmac_f32_e32 v95, v24, v24
	s_waitcnt vmcnt(28)
	v_mul_f32_e32 v97, v17, v17
	v_fmac_f32_e32 v96, v20, v20
	s_waitcnt vmcnt(27)
	v_mov_b32_e32 v80, v13
	s_waitcnt vmcnt(26)
	v_mov_b32_e32 v81, v9
	s_waitcnt vmcnt(25)
	v_mov_b32_e32 v88, v5
	s_waitcnt vmcnt(24)
	v_mov_b32_e32 v89, v1
	v_fmac_f32_e32 v94, v30, v30
	v_fmac_f32_e32 v95, v26, v26
	v_fmac_f32_e32 v97, v16, v16
	v_mov_b32_e32 v78, v12
	v_mov_b32_e32 v79, v8
	v_mov_b32_e32 v86, v4
	v_mov_b32_e32 v87, v0
	v_fmac_f32_e32 v96, v22, v22
	v_pk_mul_f32 v[80:81], v[80:81], v[80:81]
	v_pk_mul_f32 v[88:89], v[88:89], v[88:89]
	v_fmac_f32_e32 v94, v31, v31
	v_fmac_f32_e32 v95, v27, v27
	v_mov_b32_e32 v82, v14
	v_mov_b32_e32 v83, v10
	v_fmac_f32_e32 v97, v18, v18
	v_fmac_f32_e32 v96, v23, v23
	v_pk_fma_f32 v[78:79], v[78:79], v[78:79], v[80:81]
	v_pk_fma_f32 v[80:81], v[86:87], v[86:87], v[88:89]
	v_add_f32_e32 v86, v94, v95
	v_mov_b32_e32 v84, v15
	v_mov_b32_e32 v85, v11
	v_fmac_f32_e32 v97, v19, v19
	v_pk_fma_f32 v[78:79], v[82:83], v[82:83], v[78:79]
	v_add_f32_e32 v82, v86, v96
	v_mov_b32_e32 v90, v6
	v_mov_b32_e32 v91, v2
	v_pk_fma_f32 v[78:79], v[84:85], v[84:85], v[78:79]
	v_add_f32_e32 v82, v82, v97
	v_mov_b32_e32 v92, v7
	v_mov_b32_e32 v93, v3
	v_pk_fma_f32 v[80:81], v[90:91], v[90:91], v[80:81]
	v_add_f32_e32 v78, v82, v78
	v_pk_fma_f32 v[80:81], v[92:93], v[92:93], v[80:81]
	v_add_f32_e32 v78, v78, v79
	v_add_f32_e32 v78, v78, v80
	v_add_f32_e32 v78, v78, v81
	ds_bpermute_b32 v65, v65, v78
	v_cndmask_b32_e32 v79, v56, v59, vcc
	v_lshlrev_b32_e32 v79, 2, v79
	v_cmp_lt_i32_e32 vcc, v60, v57
	s_waitcnt vmcnt(21)
	v_add_f32_e32 v74, 1.0, v74
	s_waitcnt lgkmcnt(0)
	v_add_f32_e32 v65, v78, v65
	ds_bpermute_b32 v78, v79, v65
	v_cndmask_b32_e32 v79, v56, v60, vcc
	v_lshlrev_b32_e32 v79, 2, v79
	v_cmp_lt_i32_e32 vcc, v61, v57
	v_lshl_add_u64 v[82:83], v[54:55], 0, v[38:39]
	s_waitcnt lgkmcnt(0)
	v_add_f32_e32 v65, v65, v78
	ds_bpermute_b32 v78, v79, v65
	v_cndmask_b32_e32 v79, v56, v61, vcc
	v_lshlrev_b32_e32 v79, 2, v79
	v_cmp_lt_i32_e32 vcc, v62, v57
	s_waitcnt lgkmcnt(0)
	v_add_f32_e32 v65, v65, v78
	ds_bpermute_b32 v78, v79, v65
	v_cndmask_b32_e32 v79, v56, v62, vcc
	v_lshlrev_b32_e32 v79, 2, v79
	v_cmp_lt_i32_e32 vcc, v63, v57
	s_waitcnt lgkmcnt(0)
; __device__ __forceinline__ unsigned cvt_pk_bf16(float lo, float hi) { unsigned r; asm("v_cvt_pk_bf16_f32 %0, %1, %2" : "=v"(r) : "v"(lo), "v"(hi)); return r; }
; __device__ __forceinline__ void xn_row(const float* hrow, const float* g, const float* shift, const float* scale, bf16_t* orow, int lane) {
;     ...
;     const float r = rsqrtf(wave_sum(s) * (1.f / D) + 1e-6f);
;     u32x2* o = (u32x2*)orow + lane;
; #pragma unroll
;     for (int j = 0; j < 8; ++j) { const float4 gg = ((const float4*)g)[lane + 64 * j], sh = ((const float4*)shift)[lane + 64 * j], sc = ((const float4*)scale)[lane + 64 * j];
;         u32x2 w; w.x = cvt_pk_bf16(v[j].x * r * gg.x * (1.f + sc.x) + sh.x, v[j].y * r * gg.y * (1.f + sc.y) + sh.y);
;         w.y = cvt_pk_bf16(v[j].z * r * gg.z * (1.f + sc.z) + sh.z, v[j].w * r * gg.w * (1.f + sc.w) + sh.w);
;         o[64 * j] = w; }
	v_add_f32_e32 v65, v65, v78
	ds_bpermute_b32 v81, v79, v65
	v_cndmask_b32_e32 v80, v56, v63, vcc
	v_lshlrev_b64 v[78:79], 12, v[32:33]
	v_lshlrev_b32_e32 v33, 2, v80
	v_lshl_add_u64 v[78:79], s[20:21], 0, v[78:79]
	s_waitcnt lgkmcnt(0)
	v_add_f32_e32 v65, v65, v81
	ds_bpermute_b32 v33, v33, v65
	v_lshl_add_u64 v[78:79], v[78:79], 0, v[36:37]
	v_add_co_u32_e32 v80, vcc, s12, v78
	v_add_u32_e32 v32, s86, v32
	s_waitcnt lgkmcnt(0)
	v_add_f32_e32 v33, v65, v33
	v_addc_co_u32_e32 v81, vcc, 0, v79, vcc
	v_fmamk_f32 v33, v33, 0x3a000000, v64
	v_mul_f32_e32 v65, 0x4b800000, v33
	v_cmp_gt_f32_e32 vcc, s3, v33
	s_nop 1
	v_cndmask_b32_e32 v33, v33, v65, vcc
	v_rsq_f32_e32 v33, v33
	v_add_f32_e32 v65, 1.0, v75
	v_add_f32_e32 v75, 1.0, v76
	v_add_f32_e32 v76, 1.0, v77
	v_mul_f32_e32 v77, 0x45800000, v33
	v_cndmask_b32_e32 v33, v33, v77, vcc
	v_mul_f32_e32 v28, v28, v33
	v_mul_f32_e32 v29, v29, v33
	v_mul_f32_e32 v30, v30, v33
	v_mul_f32_e32 v31, v31, v33
	v_mul_f32_e32 v28, v66, v28
	v_mul_f32_e32 v29, v67, v29
	v_mul_f32_e32 v30, v68, v30
	v_mul_f32_e32 v31, v69, v31
	v_fma_f32 v28, v74, v28, v70
	v_fma_f32 v29, v65, v29, v71
	v_fma_f32 v30, v30, v75, v72
	v_fmac_f32_e32 v73, v31, v76
	v_cvt_pk_bf16_f32 v28, v28, v29
	v_cvt_pk_bf16_f32 v29, v30, v73
	global_store_dwordx2 v[80:81], v[28:29], off
	v_mul_f32_e32 v24, v24, v33
	v_mul_f32_e32 v25, v25, v33
	v_mul_f32_e32 v26, v26, v33
	v_mul_f32_e32 v27, v27, v33
	v_lshl_add_u64 v[28:29], v[78:79], 0, s[16:17]
	v_mul_f32_e32 v20, v20, v33
	v_mul_f32_e32 v21, v21, v33
	v_mul_f32_e32 v22, v22, v33
	v_mul_f32_e32 v23, v23, v33
	v_mul_f32_e32 v16, v16, v33
	v_mul_f32_e32 v17, v17, v33
	v_mul_f32_e32 v18, v18, v33
	v_mul_f32_e32 v19, v19, v33
	v_mul_f32_e32 v12, v12, v33
	v_mul_f32_e32 v13, v13, v33
	v_mul_f32_e32 v14, v14, v33
	v_mul_f32_e32 v15, v15, v33
	v_mul_f32_e32 v8, v8, v33
	v_mul_f32_e32 v9, v9, v33
	v_mul_f32_e32 v10, v10, v33
	v_mul_f32_e32 v11, v11, v33
	v_mul_f32_e32 v4, v4, v33
	v_mul_f32_e32 v5, v5, v33
	v_mul_f32_e32 v6, v6, v33
	v_mul_f32_e32 v7, v7, v33
	v_mul_f32_e32 v0, v0, v33
	v_mul_f32_e32 v1, v1, v33
	v_cmp_lt_i32_e32 vcc, s13, v32
	v_mul_f32_e32 v2, v2, v33
	v_mul_f32_e32 v3, v3, v33
	s_or_b64 s[6:7], vcc, s[6:7]
	s_waitcnt vmcnt(18)
	v_mul_f32_e32 v24, v24, v100
	v_mul_f32_e32 v25, v25, v101
	v_mul_f32_e32 v26, v26, v102
	v_mul_f32_e32 v27, v27, v103
	v_add_f32_e32 v104, 1.0, v104
	v_add_f32_e32 v105, 1.0, v105
	v_add_f32_e32 v106, 1.0, v106
	v_add_f32_e32 v107, 1.0, v107
	v_fma_f32 v24, v24, v104, v108
	v_fma_f32 v25, v25, v105, v109
	v_fma_f32 v26, v26, v106, v110
	v_fma_f32 v27, v27, v107, v111
	v_cvt_pk_bf16_f32 v24, v24, v25
	v_cvt_pk_bf16_f32 v25, v26, v27
	global_store_dwordx2 v[28:29], v[24:25], off offset:512
	s_waitcnt vmcnt(15)
	v_mul_f32_e32 v20, v20, v112
	v_mul_f32_e32 v21, v21, v113
	v_mul_f32_e32 v22, v22, v114
	v_mul_f32_e32 v23, v23, v115
	v_add_f32_e32 v116, 1.0, v116
	v_add_f32_e32 v117, 1.0, v117
	v_add_f32_e32 v118, 1.0, v118
	v_add_f32_e32 v119, 1.0, v119
	v_fma_f32 v20, v20, v116, v120
	v_fma_f32 v21, v21, v117, v121
	v_fma_f32 v22, v22, v118, v122
	v_fma_f32 v23, v23, v119, v123
	v_cvt_pk_bf16_f32 v20, v20, v21
	v_cvt_pk_bf16_f32 v21, v22, v23
	global_store_dwordx2 v[28:29], v[20:21], off offset:1024
	s_waitcnt vmcnt(12)
	v_mul_f32_e32 v16, v16, v124
	v_mul_f32_e32 v17, v17, v125
	v_mul_f32_e32 v18, v18, v126
	v_mul_f32_e32 v19, v19, v127
	v_add_f32_e32 v128, 1.0, v128
	v_add_f32_e32 v129, 1.0, v129
	v_add_f32_e32 v130, 1.0, v130
	v_add_f32_e32 v131, 1.0, v131
	v_fma_f32 v16, v16, v128, v132
	v_fma_f32 v17, v17, v129, v133
	v_fma_f32 v18, v18, v130, v134
	v_fma_f32 v19, v19, v131, v135
	v_cvt_pk_bf16_f32 v16, v16, v17
	v_cvt_pk_bf16_f32 v17, v18, v19
	global_store_dwordx2 v[28:29], v[16:17], off offset:1536
	s_waitcnt vmcnt(9)
	v_mul_f32_e32 v12, v12, v136
	v_mul_f32_e32 v13, v13, v137
	v_mul_f32_e32 v14, v14, v138
	v_mul_f32_e32 v15, v15, v139
	v_add_f32_e32 v140, 1.0, v140
	v_add_f32_e32 v141, 1.0, v141
	v_add_f32_e32 v142, 1.0, v142
	v_add_f32_e32 v143, 1.0, v143
	v_fma_f32 v12, v12, v140, v144
	v_fma_f32 v13, v13, v141, v145
	v_fma_f32 v14, v14, v142, v146
	v_fma_f32 v15, v15, v143, v147
	v_cvt_pk_bf16_f32 v12, v12, v13
	v_cvt_pk_bf16_f32 v13, v14, v15
	global_store_dwordx2 v[28:29], v[12:13], off offset:2048
	s_waitcnt vmcnt(6)
	v_mul_f32_e32 v8, v8, v148
	v_mul_f32_e32 v9, v9, v149
	v_mul_f32_e32 v10, v10, v150
	v_mul_f32_e32 v11, v11, v151
	v_add_f32_e32 v152, 1.0, v152
	v_add_f32_e32 v153, 1.0, v153
	v_add_f32_e32 v154, 1.0, v154
	v_add_f32_e32 v155, 1.0, v155
	v_fma_f32 v8, v8, v152, v156
	v_fma_f32 v9, v9, v153, v157
	v_fma_f32 v10, v10, v154, v158
	v_fma_f32 v11, v11, v155, v159
	v_cvt_pk_bf16_f32 v8, v8, v9
	v_cvt_pk_bf16_f32 v9, v10, v11
	global_store_dwordx2 v[28:29], v[8:9], off offset:2560
	s_waitcnt vmcnt(3)
	v_mul_f32_e32 v4, v4, v160
	v_mul_f32_e32 v5, v5, v161
	v_mul_f32_e32 v6, v6, v162
	v_mul_f32_e32 v7, v7, v163
	v_add_f32_e32 v164, 1.0, v164
	v_add_f32_e32 v165, 1.0, v165
	v_add_f32_e32 v166, 1.0, v166
	v_add_f32_e32 v167, 1.0, v167
	v_fma_f32 v4, v4, v164, v168
	v_fma_f32 v5, v5, v165, v169
	v_fma_f32 v6, v6, v166, v170
	v_fma_f32 v7, v7, v167, v171
	v_cvt_pk_bf16_f32 v4, v4, v5
	v_cvt_pk_bf16_f32 v5, v6, v7
	global_store_dwordx2 v[28:29], v[4:5], off offset:3072
	s_waitcnt vmcnt(0)
	v_mul_f32_e32 v0, v0, v172
	v_mul_f32_e32 v1, v1, v173
	v_mul_f32_e32 v2, v2, v174
	v_mul_f32_e32 v3, v3, v175
	v_add_f32_e32 v176, 1.0, v176
	v_add_f32_e32 v177, 1.0, v177
	v_add_f32_e32 v178, 1.0, v178
	v_add_f32_e32 v179, 1.0, v179
	v_fma_f32 v0, v0, v176, v180
	v_fma_f32 v1, v1, v177, v181
	v_fma_f32 v2, v2, v178, v182
	v_fma_f32 v3, v3, v179, v183
	v_cvt_pk_bf16_f32 v0, v0, v1
	v_cvt_pk_bf16_f32 v1, v2, v3
	global_store_dwordx2 v[28:29], v[0:1], off offset:3584
	s_andn2_b64 exec, exec, s[6:7]
	s_cbranch_execnz .LBB0_1001

; #define PG8_STAGE(bufoff, gbase, voff) do { _Pragma("unroll") for (int _i = 0; _i < 2; ++_i) \
;         __builtin_amdgcn_global_load_lds((const unsigned*)((const char*)(gbase) + (size_t)_i * r64##voff + (voff)), (LAS unsigned*)(lds + (bufoff) + ldsw + _i * 8192), 16, 0, 0); } while (0)
; #define PG8_LDA(dst, b, h) do { _Pragma("unroll") for (int m = 0; m < 4; ++m) _Pragma("unroll") for (int k = 0; k < 2; ++k) dst[m][k] = *(const LAS bf16x8*)(lds + PG8_SA(b, h) + aoff + m * 2048 + k * 1024); } while (0)
; #define PG8_LDB(dst, b, h) do { _Pragma("unroll") for (int n = 0; n < 2; ++n) _Pragma("unroll") for (int k = 0; k < 2; ++k) dst[n][k] = *(const LAS bf16x8*)(lds + PG8_SB(b, h) + boff + n * 2048 + k * 1024); } while (0)
; #define PG8_MMA(ai, bj, At, Bt) do { __builtin_amdgcn_s_setprio(1); _Pragma("unroll") for (int m = 0; m < 4; ++m) _Pragma("unroll") for (int n = 0; n < 2; ++n) _Pragma("unroll") for (int k = 0; k < 2; ++k) \
;         acc[ai][bj][m][n] = __builtin_amdgcn_mfma_f32_16x16x32_bf16(Bt[n][k], At[m][k], acc[ai][bj][m][n], 0, 0, 0); __builtin_amdgcn_s_setprio(0); } while (0)
; #define PG8_WAIT_L(n) asm volatile("s_waitcnt lgkmcnt(" #n ")" ::: "memory")
; #define PG8_BAR __builtin_amdgcn_s_barrier()
; #define PG8_SCHED __builtin_amdgcn_sched_barrier(0)
; template <class Epi, class Sched>
; __device__ __forceinline__ void gemm_phase(LAS unsigned char* lds, const Gemm g, const Sched& S, const Epi& E) {
;     ...
;         for (int t = 0; t < nt; t += 2) {
;             const bool last = (t == nt - 2);
;             const char* a1 = cA + (size_t)(t + 1) * kstep;
;             const char* a2 = last ? nA : cA + (size_t)(t + 2) * kstep; const char* b2 = last ? nB : cB + (size_t)(t + 2) * kstep;
;             const char* a3 = a2 + kstep; const char* b3 = b2 + kstep;
;             PG8_LDB(B0, 0, 0); PG8_SCHED; PG8_LDA(At, 0, 0); PG8_STAGE(PG8_SA(1, 1), a1 + hstepA, voffA);
;             PG8_WAIT_L(8); PG8_BAR; PG8_WAIT_L(0); PG8_MMA(0, 0, At, B0); PG8_BAR; PG8_SCHED;
;             PG8_LDB(B1, 0, 1); PG8_STAGE(PG8_SB(0, 0), b2, voffB);
;             PG8_BAR; PG8_WAIT_L(0); PG8_MMA(0, 1, At, B1); PG8_BAR;
;             PG8_LDA(At, 0, 1); PG8_STAGE(PG8_SA(0, 0), a2, voffA);
;             PG8_BAR; PG8_WAIT_L(0); PG8_MMA(1, 0, At, B0); PG8_BAR; PG8_SCHED;
.LBB0_1106:
	ds_read_b128 v[138:141], v145
	ds_read_b128 v[148:151], v145 offset:1024
	ds_read_b128 v[152:155], v145 offset:2048
	ds_read_b128 v[156:159], v145 offset:3072
	s_add_u32 s45, s42, 0xffd40080
	s_addc_u32 s69, s43, -1
	s_cmpk_eq_i32 s44, 0x54
	s_cselect_b32 s71, s5, s69
	s_cselect_b32 s70, s4, s45
	s_cselect_b32 s73, s7, s68
	s_cselect_b32 s72, s6, s67
	v_lshl_add_u64 v[142:143], s[42:43], 0, v[132:133]
	s_add_i32 m0, s49, 0xc000
	ds_read_b128 v[160:163], v146
	ds_read_b128 v[164:167], v146 offset:1024
	ds_read_b128 v[168:171], v146 offset:2048
	ds_read_b128 v[172:175], v146 offset:3072
	ds_read_b128 v[176:179], v146 offset:4096
	ds_read_b128 v[180:183], v146 offset:5120
	ds_read_b128 v[184:187], v146 offset:6144
	ds_read_b128 v[188:191], v146 offset:7168
	global_load_lds_dwordx4 v[142:143], off
	v_lshl_add_u64 v[142:143], v[142:143], 0, s[10:11]
	s_add_i32 m0, s49, 0xe000
	s_nop 0
	global_load_lds_dwordx4 v[142:143], off
	s_waitcnt lgkmcnt(8)
	s_barrier
	s_waitcnt lgkmcnt(0)
	s_setprio 1
	s_waitcnt lgkmcnt(0)
	v_mfma_f32_16x16x32_bf16 v[124:127], v[138:141], v[160:163], v[124:127]
	v_mfma_f32_16x16x32_bf16 v[120:123], v[152:155], v[160:163], v[120:123]
	v_mfma_f32_16x16x32_bf16 v[112:115], v[138:141], v[168:171], v[112:115]
	v_mfma_f32_16x16x32_bf16 v[104:107], v[152:155], v[168:171], v[104:107]
	v_mfma_f32_16x16x32_bf16 v[96:99], v[138:141], v[176:179], v[96:99]
	v_mfma_f32_16x16x32_bf16 v[88:91], v[152:155], v[176:179], v[88:91]
	v_mfma_f32_16x16x32_bf16 v[80:83], v[138:141], v[184:187], v[80:83]
	v_mfma_f32_16x16x32_bf16 v[72:75], v[152:155], v[184:187], v[72:75]
	v_mfma_f32_16x16x32_bf16 v[124:127], v[148:151], v[164:167], v[124:127]
	v_mfma_f32_16x16x32_bf16 v[120:123], v[156:159], v[164:167], v[120:123]
	v_mfma_f32_16x16x32_bf16 v[112:115], v[148:151], v[172:175], v[112:115]
	v_mfma_f32_16x16x32_bf16 v[104:107], v[156:159], v[172:175], v[104:107]
	v_mfma_f32_16x16x32_bf16 v[96:99], v[148:151], v[180:183], v[96:99]
	v_mfma_f32_16x16x32_bf16 v[88:91], v[156:159], v[180:183], v[88:91]
	v_mfma_f32_16x16x32_bf16 v[80:83], v[148:151], v[188:191], v[80:83]
	v_mfma_f32_16x16x32_bf16 v[72:75], v[156:159], v[188:191], v[72:75]
	s_setprio 0
	s_barrier
	s_add_i32 s45, s62, s48
	v_lshl_add_u64 v[142:143], s[72:73], 0, v[128:129]
	s_mov_b32 m0, s45
	ds_read_b128 v[192:195], v147
	ds_read_b128 v[196:199], v147 offset:1024
	ds_read_b128 v[200:203], v147 offset:2048
	ds_read_b128 v[204:207], v147 offset:3072
	global_load_lds_dwordx4 v[142:143], off
	v_lshl_add_u64 v[208:209], v[142:143], 0, s[8:9]
	s_add_i32 m0, s45, 0x2000
	s_nop 0
	global_load_lds_dwordx4 v[208:209], off
	s_barrier
	s_waitcnt lgkmcnt(0)
	s_setprio 1
	s_waitcnt lgkmcnt(0)
	v_mfma_f32_16x16x32_bf16 v[116:119], v[192:195], v[160:163], v[116:119]
	v_mfma_f32_16x16x32_bf16 v[108:111], v[200:203], v[160:163], v[108:111]
	v_mfma_f32_16x16x32_bf16 v[100:103], v[192:195], v[168:171], v[100:103]
	v_mfma_f32_16x16x32_bf16 v[92:95], v[200:203], v[168:171], v[92:95]
	v_mfma_f32_16x16x32_bf16 v[84:87], v[192:195], v[176:179], v[84:87]
	v_mfma_f32_16x16x32_bf16 v[76:79], v[200:203], v[176:179], v[76:79]
	v_mfma_f32_16x16x32_bf16 v[68:71], v[192:195], v[184:187], v[68:71]
	v_mfma_f32_16x16x32_bf16 v[64:67], v[200:203], v[184:187], v[64:67]
	v_mfma_f32_16x16x32_bf16 v[116:119], v[196:199], v[164:167], v[116:119]
	v_mfma_f32_16x16x32_bf16 v[108:111], v[204:207], v[164:167], v[108:111]
	v_mfma_f32_16x16x32_bf16 v[100:103], v[196:199], v[172:175], v[100:103]
	v_mfma_f32_16x16x32_bf16 v[92:95], v[204:207], v[172:175], v[92:95]
	v_mfma_f32_16x16x32_bf16 v[84:87], v[196:199], v[180:183], v[84:87]
	v_mfma_f32_16x16x32_bf16 v[76:79], v[204:207], v[180:183], v[76:79]
	v_mfma_f32_16x16x32_bf16 v[68:71], v[196:199], v[188:191], v[68:71]
	v_mfma_f32_16x16x32_bf16 v[64:67], v[204:207], v[188:191], v[64:67]
	s_setprio 0
	s_mov_b32 m0, s49
	v_lshl_add_u64 v[208:209], s[70:71], 0, v[130:131]
	s_barrier
	ds_read_b128 v[160:163], v146 offset:16384
	ds_read_b128 v[164:167], v146 offset:17408
	ds_read_b128 v[168:171], v146 offset:18432
	ds_read_b128 v[172:175], v146 offset:19456
	ds_read_b128 v[176:179], v146 offset:20480
	ds_read_b128 v[180:183], v146 offset:21504
	ds_read_b128 v[184:187], v146 offset:22528
	ds_read_b128 v[188:191], v146 offset:23552
	global_load_lds_dwordx4 v[208:209], off
	v_lshl_add_u64 v[210:211], v[208:209], 0, s[10:11]
	s_mov_b32 m0, s50
	s_nop 0
	global_load_lds_dwordx4 v[210:211], off
	s_barrier
	s_waitcnt lgkmcnt(0)
	s_setprio 1
	s_waitcnt lgkmcnt(0)
	v_mfma_f32_16x16x32_bf16 v[60:63], v[138:141], v[160:163], v[60:63]
	v_mfma_f32_16x16x32_bf16 v[56:59], v[152:155], v[160:163], v[56:59]
	v_mfma_f32_16x16x32_bf16 v[48:51], v[138:141], v[168:171], v[48:51]
	v_mfma_f32_16x16x32_bf16 v[40:43], v[152:155], v[168:171], v[40:43]
	v_mfma_f32_16x16x32_bf16 v[32:35], v[138:141], v[176:179], v[32:35]
	v_mfma_f32_16x16x32_bf16 v[24:27], v[152:155], v[176:179], v[24:27]
	v_mfma_f32_16x16x32_bf16 v[16:19], v[138:141], v[184:187], v[16:19]
	v_mfma_f32_16x16x32_bf16 v[8:11], v[152:155], v[184:187], v[8:11]
	v_mfma_f32_16x16x32_bf16 v[60:63], v[148:151], v[164:167], v[60:63]
	v_mfma_f32_16x16x32_bf16 v[56:59], v[156:159], v[164:167], v[56:59]
	v_mfma_f32_16x16x32_bf16 v[48:51], v[148:151], v[172:175], v[48:51]
	v_mfma_f32_16x16x32_bf16 v[40:43], v[156:159], v[172:175], v[40:43]
	v_mfma_f32_16x16x32_bf16 v[32:35], v[148:151], v[180:183], v[32:35]
	v_mfma_f32_16x16x32_bf16 v[24:27], v[156:159], v[180:183], v[24:27]
	v_mfma_f32_16x16x32_bf16 v[16:19], v[148:151], v[188:191], v[16:19]
	v_mfma_f32_16x16x32_bf16 v[8:11], v[156:159], v[188:191], v[8:11]
	s_setprio 0
	s_barrier
; #define PG8_STAGE(bufoff, gbase, voff) do { _Pragma("unroll") for (int _i = 0; _i < 2; ++_i) \
;         __builtin_amdgcn_global_load_lds((const unsigned*)((const char*)(gbase) + (size_t)_i * r64##voff + (voff)), (LAS unsigned*)(lds + (bufoff) + ldsw + _i * 8192), 16, 0, 0); } while (0)
; #define PG8_LDA(dst, b, h) do { _Pragma("unroll") for (int m = 0; m < 4; ++m) _Pragma("unroll") for (int k = 0; k < 2; ++k) dst[m][k] = *(const LAS bf16x8*)(lds + PG8_SA(b, h) + aoff + m * 2048 + k * 1024); } while (0)
; #define PG8_LDB(dst, b, h) do { _Pragma("unroll") for (int n = 0; n < 2; ++n) _Pragma("unroll") for (int k = 0; k < 2; ++k) dst[n][k] = *(const LAS bf16x8*)(lds + PG8_SB(b, h) + boff + n * 2048 + k * 1024); } while (0)
; #define PG8_MMA(ai, bj, At, Bt) do { __builtin_amdgcn_s_setprio(1); _Pragma("unroll") for (int m = 0; m < 4; ++m) _Pragma("unroll") for (int n = 0; n < 2; ++n) _Pragma("unroll") for (int k = 0; k < 2; ++k) \
;         acc[ai][bj][m][n] = __builtin_amdgcn_mfma_f32_16x16x32_bf16(Bt[n][k], At[m][k], acc[ai][bj][m][n], 0, 0, 0); __builtin_amdgcn_s_setprio(0); } while (0)
; #define PG8_WAIT_V(n) asm volatile("s_waitcnt vmcnt(" #n ")" ::: "memory")
; #define PG8_WAIT_L(n) asm volatile("s_waitcnt lgkmcnt(" #n ")" ::: "memory")
; #define PG8_BAR __builtin_amdgcn_s_barrier()
; #define PG8_SCHED __builtin_amdgcn_sched_barrier(0)
; template <class Epi, class Sched>
; __device__ __forceinline__ void gemm_phase(LAS unsigned char* lds, const Gemm g, const Sched& S, const Epi& E) {
;     ...
;             PG8_STAGE(PG8_SB(0, 1), b2 + hstepB, voffB);
;             PG8_WAIT_V(6); PG8_BAR; PG8_MMA(1, 1, At, B1); PG8_BAR;
;             PG8_LDB(B0, 1, 0); PG8_SCHED; PG8_LDA(At, 1, 0); PG8_STAGE(PG8_SA(0, 1), a2 + hstepA, voffA);
;             PG8_WAIT_L(8); PG8_BAR; PG8_WAIT_L(0); PG8_MMA(0, 0, At, B0); PG8_BAR; PG8_SCHED;
;             PG8_LDB(B1, 1, 1); PG8_STAGE(PG8_SB(1, 0), b3, voffB);
;             PG8_BAR; PG8_WAIT_L(0); PG8_MMA(0, 1, At, B1); PG8_BAR;
;             PG8_LDA(At, 1, 1); PG8_STAGE(PG8_SA(1, 0), a3, voffA);
;             PG8_BAR; PG8_WAIT_L(0); PG8_MMA(1, 0, At, B0); PG8_BAR; PG8_SCHED;
;             PG8_STAGE(PG8_SB(1, 1), b3 + hstepB, voffB);
	s_add_i32 s45, s63, s48
	v_lshl_add_u64 v[138:139], v[142:143], 0, s[10:11]
	s_mov_b32 m0, s45
	s_nop 0
	global_load_lds_dwordx4 v[138:139], off
	v_lshl_add_u64 v[138:139], v[142:143], 0, s[16:17]
	s_add_i32 m0, s45, 0x2000
	s_nop 0
	global_load_lds_dwordx4 v[138:139], off
	s_waitcnt vmcnt(6)
	s_barrier
	s_setprio 1
	v_mfma_f32_16x16x32_bf16 v[52:55], v[192:195], v[160:163], v[52:55]
	v_mfma_f32_16x16x32_bf16 v[44:47], v[200:203], v[160:163], v[44:47]
	v_mfma_f32_16x16x32_bf16 v[36:39], v[192:195], v[168:171], v[36:39]
	v_mfma_f32_16x16x32_bf16 v[28:31], v[200:203], v[168:171], v[28:31]
	v_mfma_f32_16x16x32_bf16 v[20:23], v[192:195], v[176:179], v[20:23]
	v_mfma_f32_16x16x32_bf16 v[12:15], v[200:203], v[176:179], v[12:15]
	v_mfma_f32_16x16x32_bf16 v[4:7], v[192:195], v[184:187], v[4:7]
	v_mfma_f32_16x16x32_bf16 v[0:3], v[200:203], v[184:187], v[0:3]
	v_mfma_f32_16x16x32_bf16 v[52:55], v[196:199], v[164:167], v[52:55]
	v_mfma_f32_16x16x32_bf16 v[44:47], v[204:207], v[164:167], v[44:47]
	v_mfma_f32_16x16x32_bf16 v[36:39], v[196:199], v[172:175], v[36:39]
	v_mfma_f32_16x16x32_bf16 v[28:31], v[204:207], v[172:175], v[28:31]
	v_mfma_f32_16x16x32_bf16 v[20:23], v[196:199], v[180:183], v[20:23]
	v_mfma_f32_16x16x32_bf16 v[12:15], v[204:207], v[180:183], v[12:15]
	v_mfma_f32_16x16x32_bf16 v[4:7], v[196:199], v[188:191], v[4:7]
	v_mfma_f32_16x16x32_bf16 v[0:3], v[204:207], v[188:191], v[0:3]
	s_setprio 0
	s_add_i32 s45, 0, 0x18000
	v_add_u32_e32 v156, s45, v144
	s_barrier
	ds_read_b128 v[138:141], v156
	ds_read_b128 v[148:151], v156 offset:1024
	ds_read_b128 v[152:155], v156 offset:2048
	ds_read_b128 v[156:159], v156 offset:3072
	s_mov_b32 m0, s51
	v_lshl_add_u64 v[192:193], v[208:209], 0, s[18:19]
	ds_read_b128 v[160:163], v146 offset:32768
	ds_read_b128 v[164:167], v146 offset:33792
	ds_read_b128 v[168:171], v146 offset:34816
	ds_read_b128 v[172:175], v146 offset:35840
	ds_read_b128 v[176:179], v146 offset:36864
	ds_read_b128 v[180:183], v146 offset:37888
	ds_read_b128 v[184:187], v146 offset:38912
	ds_read_b128 v[188:191], v146 offset:39936
	global_load_lds_dwordx4 v[192:193], off
	v_lshl_add_u64 v[192:193], v[208:209], 0, s[20:21]
	s_mov_b32 m0, s52
	s_nop 0
	global_load_lds_dwordx4 v[192:193], off
	s_waitcnt lgkmcnt(8)
	s_barrier
	s_waitcnt lgkmcnt(0)
	s_setprio 1
	s_waitcnt lgkmcnt(0)
	v_mfma_f32_16x16x32_bf16 v[124:127], v[138:141], v[160:163], v[124:127]
	v_mfma_f32_16x16x32_bf16 v[120:123], v[152:155], v[160:163], v[120:123]
	v_mfma_f32_16x16x32_bf16 v[112:115], v[138:141], v[168:171], v[112:115]
	v_mfma_f32_16x16x32_bf16 v[104:107], v[152:155], v[168:171], v[104:107]
	v_mfma_f32_16x16x32_bf16 v[96:99], v[138:141], v[176:179], v[96:99]
	v_mfma_f32_16x16x32_bf16 v[88:91], v[152:155], v[176:179], v[88:91]
	v_mfma_f32_16x16x32_bf16 v[80:83], v[138:141], v[184:187], v[80:83]
	v_mfma_f32_16x16x32_bf16 v[72:75], v[152:155], v[184:187], v[72:75]
	v_mfma_f32_16x16x32_bf16 v[124:127], v[148:151], v[164:167], v[124:127]
	v_mfma_f32_16x16x32_bf16 v[120:123], v[156:159], v[164:167], v[120:123]
	v_mfma_f32_16x16x32_bf16 v[112:115], v[148:151], v[172:175], v[112:115]
	v_mfma_f32_16x16x32_bf16 v[104:107], v[156:159], v[172:175], v[104:107]
	v_mfma_f32_16x16x32_bf16 v[96:99], v[148:151], v[180:183], v[96:99]
	v_mfma_f32_16x16x32_bf16 v[88:91], v[156:159], v[180:183], v[88:91]
	v_mfma_f32_16x16x32_bf16 v[80:83], v[148:151], v[188:191], v[80:83]
	v_mfma_f32_16x16x32_bf16 v[72:75], v[156:159], v[188:191], v[72:75]
	s_setprio 0
	s_barrier
	s_add_i32 s69, 0, 0x1c000
	s_add_i32 s45, s45, s48
	v_add_u32_e32 v204, s69, v144
	v_lshl_add_u64 v[210:211], v[142:143], 0, s[26:27]
	s_mov_b32 m0, s45
	ds_read_b128 v[192:195], v204
	ds_read_b128 v[196:199], v204 offset:1024
	ds_read_b128 v[200:203], v204 offset:2048
	ds_read_b128 v[204:207], v204 offset:3072
	global_load_lds_dwordx4 v[210:211], off
	v_lshl_add_u64 v[210:211], v[142:143], 0, s[28:29]
	s_add_i32 m0, s45, 0x2000
	s_nop 0
	global_load_lds_dwordx4 v[210:211], off
	s_barrier
	s_waitcnt lgkmcnt(0)
	s_setprio 1
	s_waitcnt lgkmcnt(0)
	v_mfma_f32_16x16x32_bf16 v[116:119], v[192:195], v[160:163], v[116:119]
	v_mfma_f32_16x16x32_bf16 v[108:111], v[200:203], v[160:163], v[108:111]
	v_mfma_f32_16x16x32_bf16 v[100:103], v[192:195], v[168:171], v[100:103]
	v_mfma_f32_16x16x32_bf16 v[92:95], v[200:203], v[168:171], v[92:95]
	v_mfma_f32_16x16x32_bf16 v[84:87], v[192:195], v[176:179], v[84:87]
	v_mfma_f32_16x16x32_bf16 v[76:79], v[200:203], v[176:179], v[76:79]
	v_mfma_f32_16x16x32_bf16 v[68:71], v[192:195], v[184:187], v[68:71]
	v_mfma_f32_16x16x32_bf16 v[64:67], v[200:203], v[184:187], v[64:67]
	v_mfma_f32_16x16x32_bf16 v[116:119], v[196:199], v[164:167], v[116:119]
	v_mfma_f32_16x16x32_bf16 v[108:111], v[204:207], v[164:167], v[108:111]
	v_mfma_f32_16x16x32_bf16 v[100:103], v[196:199], v[172:175], v[100:103]
	v_mfma_f32_16x16x32_bf16 v[92:95], v[204:207], v[172:175], v[92:95]
	v_mfma_f32_16x16x32_bf16 v[84:87], v[196:199], v[180:183], v[84:87]
	v_mfma_f32_16x16x32_bf16 v[76:79], v[204:207], v[180:183], v[76:79]
	v_mfma_f32_16x16x32_bf16 v[68:71], v[196:199], v[188:191], v[68:71]
	v_mfma_f32_16x16x32_bf16 v[64:67], v[204:207], v[188:191], v[64:67]
	s_setprio 0
	s_mov_b32 m0, s56
	v_lshl_add_u64 v[210:211], v[208:209], 0, s[26:27]
	s_barrier
	ds_read_b128 v[160:163], v146 offset:49152
	ds_read_b128 v[164:167], v146 offset:50176
	ds_read_b128 v[168:171], v146 offset:51200
	ds_read_b128 v[172:175], v146 offset:52224
	ds_read_b128 v[176:179], v146 offset:53248
	ds_read_b128 v[180:183], v146 offset:54272
	ds_read_b128 v[184:187], v146 offset:55296
	ds_read_b128 v[188:191], v146 offset:56320
	global_load_lds_dwordx4 v[210:211], off
	v_lshl_add_u64 v[208:209], v[208:209], 0, s[30:31]
	s_mov_b32 m0, s57
	s_nop 0
	global_load_lds_dwordx4 v[208:209], off
	s_barrier
; #define PG8_STAGE(bufoff, gbase, voff) do { _Pragma("unroll") for (int _i = 0; _i < 2; ++_i) \
;         __builtin_amdgcn_global_load_lds((const unsigned*)((const char*)(gbase) + (size_t)_i * r64##voff + (voff)), (LAS unsigned*)(lds + (bufoff) + ldsw + _i * 8192), 16, 0, 0); } while (0)
; #define PG8_LDA(dst, b, h) do { _Pragma("unroll") for (int m = 0; m < 4; ++m) _Pragma("unroll") for (int k = 0; k < 2; ++k) dst[m][k] = *(const LAS bf16x8*)(lds + PG8_SA(b, h) + aoff + m * 2048 + k * 1024); } while (0)
; #define PG8_WAIT_V(n) asm volatile("s_waitcnt vmcnt(" #n ")" ::: "memory")
; #define PG8_WAIT_L(n) asm volatile("s_waitcnt lgkmcnt(" #n ")" ::: "memory")
; #define PG8_BAR __builtin_amdgcn_s_barrier()
; #define PG8_SCHED __builtin_amdgcn_sched_barrier(0)
; template <class Epi, class Sched>
; __device__ __forceinline__ void gemm_phase(LAS unsigned char* lds, const Gemm g, const Sched& S, const Epi& E) {
;     ...
;             PG8_BAR; PG8_WAIT_L(0); PG8_MMA(0, 1, At, B1); PG8_BAR;
;             PG8_LDA(At, 1, 1); PG8_STAGE(PG8_SA(1, 0), a3, voffA);
;             PG8_BAR; PG8_WAIT_L(0); PG8_MMA(1, 0, At, B0); PG8_BAR; PG8_SCHED;
;             PG8_STAGE(PG8_SB(1, 1), b3 + hstepB, voffB);
;             PG8_WAIT_V(6); PG8_BAR; PG8_MMA(1, 1, At, B1); PG8_BAR;
;         }
;         E(acc, cur, wr, wc, fr, fq);
;     __device__ __forceinline__ void operator()(const f32x4 (&acc)[2][2][4][2], const pg8::Unit& u, int wr_, int wc_, int fr_, int fq_) const {
;     ...
;         const int rbase = u.pm * 256;
;         const bool isc = rbase >= RL;
;         const int mr = isc ? 4 : (rbase >> 12);
;         const float* gate = modsel + (size_t)mr * 12288;
;         const float* src = isc ? srcC - (size_t)RL * 2048 : srcL;
;         float* dst = isc ? dstC - (size_t)RL * 2048 : dstL;
;         const int row0 = rbase + wr * 64 + fr, col0 = u.pn * 256 + wc * 32 + 4 * fq;
; #pragma unroll
;         for (int ai = 0; ai < 2; ++ai)
; #pragma unroll
;             for (int m = 0; m < 4; ++m) { const size_t ro = (size_t)(row0 + ai * 128 + m * 16) * 2048;
; #pragma unroll
;                 for (int bj = 0; bj < 2; ++bj)
; #pragma unroll
;                     for (int n = 0; n < 2; ++n) { const int col = col0 + bj * 128 + n * 16;
;                         const f32x4 gg = *(const f32x4*)(gate + col), s = *(const f32x4*)(src + ro + col);
	s_waitcnt lgkmcnt(0)
	s_setprio 1
	s_waitcnt lgkmcnt(0)
	v_mfma_f32_16x16x32_bf16 v[60:63], v[138:141], v[160:163], v[60:63]
	v_mfma_f32_16x16x32_bf16 v[56:59], v[152:155], v[160:163], v[56:59]
	v_mfma_f32_16x16x32_bf16 v[48:51], v[138:141], v[168:171], v[48:51]
	v_mfma_f32_16x16x32_bf16 v[40:43], v[152:155], v[168:171], v[40:43]
	v_mfma_f32_16x16x32_bf16 v[32:35], v[138:141], v[176:179], v[32:35]
	v_mfma_f32_16x16x32_bf16 v[24:27], v[152:155], v[176:179], v[24:27]
	v_mfma_f32_16x16x32_bf16 v[16:19], v[138:141], v[184:187], v[16:19]
	v_mfma_f32_16x16x32_bf16 v[8:11], v[152:155], v[184:187], v[8:11]
	v_mfma_f32_16x16x32_bf16 v[60:63], v[148:151], v[164:167], v[60:63]
	v_mfma_f32_16x16x32_bf16 v[56:59], v[156:159], v[164:167], v[56:59]
	v_mfma_f32_16x16x32_bf16 v[48:51], v[148:151], v[172:175], v[48:51]
	v_mfma_f32_16x16x32_bf16 v[40:43], v[156:159], v[172:175], v[40:43]
	v_mfma_f32_16x16x32_bf16 v[32:35], v[148:151], v[180:183], v[32:35]
	v_mfma_f32_16x16x32_bf16 v[24:27], v[156:159], v[180:183], v[24:27]
	v_mfma_f32_16x16x32_bf16 v[16:19], v[148:151], v[188:191], v[16:19]
	v_mfma_f32_16x16x32_bf16 v[8:11], v[156:159], v[188:191], v[8:11]
	s_setprio 0
	s_barrier
	s_add_i32 s45, s69, s48
	v_lshl_add_u64 v[138:139], v[142:143], 0, s[30:31]
	s_mov_b32 m0, s45
	s_nop 0
	global_load_lds_dwordx4 v[138:139], off
	v_lshl_add_u64 v[138:139], v[142:143], 0, s[34:35]
	s_add_i32 m0, s45, 0x2000
	s_nop 0
	global_load_lds_dwordx4 v[138:139], off
	s_waitcnt vmcnt(6)
	s_barrier
	s_setprio 1
	v_mfma_f32_16x16x32_bf16 v[52:55], v[192:195], v[160:163], v[52:55]
	v_mfma_f32_16x16x32_bf16 v[44:47], v[200:203], v[160:163], v[44:47]
	v_mfma_f32_16x16x32_bf16 v[36:39], v[192:195], v[168:171], v[36:39]
	v_mfma_f32_16x16x32_bf16 v[28:31], v[200:203], v[168:171], v[28:31]
	v_mfma_f32_16x16x32_bf16 v[20:23], v[192:195], v[176:179], v[20:23]
	v_mfma_f32_16x16x32_bf16 v[12:15], v[200:203], v[176:179], v[12:15]
	v_mfma_f32_16x16x32_bf16 v[4:7], v[192:195], v[184:187], v[4:7]
	v_mfma_f32_16x16x32_bf16 v[0:3], v[200:203], v[184:187], v[0:3]
	v_mfma_f32_16x16x32_bf16 v[52:55], v[196:199], v[164:167], v[52:55]
	v_mfma_f32_16x16x32_bf16 v[44:47], v[204:207], v[164:167], v[44:47]
	v_mfma_f32_16x16x32_bf16 v[36:39], v[196:199], v[172:175], v[36:39]
	v_mfma_f32_16x16x32_bf16 v[28:31], v[204:207], v[172:175], v[28:31]
	v_mfma_f32_16x16x32_bf16 v[20:23], v[196:199], v[180:183], v[20:23]
	v_mfma_f32_16x16x32_bf16 v[12:15], v[204:207], v[180:183], v[12:15]
	v_mfma_f32_16x16x32_bf16 v[4:7], v[196:199], v[188:191], v[4:7]
	v_mfma_f32_16x16x32_bf16 v[0:3], v[204:207], v[188:191], v[0:3]
	s_setprio 0
	s_add_i32 s44, s44, 2
	s_add_u32 s67, s67, 0x100
	s_addc_u32 s68, s68, 0
	s_add_u32 s42, s42, 0x100
	s_addc_u32 s43, s43, 0
	s_cmpk_lt_u32 s44, 0x56
	s_barrier
	s_cbranch_scc1 .LBB0_1106
	s_min_i32 s42, s66, 64
	s_ashr_i32 s42, s42, 4
	s_lshl_b32 s67, s66, 8
	s_mul_hi_i32 s43, s42, 0xc000
	s_mul_i32 s42, s42, 0xc000
	v_mov_b32_e32 v139, v222
	s_add_u32 s68, s54, s42
	s_addc_u32 s69, s55, s43
	v_ashrrev_i32_e32 v138, 2, v139
	s_cmp_gt_i32 s66, 63
	v_and_b32_e32 v140, 0xffffffc0, v138
	v_lshrrev_b32_e32 v138, 1, v139
	v_lshrrev_b32_e32 v141, 2, v139
	v_and_or_b32 v139, v139, 15, s67
	s_cselect_b32 s45, s59, s23
	s_cselect_b32 s44, s58, s22
	s_cselect_b32 s43, s61, s25
	s_cselect_b32 s42, s60, s24
	s_lshl_b32 s12, s12, 8
	v_and_b32_e32 v138, 0x60, v138
	v_and_b32_e32 v141, 12, v141
	v_add_u32_e32 v156, v139, v140
	v_or3_b32 v138, v138, s12, v141
	v_ashrrev_i32_e32 v157, 31, v156
	v_ashrrev_i32_e32 v139, 31, v138
	v_lshlrev_b64 v[142:143], 13, v[156:157]
	v_lshlrev_b64 v[140:141], 2, v[138:139]
	v_lshl_add_u64 v[152:153], s[44:45], 0, v[142:143]
	v_lshl_add_u64 v[138:139], s[68:69], 0, v[140:141]
	v_lshl_add_u64 v[158:159], v[152:153], 0, v[140:141]
	v_lshl_add_u64 v[160:161], s[42:43], 0, v[142:143]
	v_lshl_add_u64 v[160:161], v[160:161], 0, v[140:141]
	s_mov_b32 s66, s65
	s_andn2_b64 vcc, exec, s[2:3]
	s_mov_b32 s12, s64
	s_mov_b64 s[44:45], s[4:5]
	s_mov_b64 s[42:43], s[6:7]
	s_mov_b32 s98, 0x20000
	s_mov_b32 s99, 0
	s_mov_b32 s100, 0xa0000
	s_mov_b32 s101, 0
	global_load_dwordx4 v[148:151], v[138:139], off
	global_load_dwordx4 v[162:165], v[138:139], off offset:64
	global_load_dwordx4 v[166:169], v[138:139], off offset:512
	global_load_dwordx4 v[170:173], v[138:139], off offset:576
	global_load_dwordx4 v[174:177], v[158:159], off
	global_load_dwordx4 v[178:181], v[158:159], off offset:64
	global_load_dwordx4 v[182:185], v[158:159], off offset:512
	global_load_dwordx4 v[186:189], v[158:159], off offset:576
	v_lshl_add_u64 v[158:159], v[158:159], 0, s[98:99]
	global_load_dwordx4 v[190:193], v[158:159], off
	global_load_dwordx4 v[194:197], v[158:159], off offset:64
	global_load_dwordx4 v[198:201], v[158:159], off offset:512
	global_load_dwordx4 v[202:205], v[158:159], off offset:576
	v_lshl_add_u64 v[158:159], v[158:159], 0, s[98:99]
	global_load_dwordx4 v[206:209], v[158:159], off
	global_load_dwordx4 v[210:213], v[158:159], off offset:64
	global_load_dwordx4 v[214:217], v[158:159], off offset:512
	global_load_dwordx4 v[218:221], v[158:159], off offset:576
	v_lshl_add_u64 v[158:159], v[158:159], 0, s[98:99]
	global_load_dwordx4 v[224:227], v[158:159], off
	global_load_dwordx4 v[228:231], v[158:159], off offset:64
	global_load_dwordx4 v[232:235], v[158:159], off offset:512
	global_load_dwordx4 v[236:239], v[158:159], off offset:576
	v_lshl_add_u64 v[158:159], v[158:159], 0, s[100:101]
	s_waitcnt vmcnt(0)
;     __device__ __forceinline__ void operator()(const f32x4 (&acc)[2][2][4][2], const pg8::Unit& u, int wr_, int wc_, int fr_, int fq_) const {
;     ...
;         const int rbase = u.pm * 256;
;         const bool isc = rbase >= RL;
;         const int mr = isc ? 4 : (rbase >> 12);
;         const float* gate = modsel + (size_t)mr * 12288;
;         const float* src = isc ? srcC - (size_t)RL * 2048 : srcL;
;         float* dst = isc ? dstC - (size_t)RL * 2048 : dstL;
;         const int row0 = rbase + wr * 64 + fr, col0 = u.pn * 256 + wc * 32 + 4 * fq;
; #pragma unroll
;         for (int ai = 0; ai < 2; ++ai)
; #pragma unroll
;             for (int m = 0; m < 4; ++m) { const size_t ro = (size_t)(row0 + ai * 128 + m * 16) * 2048;
; #pragma unroll
;                 for (int bj = 0; bj < 2; ++bj)
; #pragma unroll
;                     for (int n = 0; n < 2; ++n) { const int col = col0 + bj * 128 + n * 16;
;                         const f32x4 gg = *(const f32x4*)(gate + col), s = *(const f32x4*)(src + ro + col);
;                         *(f32x4*)(dst + ro + col) = s + gg * acc[ai][bj][m][n]; } }
	v_pk_fma_f32 v[124:125], v[124:125], v[148:149], v[174:175]
	v_pk_fma_f32 v[126:127], v[126:127], v[150:151], v[176:177]
	v_pk_fma_f32 v[120:121], v[120:121], v[162:163], v[178:179]
	v_pk_fma_f32 v[122:123], v[122:123], v[164:165], v[180:181]
	v_pk_fma_f32 v[116:117], v[116:117], v[166:167], v[182:183]
	v_pk_fma_f32 v[118:119], v[118:119], v[168:169], v[184:185]
	v_pk_fma_f32 v[108:109], v[108:109], v[170:171], v[186:187]
	v_pk_fma_f32 v[110:111], v[110:111], v[172:173], v[188:189]
	v_pk_fma_f32 v[112:113], v[112:113], v[148:149], v[190:191]
	v_pk_fma_f32 v[114:115], v[114:115], v[150:151], v[192:193]
	v_pk_fma_f32 v[104:105], v[104:105], v[162:163], v[194:195]
	v_pk_fma_f32 v[106:107], v[106:107], v[164:165], v[196:197]
	v_pk_fma_f32 v[100:101], v[100:101], v[166:167], v[198:199]
	v_pk_fma_f32 v[102:103], v[102:103], v[168:169], v[200:201]
	v_pk_fma_f32 v[92:93], v[92:93], v[170:171], v[202:203]
	v_pk_fma_f32 v[94:95], v[94:95], v[172:173], v[204:205]
	v_pk_fma_f32 v[96:97], v[96:97], v[148:149], v[206:207]
	v_pk_fma_f32 v[98:99], v[98:99], v[150:151], v[208:209]
	v_pk_fma_f32 v[88:89], v[88:89], v[162:163], v[210:211]
	v_pk_fma_f32 v[90:91], v[90:91], v[164:165], v[212:213]
	v_pk_fma_f32 v[84:85], v[84:85], v[166:167], v[214:215]
	v_pk_fma_f32 v[86:87], v[86:87], v[168:169], v[216:217]
	v_pk_fma_f32 v[76:77], v[76:77], v[170:171], v[218:219]
	v_pk_fma_f32 v[78:79], v[78:79], v[172:173], v[220:221]
	v_pk_fma_f32 v[80:81], v[80:81], v[148:149], v[224:225]
	v_pk_fma_f32 v[82:83], v[82:83], v[150:151], v[226:227]
	v_pk_fma_f32 v[72:73], v[72:73], v[162:163], v[228:229]
	v_pk_fma_f32 v[74:75], v[74:75], v[164:165], v[230:231]
	v_pk_fma_f32 v[68:69], v[68:69], v[166:167], v[232:233]
	v_pk_fma_f32 v[70:71], v[70:71], v[168:169], v[234:235]
	v_pk_fma_f32 v[64:65], v[64:65], v[170:171], v[236:237]
	v_pk_fma_f32 v[66:67], v[66:67], v[172:173], v[238:239]
	global_load_dwordx4 v[174:177], v[158:159], off
	global_load_dwordx4 v[178:181], v[158:159], off offset:64
	global_load_dwordx4 v[182:185], v[158:159], off offset:512
	global_load_dwordx4 v[186:189], v[158:159], off offset:576
	v_lshl_add_u64 v[158:159], v[158:159], 0, s[98:99]
	global_load_dwordx4 v[190:193], v[158:159], off
	global_load_dwordx4 v[194:197], v[158:159], off offset:64
	global_load_dwordx4 v[198:201], v[158:159], off offset:512
	global_load_dwordx4 v[202:205], v[158:159], off offset:576
	v_lshl_add_u64 v[158:159], v[158:159], 0, s[98:99]
	global_load_dwordx4 v[206:209], v[158:159], off
	global_load_dwordx4 v[210:213], v[158:159], off offset:64
	global_load_dwordx4 v[214:217], v[158:159], off offset:512
	global_load_dwordx4 v[218:221], v[158:159], off offset:576
	v_lshl_add_u64 v[158:159], v[158:159], 0, s[98:99]
	global_load_dwordx4 v[224:227], v[158:159], off
	global_load_dwordx4 v[228:231], v[158:159], off offset:64
	global_load_dwordx4 v[232:235], v[158:159], off offset:512
	global_load_dwordx4 v[236:239], v[158:159], off offset:576
	global_store_dwordx4 v[160:161], v[124:127], off
	global_store_dwordx4 v[160:161], v[120:123], off offset:64
	global_store_dwordx4 v[160:161], v[116:119], off offset:512
	global_store_dwordx4 v[160:161], v[108:111], off offset:576
	v_lshl_add_u64 v[160:161], v[160:161], 0, s[98:99]
	global_store_dwordx4 v[160:161], v[112:115], off
	global_store_dwordx4 v[160:161], v[104:107], off offset:64
	global_store_dwordx4 v[160:161], v[100:103], off offset:512
	global_store_dwordx4 v[160:161], v[92:95], off offset:576
	v_lshl_add_u64 v[160:161], v[160:161], 0, s[98:99]
	global_store_dwordx4 v[160:161], v[96:99], off
	global_store_dwordx4 v[160:161], v[88:91], off offset:64
	global_store_dwordx4 v[160:161], v[84:87], off offset:512
	global_store_dwordx4 v[160:161], v[76:79], off offset:576
	v_lshl_add_u64 v[160:161], v[160:161], 0, s[98:99]
	global_store_dwordx4 v[160:161], v[80:83], off
	global_store_dwordx4 v[160:161], v[72:75], off offset:64
	global_store_dwordx4 v[160:161], v[68:71], off offset:512
	global_store_dwordx4 v[160:161], v[64:67], off offset:576
	v_lshl_add_u64 v[160:161], v[160:161], 0, s[100:101]
	s_waitcnt vmcnt(16)
	v_pk_fma_f32 v[60:61], v[60:61], v[148:149], v[174:175]
	v_pk_fma_f32 v[62:63], v[62:63], v[150:151], v[176:177]
	v_pk_fma_f32 v[56:57], v[56:57], v[162:163], v[178:179]
	v_pk_fma_f32 v[58:59], v[58:59], v[164:165], v[180:181]
	v_pk_fma_f32 v[52:53], v[52:53], v[166:167], v[182:183]
	v_pk_fma_f32 v[54:55], v[54:55], v[168:169], v[184:185]
	v_pk_fma_f32 v[44:45], v[44:45], v[170:171], v[186:187]
	v_pk_fma_f32 v[46:47], v[46:47], v[172:173], v[188:189]
	v_pk_fma_f32 v[48:49], v[48:49], v[148:149], v[190:191]
	v_pk_fma_f32 v[50:51], v[50:51], v[150:151], v[192:193]
	v_pk_fma_f32 v[40:41], v[40:41], v[162:163], v[194:195]
	v_pk_fma_f32 v[42:43], v[42:43], v[164:165], v[196:197]
	v_pk_fma_f32 v[36:37], v[36:37], v[166:167], v[198:199]
	v_pk_fma_f32 v[38:39], v[38:39], v[168:169], v[200:201]
	v_pk_fma_f32 v[28:29], v[28:29], v[170:171], v[202:203]
	v_pk_fma_f32 v[30:31], v[30:31], v[172:173], v[204:205]
	v_pk_fma_f32 v[32:33], v[32:33], v[148:149], v[206:207]
	v_pk_fma_f32 v[34:35], v[34:35], v[150:151], v[208:209]
	v_pk_fma_f32 v[24:25], v[24:25], v[162:163], v[210:211]
	v_pk_fma_f32 v[26:27], v[26:27], v[164:165], v[212:213]
	v_pk_fma_f32 v[20:21], v[20:21], v[166:167], v[214:215]
	v_pk_fma_f32 v[22:23], v[22:23], v[168:169], v[216:217]
	v_pk_fma_f32 v[12:13], v[12:13], v[170:171], v[218:219]
	v_pk_fma_f32 v[14:15], v[14:15], v[172:173], v[220:221]
	v_pk_fma_f32 v[16:17], v[16:17], v[148:149], v[224:225]
	v_pk_fma_f32 v[18:19], v[18:19], v[150:151], v[226:227]
	v_pk_fma_f32 v[8:9], v[8:9], v[162:163], v[228:229]
	v_pk_fma_f32 v[10:11], v[10:11], v[164:165], v[230:231]
	v_pk_fma_f32 v[4:5], v[4:5], v[166:167], v[232:233]
	v_pk_fma_f32 v[6:7], v[6:7], v[168:169], v[234:235]
	v_pk_fma_f32 v[0:1], v[0:1], v[170:171], v[236:237]
	v_pk_fma_f32 v[2:3], v[2:3], v[172:173], v[238:239]
	global_store_dwordx4 v[160:161], v[60:63], off
	global_store_dwordx4 v[160:161], v[56:59], off offset:64
	global_store_dwordx4 v[160:161], v[52:55], off offset:512
	global_store_dwordx4 v[160:161], v[44:47], off offset:576
	v_lshl_add_u64 v[160:161], v[160:161], 0, s[98:99]
	global_store_dwordx4 v[160:161], v[48:51], off
	global_store_dwordx4 v[160:161], v[40:43], off offset:64
	global_store_dwordx4 v[160:161], v[36:39], off offset:512
	global_store_dwordx4 v[160:161], v[28:31], off offset:576
	v_lshl_add_u64 v[160:161], v[160:161], 0, s[98:99]
	global_store_dwordx4 v[160:161], v[32:35], off
	global_store_dwordx4 v[160:161], v[24:27], off offset:64
	global_store_dwordx4 v[160:161], v[20:23], off offset:512
	global_store_dwordx4 v[160:161], v[12:15], off offset:576
	v_lshl_add_u64 v[160:161], v[160:161], 0, s[98:99]
	global_store_dwordx4 v[160:161], v[16:19], off
	global_store_dwordx4 v[160:161], v[8:11], off offset:64
	global_store_dwordx4 v[160:161], v[4:7], off offset:512
	global_store_dwordx4 v[160:161], v[0:3], off offset:576
	s_cbranch_vccnz .LBB0_1095
; #define PG8_WAIT_V(n) asm volatile("s_waitcnt vmcnt(" #n ")" ::: "memory")
; #define PG8_BAR __builtin_amdgcn_s_barrier()
; template <class Epi, class Sched>
; __device__ __forceinline__ void gemm_phase(LAS unsigned char* lds, const Gemm g, const Sched& S, const Epi& E) {
;     ...
;     PG8_WAIT_V(0);
;     if (wr == 0) PG8_BAR;
;     PG8_BAR;
	s_waitcnt vmcnt(0)
	s_cmpk_gt_u32 s13, 0xff
	s_cbranch_scc1 .LBB0_1110
	s_barrier

; __global__ void __launch_bounds__(512, 2) fwd_megakernel(Params p_) {
	.amdhsa_kernel _Z14fwd_megakernel6Params
		.amdhsa_group_segment_fixed_size 0
		.amdhsa_private_segment_fixed_size 0
		.amdhsa_kernarg_size 560
		.amdhsa_user_sgpr_count 2
		.amdhsa_user_sgpr_dispatch_ptr 0
		.amdhsa_user_sgpr_queue_ptr 0
		.amdhsa_user_sgpr_kernarg_segment_ptr 1
		.amdhsa_user_sgpr_dispatch_id 0
		.amdhsa_user_sgpr_kernarg_preload_length 0
		.amdhsa_user_sgpr_kernarg_preload_offset 0
		.amdhsa_user_sgpr_private_segment_size 0
		.amdhsa_uses_dynamic_stack 0
		.amdhsa_enable_private_segment 0
		.amdhsa_system_sgpr_workgroup_id_x 1
		.amdhsa_system_sgpr_workgroup_id_y 0
		.amdhsa_system_sgpr_workgroup_id_z 0
		.amdhsa_system_sgpr_workgroup_info 0
		.amdhsa_system_vgpr_workitem_id 2
		.amdhsa_next_free_vgpr 246
		.amdhsa_next_free_sgpr 102
		.amdhsa_accum_offset 248
		.amdhsa_reserve_vcc 1
		.amdhsa_float_round_mode_32 0
		.amdhsa_float_round_mode_16_64 0
		.amdhsa_float_denorm_mode_32 3
		.amdhsa_float_denorm_mode_16_64 3
		.amdhsa_dx10_clamp 1
		.amdhsa_ieee_mode 1
		.amdhsa_fp16_overflow 0
		.amdhsa_tg_split 0
		.amdhsa_exception_fp_ieee_invalid_op 0
		.amdhsa_exception_fp_denorm_src 0
		.amdhsa_exception_fp_ieee_div_zero 0
		.amdhsa_exception_fp_ieee_overflow 0
		.amdhsa_exception_fp_ieee_underflow 0
		.amdhsa_exception_fp_ieee_inexact 0
		.amdhsa_exception_int_div_zero 0
	.end_amdhsa_kernel

; __global__ void __launch_bounds__(512, 2) fwd_megakernel(Params p_) {
amdhsa.kernels:
  - .agpr_count:     0
    .args:
      - .offset:         0
        .size:           304
        .value_kind:     by_value
      - .offset:         304
        .size:           4
        .value_kind:     hidden_block_count_x
      - .offset:         308
        .size:           4
        .value_kind:     hidden_block_count_y
      - .offset:         312
        .size:           4
        .value_kind:     hidden_block_count_z
      - .offset:         316
        .size:           2
        .value_kind:     hidden_group_size_x
      - .offset:         318
        .size:           2
        .value_kind:     hidden_group_size_y
      - .offset:         320
        .size:           2
        .value_kind:     hidden_group_size_z
      - .offset:         322
        .size:           2
        .value_kind:     hidden_remainder_x
      - .offset:         324
        .size:           2
        .value_kind:     hidden_remainder_y
      - .offset:         326
        .size:           2
        .value_kind:     hidden_remainder_z
      - .offset:         344
        .size:           8
        .value_kind:     hidden_global_offset_x
      - .offset:         352
        .size:           8
        .value_kind:     hidden_global_offset_y
      - .offset:         360
        .size:           8
        .value_kind:     hidden_global_offset_z
      - .offset:         368
        .size:           2
        .value_kind:     hidden_grid_dims
      - .offset:         392
        .size:           8
        .value_kind:     hidden_multigrid_sync_arg
      - .offset:         424
        .size:           4
        .value_kind:     hidden_dynamic_lds_size
    .group_segment_fixed_size: 0
    .kernarg_segment_align: 8
    .kernarg_segment_size: 560
    .language:       OpenCL C
    .language_version:
      - 2
      - 0
    .max_flat_workgroup_size: 512
    .name:           _Z14fwd_megakernel6Params
    .private_segment_fixed_size: 0
    .sgpr_count:     108
    .sgpr_spill_count: 69
    .symbol:         _Z14fwd_megakernel6Params.kd
    .uniform_work_group_size: 1
    .uses_dynamic_stack: false
    .vgpr_count:     246
    .vgpr_spill_count: 0
    .wavefront_size: 64
